# static raise of waves 0-3 limited to the K loop: priority reset to 0 at each unit epilogue
# speedup vs baseline: 1.0134x; 1.0134x over previous
; #define PG8_STAGE(bufoff, gbase, voff) do { _Pragma("unroll") for (int _i = 0; _i < 2; ++_i) \
;         __builtin_amdgcn_global_load_lds((const unsigned*)((const char*)(gbase) + (voff)[_i]), (LAS unsigned*)(lds + (bufoff) + ldsw + _i * 8192), 16, 0, 0); } while (0)
; #define PG8_LDA(dst, b, h) do { _Pragma("unroll") for (int m = 0; m < 4; ++m) _Pragma("unroll") for (int k = 0; k < 2; ++k) dst[m][k] = *(const LAS bf16x8*)(lds + PG8_SA(b, h) + aoff + m * 2048 + k * 1024); } while (0)
; #define PG8_LDB(dst, b, h) do { _Pragma("unroll") for (int n = 0; n < 2; ++n) _Pragma("unroll") for (int k = 0; k < 2; ++k) dst[n][k] = *(const LAS bf16x8*)(lds + PG8_SB(b, h) + boff + n * 2048 + k * 1024); } while (0)
; #define PG8_MMA(ai, bj, At, Bt) do { __builtin_amdgcn_s_setprio(1); _Pragma("unroll") for (int m = 0; m < 4; ++m) _Pragma("unroll") for (int n = 0; n < 2; ++n) _Pragma("unroll") for (int k = 0; k < 2; ++k) \
;         acc[ai][bj][m][n] = __builtin_amdgcn_mfma_f32_16x16x32_bf16(Bt[n][k], At[m][k], acc[ai][bj][m][n], 0, 0, 0); __builtin_amdgcn_s_setprio(0); } while (0)
; #define PG8_WAIT_V(n) asm volatile("s_waitcnt vmcnt(" #n ")" ::: "memory")
; #define PG8_BAR __builtin_amdgcn_s_barrier()
; template <class Epi>
; __device__ __forceinline__ void gemm_phase(LAS unsigned char* lds, const Gemm g, const StaticOrder& S, const Epi& E) {
;     ...
;         for (int t = 0; t < nt; t += 2) {
;             const bool last = (t == nt - 2);
;             const char* a1 = cA + (size_t)(t + 1) * kstep;
;             const char* a2 = last ? nA : cA + (size_t)(t + 2) * kstep; const char* b2 = last ? nB : cB + (size_t)(t + 2) * kstep;
;             const char* a3 = a2 + kstep; const char* b3 = b2 + kstep;
;             if (last) E.pre(cur, wr, fr, epre);
;             PG8_LDB(B0, 0, 0); PG8_SCHED; PG8_LDA(At, 0, 0); PG8_STAGE(PG8_SA(1, 1), a1 + hstepA, voffA);
;             PG8_WAIT_L(8); PG8_BAR; PG8_WAIT_L(0); PG8_MMA(0, 0, At, B0); PG8_BAR; PG8_SCHED;
;             PG8_LDB(B1, 0, 1); PG8_STAGE(PG8_SB(0, 0), b2, voffB);
;             PG8_BAR; PG8_WAIT_L(0); PG8_MMA(0, 1, At, B1); PG8_BAR;
;             PG8_LDA(At, 0, 1); PG8_STAGE(PG8_SA(0, 0), a2, voffA);
;             PG8_BAR; PG8_WAIT_L(0); PG8_MMA(1, 0, At, B0); PG8_BAR; PG8_SCHED;
;             PG8_STAGE(PG8_SB(0, 1), b2 + hstepB, voffB);
;             PG8_WAIT_V(6); PG8_BAR; PG8_MMA(1, 1, At, B1); PG8_BAR;
.LBB0_205:
	ds_read_b128 v[146:149], v170
	ds_read_b128 v[154:157], v170 offset:1024
	ds_read_b128 v[158:161], v170 offset:2048
	ds_read_b128 v[162:165], v170 offset:3072
	s_add_u32 s22, s20, 0xfffc0080
	s_addc_u32 s23, s21, -1
	s_cmp_eq_u32 s47, 12
	s_cselect_b32 s25, s13, s23
	s_cselect_b32 s24, s19, s22
	s_cselect_b32 s23, s11, s46
	s_cselect_b32 s22, s44, s45
	v_lshl_add_u64 v[150:151], s[20:21], 0, v[138:139]
	s_add_i32 m0, s30, 0xc000
	ds_read_b128 v[174:177], v171
	ds_read_b128 v[178:181], v171 offset:1024
	ds_read_b128 v[182:185], v171 offset:2048
	ds_read_b128 v[186:189], v171 offset:3072
	ds_read_b128 v[190:193], v171 offset:4096
	ds_read_b128 v[194:197], v171 offset:5120
	ds_read_b128 v[198:201], v171 offset:6144
	ds_read_b128 v[202:205], v171 offset:7168
	global_load_lds_dwordx4 v[150:151], off
	v_lshl_add_u64 v[150:151], s[20:21], 0, v[140:141]
	s_add_i32 m0, s30, 0xe000
	s_nop 0
	global_load_lds_dwordx4 v[150:151], off
	s_waitcnt lgkmcnt(8)
	s_barrier
	s_waitcnt lgkmcnt(0)
	v_mfma_f32_16x16x32_bf16 v[76:79], v[146:149], v[174:177], v[76:79]
	v_mfma_f32_16x16x32_bf16 v[64:67], v[158:161], v[174:177], v[64:67]
	v_mfma_f32_16x16x32_bf16 v[60:63], v[146:149], v[182:185], v[60:63]
	v_mfma_f32_16x16x32_bf16 v[56:59], v[158:161], v[182:185], v[56:59]
	v_mfma_f32_16x16x32_bf16 v[48:51], v[146:149], v[190:193], v[48:51]
	v_mfma_f32_16x16x32_bf16 v[40:43], v[158:161], v[190:193], v[40:43]
	v_mfma_f32_16x16x32_bf16 v[36:39], v[146:149], v[198:201], v[36:39]
	v_mfma_f32_16x16x32_bf16 v[32:35], v[158:161], v[198:201], v[32:35]
	v_mfma_f32_16x16x32_bf16 v[76:79], v[154:157], v[178:181], v[76:79]
	v_mfma_f32_16x16x32_bf16 v[64:67], v[162:165], v[178:181], v[64:67]
	v_mfma_f32_16x16x32_bf16 v[60:63], v[154:157], v[186:189], v[60:63]
	v_mfma_f32_16x16x32_bf16 v[56:59], v[162:165], v[186:189], v[56:59]
	v_mfma_f32_16x16x32_bf16 v[48:51], v[154:157], v[194:197], v[48:51]
	v_mfma_f32_16x16x32_bf16 v[40:43], v[162:165], v[194:197], v[40:43]
	v_mfma_f32_16x16x32_bf16 v[36:39], v[154:157], v[202:205], v[36:39]
	v_mfma_f32_16x16x32_bf16 v[32:35], v[162:165], v[202:205], v[32:35]
	s_barrier
	s_add_i32 s48, s39, s27
	v_lshl_add_u64 v[150:151], s[22:23], 0, v[132:133]
	s_mov_b32 m0, s48
	ds_read_b128 v[206:209], v172
	ds_read_b128 v[210:213], v172 offset:1024
	ds_read_b128 v[214:217], v172 offset:2048
	ds_read_b128 v[218:221], v172 offset:3072
	global_load_lds_dwordx4 v[150:151], off
	v_lshl_add_u64 v[166:167], s[22:23], 0, v[128:129]
	s_add_i32 m0, s48, 0x2000
	s_nop 0
	global_load_lds_dwordx4 v[166:167], off
	s_barrier
	s_waitcnt lgkmcnt(0)
	v_mfma_f32_16x16x32_bf16 v[124:127], v[206:209], v[174:177], v[124:127]
	v_mfma_f32_16x16x32_bf16 v[120:123], v[214:217], v[174:177], v[120:123]
	v_mfma_f32_16x16x32_bf16 v[116:119], v[206:209], v[182:185], v[116:119]
	v_mfma_f32_16x16x32_bf16 v[112:115], v[214:217], v[182:185], v[112:115]
	v_mfma_f32_16x16x32_bf16 v[108:111], v[206:209], v[190:193], v[108:111]
	v_mfma_f32_16x16x32_bf16 v[104:107], v[214:217], v[190:193], v[104:107]
	v_mfma_f32_16x16x32_bf16 v[100:103], v[206:209], v[198:201], v[100:103]
	v_mfma_f32_16x16x32_bf16 v[96:99], v[214:217], v[198:201], v[96:99]
	v_mfma_f32_16x16x32_bf16 v[124:127], v[210:213], v[178:181], v[124:127]
	v_mfma_f32_16x16x32_bf16 v[120:123], v[218:221], v[178:181], v[120:123]
	v_mfma_f32_16x16x32_bf16 v[116:119], v[210:213], v[186:189], v[116:119]
	v_mfma_f32_16x16x32_bf16 v[112:115], v[218:221], v[186:189], v[112:115]
	v_mfma_f32_16x16x32_bf16 v[108:111], v[210:213], v[194:197], v[108:111]
	v_mfma_f32_16x16x32_bf16 v[104:107], v[218:221], v[194:197], v[104:107]
	v_mfma_f32_16x16x32_bf16 v[100:103], v[210:213], v[202:205], v[100:103]
	v_mfma_f32_16x16x32_bf16 v[96:99], v[218:221], v[202:205], v[96:99]
	s_mov_b32 m0, s30
	v_lshl_add_u64 v[222:223], s[24:25], 0, v[134:135]
	s_barrier
	ds_read_b128 v[174:177], v171 offset:16384
	ds_read_b128 v[178:181], v171 offset:17408
	ds_read_b128 v[182:185], v171 offset:18432
	ds_read_b128 v[186:189], v171 offset:19456
	ds_read_b128 v[190:193], v171 offset:20480
	ds_read_b128 v[194:197], v171 offset:21504
	ds_read_b128 v[198:201], v171 offset:22528
	ds_read_b128 v[202:205], v171 offset:23552
	global_load_lds_dwordx4 v[222:223], off
	v_lshl_add_u64 v[224:225], s[24:25], 0, v[130:131]
	s_mov_b32 m0, s31
	s_nop 0
	global_load_lds_dwordx4 v[224:225], off
	s_barrier
	s_waitcnt lgkmcnt(0)
	v_mfma_f32_16x16x32_bf16 v[28:31], v[146:149], v[174:177], v[28:31]
	v_mfma_f32_16x16x32_bf16 v[24:27], v[158:161], v[174:177], v[24:27]
	v_mfma_f32_16x16x32_bf16 v[20:23], v[146:149], v[182:185], v[20:23]
	v_mfma_f32_16x16x32_bf16 v[16:19], v[158:161], v[182:185], v[16:19]
	v_mfma_f32_16x16x32_bf16 v[12:15], v[146:149], v[190:193], v[12:15]
	v_mfma_f32_16x16x32_bf16 v[8:11], v[158:161], v[190:193], v[8:11]
	v_mfma_f32_16x16x32_bf16 v[4:7], v[146:149], v[198:201], v[4:7]
	v_mfma_f32_16x16x32_bf16 v[0:3], v[158:161], v[198:201], v[0:3]
	v_mfma_f32_16x16x32_bf16 v[28:31], v[154:157], v[178:181], v[28:31]
	v_mfma_f32_16x16x32_bf16 v[24:27], v[162:165], v[178:181], v[24:27]
	v_mfma_f32_16x16x32_bf16 v[20:23], v[154:157], v[186:189], v[20:23]
	v_mfma_f32_16x16x32_bf16 v[16:19], v[162:165], v[186:189], v[16:19]
	v_mfma_f32_16x16x32_bf16 v[12:15], v[154:157], v[194:197], v[12:15]
	v_mfma_f32_16x16x32_bf16 v[8:11], v[162:165], v[194:197], v[8:11]
	v_mfma_f32_16x16x32_bf16 v[4:7], v[154:157], v[202:205], v[4:7]
	v_mfma_f32_16x16x32_bf16 v[0:3], v[162:165], v[202:205], v[0:3]
	s_barrier
	s_add_u32 s48, s22, 0x40000
	s_addc_u32 s49, s23, 0
	s_add_i32 s50, s40, s27
	v_lshl_add_u64 v[146:147], s[48:49], 0, v[132:133]
	s_mov_b32 m0, s50
	s_nop 0
	global_load_lds_dwordx4 v[146:147], off
	v_lshl_add_u64 v[146:147], s[48:49], 0, v[128:129]
	s_add_i32 m0, s50, 0x2000
	s_nop 0
	global_load_lds_dwordx4 v[146:147], off
	s_waitcnt vmcnt(6)
	s_barrier
; #define PG8_STAGE(bufoff, gbase, voff) do { _Pragma("unroll") for (int _i = 0; _i < 2; ++_i) \
;         __builtin_amdgcn_global_load_lds((const unsigned*)((const char*)(gbase) + (voff)[_i]), (LAS unsigned*)(lds + (bufoff) + ldsw + _i * 8192), 16, 0, 0); } while (0)
; #define PG8_LDA(dst, b, h) do { _Pragma("unroll") for (int m = 0; m < 4; ++m) _Pragma("unroll") for (int k = 0; k < 2; ++k) dst[m][k] = *(const LAS bf16x8*)(lds + PG8_SA(b, h) + aoff + m * 2048 + k * 1024); } while (0)
; #define PG8_LDB(dst, b, h) do { _Pragma("unroll") for (int n = 0; n < 2; ++n) _Pragma("unroll") for (int k = 0; k < 2; ++k) dst[n][k] = *(const LAS bf16x8*)(lds + PG8_SB(b, h) + boff + n * 2048 + k * 1024); } while (0)
; #define PG8_MMA(ai, bj, At, Bt) do { __builtin_amdgcn_s_setprio(1); _Pragma("unroll") for (int m = 0; m < 4; ++m) _Pragma("unroll") for (int n = 0; n < 2; ++n) _Pragma("unroll") for (int k = 0; k < 2; ++k) \
;         acc[ai][bj][m][n] = __builtin_amdgcn_mfma_f32_16x16x32_bf16(Bt[n][k], At[m][k], acc[ai][bj][m][n], 0, 0, 0); __builtin_amdgcn_s_setprio(0); } while (0)
; #define PG8_WAIT_V(n) asm volatile("s_waitcnt vmcnt(" #n ")" ::: "memory")
; #define PG8_WAIT_L(n) asm volatile("s_waitcnt lgkmcnt(" #n ")" ::: "memory")
; #define PG8_BAR __builtin_amdgcn_s_barrier()
; #define PG8_SCHED __builtin_amdgcn_sched_barrier(0)
; template <class Epi>
; __device__ __forceinline__ void gemm_phase(LAS unsigned char* lds, const Gemm g, const StaticOrder& S, const Epi& E) {
;     ...
;             PG8_WAIT_V(6); PG8_BAR; PG8_MMA(1, 1, At, B1); PG8_BAR;
;             PG8_LDB(B0, 1, 0); PG8_SCHED; PG8_LDA(At, 1, 0); PG8_STAGE(PG8_SA(0, 1), a2 + hstepA, voffA);
;             PG8_WAIT_L(8); PG8_BAR; PG8_WAIT_L(0); PG8_MMA(0, 0, At, B0); PG8_BAR; PG8_SCHED;
;             PG8_LDB(B1, 1, 1); PG8_STAGE(PG8_SB(1, 0), b3, voffB);
;             PG8_BAR; PG8_WAIT_L(0); PG8_MMA(0, 1, At, B1); PG8_BAR;
;             PG8_LDA(At, 1, 1); PG8_STAGE(PG8_SA(1, 0), a3, voffA);
;             PG8_BAR; PG8_WAIT_L(0); PG8_MMA(1, 0, At, B0); PG8_BAR; PG8_SCHED;
	v_mfma_f32_16x16x32_bf16 v[92:95], v[206:209], v[174:177], v[92:95]
	v_mfma_f32_16x16x32_bf16 v[88:91], v[214:217], v[174:177], v[88:91]
	v_mfma_f32_16x16x32_bf16 v[84:87], v[206:209], v[182:185], v[84:87]
	v_mfma_f32_16x16x32_bf16 v[80:83], v[214:217], v[182:185], v[80:83]
	v_mfma_f32_16x16x32_bf16 v[72:75], v[206:209], v[190:193], v[72:75]
	v_mfma_f32_16x16x32_bf16 v[68:71], v[214:217], v[190:193], v[68:71]
	v_mfma_f32_16x16x32_bf16 v[52:55], v[206:209], v[198:201], v[52:55]
	v_mfma_f32_16x16x32_bf16 v[44:47], v[214:217], v[198:201], v[44:47]
	v_mfma_f32_16x16x32_bf16 v[92:95], v[210:213], v[178:181], v[92:95]
	v_mfma_f32_16x16x32_bf16 v[88:91], v[218:221], v[178:181], v[88:91]
	v_mfma_f32_16x16x32_bf16 v[84:87], v[210:213], v[186:189], v[84:87]
	v_mfma_f32_16x16x32_bf16 v[80:83], v[218:221], v[186:189], v[80:83]
	v_mfma_f32_16x16x32_bf16 v[72:75], v[210:213], v[194:197], v[72:75]
	v_mfma_f32_16x16x32_bf16 v[68:71], v[218:221], v[194:197], v[68:71]
	v_mfma_f32_16x16x32_bf16 v[52:55], v[210:213], v[202:205], v[52:55]
	v_mfma_f32_16x16x32_bf16 v[44:47], v[218:221], v[202:205], v[44:47]
	s_add_i32 s48, 0, 0x18000
	v_add_u32_e32 v162, s48, v168
	s_barrier
	ds_read_b128 v[146:149], v162
	ds_read_b128 v[154:157], v162 offset:1024
	ds_read_b128 v[158:161], v162 offset:2048
	ds_read_b128 v[162:165], v162 offset:3072
	s_add_u32 s24, s24, 0x40000
	s_addc_u32 s25, s25, 0
	s_mov_b32 m0, s33
	v_lshl_add_u64 v[206:207], s[24:25], 0, v[134:135]
	ds_read_b128 v[174:177], v171 offset:32768
	ds_read_b128 v[178:181], v171 offset:33792
	ds_read_b128 v[182:185], v171 offset:34816
	ds_read_b128 v[186:189], v171 offset:35840
	ds_read_b128 v[190:193], v171 offset:36864
	ds_read_b128 v[194:197], v171 offset:37888
	ds_read_b128 v[198:201], v171 offset:38912
	ds_read_b128 v[202:205], v171 offset:39936
	global_load_lds_dwordx4 v[206:207], off
	v_lshl_add_u64 v[206:207], s[24:25], 0, v[130:131]
	s_mov_b32 m0, s34
	s_nop 0
	global_load_lds_dwordx4 v[206:207], off
	s_waitcnt lgkmcnt(8)
	s_barrier
	s_waitcnt lgkmcnt(0)
	v_mfma_f32_16x16x32_bf16 v[76:79], v[146:149], v[174:177], v[76:79]
	v_mfma_f32_16x16x32_bf16 v[64:67], v[158:161], v[174:177], v[64:67]
	v_mfma_f32_16x16x32_bf16 v[60:63], v[146:149], v[182:185], v[60:63]
	v_mfma_f32_16x16x32_bf16 v[56:59], v[158:161], v[182:185], v[56:59]
	v_mfma_f32_16x16x32_bf16 v[48:51], v[146:149], v[190:193], v[48:51]
	v_mfma_f32_16x16x32_bf16 v[40:43], v[158:161], v[190:193], v[40:43]
	v_mfma_f32_16x16x32_bf16 v[36:39], v[146:149], v[198:201], v[36:39]
	v_mfma_f32_16x16x32_bf16 v[32:35], v[158:161], v[198:201], v[32:35]
	v_mfma_f32_16x16x32_bf16 v[76:79], v[154:157], v[178:181], v[76:79]
	v_mfma_f32_16x16x32_bf16 v[64:67], v[162:165], v[178:181], v[64:67]
	v_mfma_f32_16x16x32_bf16 v[60:63], v[154:157], v[186:189], v[60:63]
	v_mfma_f32_16x16x32_bf16 v[56:59], v[162:165], v[186:189], v[56:59]
	v_mfma_f32_16x16x32_bf16 v[48:51], v[154:157], v[194:197], v[48:51]
	v_mfma_f32_16x16x32_bf16 v[40:43], v[162:165], v[194:197], v[40:43]
	v_mfma_f32_16x16x32_bf16 v[36:39], v[154:157], v[202:205], v[36:39]
	v_mfma_f32_16x16x32_bf16 v[32:35], v[162:165], v[202:205], v[32:35]
	s_barrier
	s_add_i32 s24, 0, 0x1c000
	s_add_i32 s25, s48, s27
	v_add_u32_e32 v218, s24, v168
	v_lshl_add_u64 v[150:151], v[150:151], 0, s[6:7]
	s_mov_b32 m0, s25
	ds_read_b128 v[206:209], v218
	ds_read_b128 v[210:213], v218 offset:1024
	ds_read_b128 v[214:217], v218 offset:2048
	ds_read_b128 v[218:221], v218 offset:3072
	global_load_lds_dwordx4 v[150:151], off
	v_lshl_add_u64 v[150:151], v[166:167], 0, s[6:7]
	s_add_i32 m0, s25, 0x2000
	s_nop 0
	global_load_lds_dwordx4 v[150:151], off
	s_barrier
	s_waitcnt lgkmcnt(0)
	v_mfma_f32_16x16x32_bf16 v[124:127], v[206:209], v[174:177], v[124:127]
	v_mfma_f32_16x16x32_bf16 v[120:123], v[214:217], v[174:177], v[120:123]
	v_mfma_f32_16x16x32_bf16 v[116:119], v[206:209], v[182:185], v[116:119]
	v_mfma_f32_16x16x32_bf16 v[112:115], v[214:217], v[182:185], v[112:115]
	v_mfma_f32_16x16x32_bf16 v[108:111], v[206:209], v[190:193], v[108:111]
	v_mfma_f32_16x16x32_bf16 v[104:107], v[214:217], v[190:193], v[104:107]
	v_mfma_f32_16x16x32_bf16 v[100:103], v[206:209], v[198:201], v[100:103]
	v_mfma_f32_16x16x32_bf16 v[96:99], v[214:217], v[198:201], v[96:99]
	v_mfma_f32_16x16x32_bf16 v[124:127], v[210:213], v[178:181], v[124:127]
	v_mfma_f32_16x16x32_bf16 v[120:123], v[218:221], v[178:181], v[120:123]
	v_mfma_f32_16x16x32_bf16 v[116:119], v[210:213], v[186:189], v[116:119]
	v_mfma_f32_16x16x32_bf16 v[112:115], v[218:221], v[186:189], v[112:115]
	v_mfma_f32_16x16x32_bf16 v[108:111], v[210:213], v[194:197], v[108:111]
	v_mfma_f32_16x16x32_bf16 v[104:107], v[218:221], v[194:197], v[104:107]
	v_mfma_f32_16x16x32_bf16 v[100:103], v[210:213], v[202:205], v[100:103]
	v_mfma_f32_16x16x32_bf16 v[96:99], v[218:221], v[202:205], v[96:99]
	s_mov_b32 m0, s36
	v_lshl_add_u64 v[150:151], v[222:223], 0, s[6:7]
	s_barrier
	ds_read_b128 v[174:177], v171 offset:49152
	ds_read_b128 v[178:181], v171 offset:50176
	ds_read_b128 v[182:185], v171 offset:51200
	ds_read_b128 v[186:189], v171 offset:52224
	ds_read_b128 v[190:193], v171 offset:53248
	ds_read_b128 v[194:197], v171 offset:54272
	ds_read_b128 v[198:201], v171 offset:55296
	ds_read_b128 v[202:205], v171 offset:56320
	global_load_lds_dwordx4 v[150:151], off
	v_lshl_add_u64 v[150:151], v[224:225], 0, s[6:7]
	s_mov_b32 m0, s37
	s_nop 0
	global_load_lds_dwordx4 v[150:151], off
	s_barrier
;     __device__ __forceinline__ void operator()(const f32x4 (&acc)[2][2][4][2], const Unit& u, int wr, int wc, int fr, int fq, const float (&)[8]) const {
;     ...
;         if (DT && u.pn == 20) {
;             if (wc == 0) {
; #pragma unroll
;                 for (int ai = 0; ai < 2; ++ai)
; #pragma unroll
;                     for (int m = 0; m < 4; ++m) { const int row = row0 + ai * HALF + m * 16; const float rs = rsqrtf(ep[ai * 4 + m] * (1.0f / 1024.0f) + EPS);
;                         *(f32x4*)(dt + (size_t)row * 32 + 8 * fq) = acc[ai][0][m][0] * rs; *(f32x4*)(dt + (size_t)row * 32 + 8 * fq + 4) = acc[ai][0][m][1] * rs; }
;             }
;             return;
;         }
;         const int col0 = u.pn * BM + wc * 32 + 8 * fq;
; #pragma unroll
;         for (int ai = 0; ai < 2; ++ai)
; #pragma unroll
;             for (int m = 0; m < 4; ++m) { const int row = row0 + ai * HALF + m * 16; const float rs = rsqrtf(ep[ai * 4 + m] * (1.0f / 1024.0f) + EPS);
;                 u16* rowp = O + (size_t)row * ldc + col0;
; #pragma unroll
;                 for (int bj = 0; bj < 2; ++bj) { f32x4 v0 = acc[ai][bj][m][0] * rs, v1 = acc[ai][bj][m][1] * rs;
;                     if (ACT == 1) {
; #pragma unroll
;                         for (int j = 0; j < 4; ++j) { const float a0 = fmaxf(v0[j], 0.f), a1 = fmaxf(v1[j], 0.f); v0[j] = a0 * a0; v1[j] = a1 * a1; } }
;                     u32x4 w; w.x = pk2(v0[0], v0[1]); w.y = pk2(v0[2], v0[3]); w.z = pk2(v1[0], v1[1]); w.w = pk2(v1[2], v1[3]);
; template <class Epi>
; __device__ __forceinline__ void gemm_phase(LAS unsigned char* lds, const Gemm g, const StaticOrder& S, const Epi& E) {
;     ...
;             PG8_WAIT_V(6); PG8_BAR; PG8_MMA(1, 1, At, B1); PG8_BAR;
;             PG8_LDB(B0, 1, 0); PG8_SCHED; PG8_LDA(At, 1, 0); PG8_STAGE(PG8_SA(0, 1), a2 + hstepA, voffA);
;             PG8_WAIT_L(8); PG8_BAR; PG8_WAIT_L(0); PG8_MMA(0, 0, At, B0); PG8_BAR; PG8_SCHED;
;             PG8_LDB(B1, 1, 1); PG8_STAGE(PG8_SB(1, 0), b3, voffB);
;             PG8_BAR; PG8_WAIT_L(0); PG8_MMA(0, 1, At, B1); PG8_BAR;
;             PG8_LDA(At, 1, 1); PG8_STAGE(PG8_SA(1, 0), a3, voffA);
;             PG8_BAR; PG8_WAIT_L(0); PG8_MMA(1, 0, At, B0); PG8_BAR; PG8_SCHED;
;             PG8_STAGE(PG8_SB(1, 1), b3 + hstepB, voffB);
;             PG8_WAIT_V(6); PG8_BAR; PG8_MMA(1, 1, At, B1); PG8_BAR;
;         }
;         E(acc, cur, wr, wc, fr, fq, epre);
	s_waitcnt lgkmcnt(0)
	v_mfma_f32_16x16x32_bf16 v[28:31], v[146:149], v[174:177], v[28:31]
	v_mfma_f32_16x16x32_bf16 v[24:27], v[158:161], v[174:177], v[24:27]
	v_mfma_f32_16x16x32_bf16 v[20:23], v[146:149], v[182:185], v[20:23]
	v_mfma_f32_16x16x32_bf16 v[16:19], v[158:161], v[182:185], v[16:19]
	v_mfma_f32_16x16x32_bf16 v[12:15], v[146:149], v[190:193], v[12:15]
	v_mfma_f32_16x16x32_bf16 v[8:11], v[158:161], v[190:193], v[8:11]
	v_mfma_f32_16x16x32_bf16 v[4:7], v[146:149], v[198:201], v[4:7]
	v_mfma_f32_16x16x32_bf16 v[0:3], v[158:161], v[198:201], v[0:3]
	v_mfma_f32_16x16x32_bf16 v[28:31], v[154:157], v[178:181], v[28:31]
	v_mfma_f32_16x16x32_bf16 v[24:27], v[162:165], v[178:181], v[24:27]
	v_mfma_f32_16x16x32_bf16 v[20:23], v[154:157], v[186:189], v[20:23]
	v_mfma_f32_16x16x32_bf16 v[16:19], v[162:165], v[186:189], v[16:19]
	v_mfma_f32_16x16x32_bf16 v[12:15], v[154:157], v[194:197], v[12:15]
	v_mfma_f32_16x16x32_bf16 v[8:11], v[162:165], v[194:197], v[8:11]
	v_mfma_f32_16x16x32_bf16 v[4:7], v[154:157], v[202:205], v[4:7]
	v_mfma_f32_16x16x32_bf16 v[0:3], v[162:165], v[202:205], v[0:3]
	s_barrier
	s_add_u32 s22, s22, 0x40080
	s_addc_u32 s23, s23, 0
	s_add_i32 s24, s24, s27
	v_lshl_add_u64 v[146:147], s[22:23], 0, v[132:133]
	s_mov_b32 m0, s24
	s_nop 0
	global_load_lds_dwordx4 v[146:147], off
	v_lshl_add_u64 v[146:147], s[22:23], 0, v[128:129]
	s_add_i32 m0, s24, 0x2000
	s_nop 0
	global_load_lds_dwordx4 v[146:147], off
	s_waitcnt vmcnt(6)
	s_barrier
	v_mfma_f32_16x16x32_bf16 v[92:95], v[206:209], v[174:177], v[92:95]
	v_mfma_f32_16x16x32_bf16 v[88:91], v[214:217], v[174:177], v[88:91]
	v_mfma_f32_16x16x32_bf16 v[84:87], v[206:209], v[182:185], v[84:87]
	v_mfma_f32_16x16x32_bf16 v[80:83], v[214:217], v[182:185], v[80:83]
	v_mfma_f32_16x16x32_bf16 v[72:75], v[206:209], v[190:193], v[72:75]
	v_mfma_f32_16x16x32_bf16 v[68:71], v[214:217], v[190:193], v[68:71]
	v_mfma_f32_16x16x32_bf16 v[52:55], v[206:209], v[198:201], v[52:55]
	v_mfma_f32_16x16x32_bf16 v[44:47], v[214:217], v[198:201], v[44:47]
	v_mfma_f32_16x16x32_bf16 v[92:95], v[210:213], v[178:181], v[92:95]
	v_mfma_f32_16x16x32_bf16 v[88:91], v[218:221], v[178:181], v[88:91]
	v_mfma_f32_16x16x32_bf16 v[84:87], v[210:213], v[186:189], v[84:87]
	v_mfma_f32_16x16x32_bf16 v[80:83], v[218:221], v[186:189], v[80:83]
	v_mfma_f32_16x16x32_bf16 v[72:75], v[210:213], v[194:197], v[72:75]
	v_mfma_f32_16x16x32_bf16 v[68:71], v[218:221], v[194:197], v[68:71]
	v_mfma_f32_16x16x32_bf16 v[52:55], v[210:213], v[202:205], v[52:55]
	v_mfma_f32_16x16x32_bf16 v[44:47], v[218:221], v[202:205], v[44:47]
	s_add_i32 s47, s47, 2
	s_add_u32 s20, s20, 0x100
	s_addc_u32 s21, s21, 0
	s_add_u32 s45, s45, 0x100
	s_addc_u32 s46, s46, 0
	s_cmp_gt_u32 s47, 13
	s_barrier
	s_cbranch_scc0 .LBB0_205
	s_setprio 0
	s_bfe_u32 vcc_lo, s18, 0x20003
	s_lshl_b32 vcc_lo, vcc_lo, 10
	s_add_i32 vcc_lo, vcc_lo, 0x20010
	v_lshl_add_u32 v236, v153, 2, vcc_lo
	ds_read_b32 v228, v236
	ds_read_b32 v229, v236 offset:64
	ds_read_b32 v230, v236 offset:128
	ds_read_b32 v231, v236 offset:192
	ds_read_b32 v232, v236 offset:512
	ds_read_b32 v233, v236 offset:576
	ds_read_b32 v234, v236 offset:640
	ds_read_b32 v235, v236 offset:704
	s_waitcnt lgkmcnt(0)
	v_lshl_add_u32 v162, s18, 8, v153
	v_ashrrev_i32_e32 v163, 31, v162
	v_or_b32_e32 v160, 16, v162
	v_or_b32_e32 v158, 32, v162
	v_or_b32_e32 v156, 48, v162
	v_ashrrev_i32_e32 v161, 31, v160
	v_ashrrev_i32_e32 v159, 31, v158
	v_ashrrev_i32_e32 v157, 31, v156
	v_add_u32_e32 v154, 0x80, v162
	v_add_u32_e32 v150, 0x90, v162
	v_add_u32_e32 v148, 0xa0, v162
	v_add_u32_e32 v146, 0xb0, v162
	v_ashrrev_i32_e32 v155, 31, v154
	v_ashrrev_i32_e32 v151, 31, v150
	v_ashrrev_i32_e32 v149, 31, v148
	v_ashrrev_i32_e32 v147, 31, v146
	s_cmp_lg_u32 s43, 20
	s_mov_b64 s[18:19], -1
	s_cbranch_scc0 .LBB0_208
	s_waitcnt vmcnt(8)
	v_lshl_or_b32 v166, s43, 8, v169
	v_ashrrev_i32_e32 v167, 31, v166
	v_lshlrev_b64 v[166:167], 1, v[166:167]
	v_mov_b32_e32 v186, v228
	v_mov_b64_e32 v[164:165], s[96:97]
	v_mad_i64_i32 v[182:183], s[18:19], v162, s42, v[164:165]
	v_lshl_add_u64 v[188:189], v[182:183], 0, v[166:167]
	v_pk_mul_f32 v[184:185], v[78:79], v[186:187] op_sel_hi:[1,0]
	v_pk_mul_f32 v[182:183], v[76:77], v[186:187] op_sel_hi:[1,0]
	v_pk_mul_f32 v[190:191], v[66:67], v[186:187] op_sel_hi:[1,0]
	v_pk_mul_f32 v[192:193], v[64:65], v[186:187] op_sel_hi:[1,0]
	v_cvt_pk_bf16_f32 v182, v182, v183
	v_cvt_pk_bf16_f32 v183, v184, v185
	v_cvt_pk_bf16_f32 v184, v192, v193
	v_cvt_pk_bf16_f32 v185, v190, v191
	v_pk_mul_f32 v[124:125], v[124:125], v[186:187] op_sel_hi:[1,0]
	global_store_dwordx4 v[188:189], v[182:185], off
	v_pk_mul_f32 v[126:127], v[126:127], v[186:187] op_sel_hi:[1,0]
	s_nop 0
	v_pk_mul_f32 v[182:183], v[122:123], v[186:187] op_sel_hi:[1,0]
	v_pk_mul_f32 v[122:123], v[120:121], v[186:187] op_sel_hi:[1,0]
	v_cvt_pk_bf16_f32 v120, v124, v125
	v_cvt_pk_bf16_f32 v121, v126, v127
	v_cvt_pk_bf16_f32 v122, v122, v123
	v_cvt_pk_bf16_f32 v123, v182, v183
	global_store_dwordx4 v[188:189], v[120:123], off offset:256
	s_nop 1
	v_mov_b32_e32 v124, v229
	v_mad_i64_i32 v[120:121], s[18:19], v160, s42, v[164:165]
	v_lshl_add_u64 v[126:127], v[120:121], 0, v[166:167]
	v_pk_mul_f32 v[122:123], v[62:63], v[124:125] op_sel_hi:[1,0]
	v_pk_mul_f32 v[120:121], v[60:61], v[124:125] op_sel_hi:[1,0]
	v_pk_mul_f32 v[182:183], v[58:59], v[124:125] op_sel_hi:[1,0]
	v_pk_mul_f32 v[184:185], v[56:57], v[124:125] op_sel_hi:[1,0]
	v_cvt_pk_bf16_f32 v120, v120, v121
	v_cvt_pk_bf16_f32 v121, v122, v123
	v_cvt_pk_bf16_f32 v122, v184, v185
	v_cvt_pk_bf16_f32 v123, v182, v183
	v_pk_mul_f32 v[116:117], v[116:117], v[124:125] op_sel_hi:[1,0]
; __device__ __forceinline__ unsigned pk2(float lo, float hi) { const f32x2 v = (f32x2){lo, hi}; const bf16x2_t b = __builtin_convertvector(v, bf16x2_t); return __builtin_bit_cast(unsigned, b); }
;     __device__ __forceinline__ void operator()(const f32x4 (&acc)[2][2][4][2], const Unit& u, int wr, int wc, int fr, int fq, const float (&)[8]) const {
;     ...
;         const int col0 = u.pn * BM + wc * 32 + 8 * fq;
; #pragma unroll
;         for (int ai = 0; ai < 2; ++ai)
; #pragma unroll
;             for (int m = 0; m < 4; ++m) { const int row = row0 + ai * HALF + m * 16; const float rs = rsqrtf(ep[ai * 4 + m] * (1.0f / 1024.0f) + EPS);
;                 u16* rowp = O + (size_t)row * ldc + col0;
; #pragma unroll
;                 for (int bj = 0; bj < 2; ++bj) { f32x4 v0 = acc[ai][bj][m][0] * rs, v1 = acc[ai][bj][m][1] * rs;
;                     if (ACT == 1) {
; #pragma unroll
;                         for (int j = 0; j < 4; ++j) { const float a0 = fmaxf(v0[j], 0.f), a1 = fmaxf(v1[j], 0.f); v0[j] = a0 * a0; v1[j] = a1 * a1; } }
;                     u32x4 w; w.x = pk2(v0[0], v0[1]); w.y = pk2(v0[2], v0[3]); w.z = pk2(v1[0], v1[1]); w.w = pk2(v1[2], v1[3]);
;                     *(u32x4*)(rowp + bj * HALF) = w; } }
	global_store_dwordx4 v[126:127], v[120:123], off
	v_pk_mul_f32 v[118:119], v[118:119], v[124:125] op_sel_hi:[1,0]
	s_nop 0
	v_pk_mul_f32 v[120:121], v[114:115], v[124:125] op_sel_hi:[1,0]
	v_pk_mul_f32 v[114:115], v[112:113], v[124:125] op_sel_hi:[1,0]
	v_cvt_pk_bf16_f32 v112, v116, v117
	v_cvt_pk_bf16_f32 v113, v118, v119
	v_cvt_pk_bf16_f32 v114, v114, v115
	v_cvt_pk_bf16_f32 v115, v120, v121
	global_store_dwordx4 v[126:127], v[112:115], off offset:256
	s_nop 1
	v_mov_b32_e32 v116, v230
	v_mad_i64_i32 v[112:113], s[18:19], v158, s42, v[164:165]
	v_lshl_add_u64 v[118:119], v[112:113], 0, v[166:167]
	v_pk_mul_f32 v[114:115], v[50:51], v[116:117] op_sel_hi:[1,0]
	v_pk_mul_f32 v[112:113], v[48:49], v[116:117] op_sel_hi:[1,0]
	v_pk_mul_f32 v[120:121], v[42:43], v[116:117] op_sel_hi:[1,0]
	v_pk_mul_f32 v[122:123], v[40:41], v[116:117] op_sel_hi:[1,0]
	v_cvt_pk_bf16_f32 v112, v112, v113
	v_cvt_pk_bf16_f32 v113, v114, v115
	v_cvt_pk_bf16_f32 v114, v122, v123
	v_cvt_pk_bf16_f32 v115, v120, v121
	v_pk_mul_f32 v[108:109], v[108:109], v[116:117] op_sel_hi:[1,0]
	global_store_dwordx4 v[118:119], v[112:115], off
	v_pk_mul_f32 v[110:111], v[110:111], v[116:117] op_sel_hi:[1,0]
	s_nop 0
	v_pk_mul_f32 v[112:113], v[106:107], v[116:117] op_sel_hi:[1,0]
	v_pk_mul_f32 v[106:107], v[104:105], v[116:117] op_sel_hi:[1,0]
	v_cvt_pk_bf16_f32 v104, v108, v109
	v_cvt_pk_bf16_f32 v105, v110, v111
	v_cvt_pk_bf16_f32 v106, v106, v107
	v_cvt_pk_bf16_f32 v107, v112, v113
	global_store_dwordx4 v[118:119], v[104:107], off offset:256
	s_nop 1
	v_mov_b32_e32 v108, v231
	v_mad_i64_i32 v[104:105], s[18:19], v156, s42, v[164:165]
	v_lshl_add_u64 v[110:111], v[104:105], 0, v[166:167]
	v_pk_mul_f32 v[106:107], v[38:39], v[108:109] op_sel_hi:[1,0]
	v_pk_mul_f32 v[104:105], v[36:37], v[108:109] op_sel_hi:[1,0]
	v_pk_mul_f32 v[112:113], v[34:35], v[108:109] op_sel_hi:[1,0]
	v_pk_mul_f32 v[114:115], v[32:33], v[108:109] op_sel_hi:[1,0]
	v_cvt_pk_bf16_f32 v104, v104, v105
	v_cvt_pk_bf16_f32 v105, v106, v107
	v_cvt_pk_bf16_f32 v106, v114, v115
	v_cvt_pk_bf16_f32 v107, v112, v113
	v_pk_mul_f32 v[100:101], v[100:101], v[108:109] op_sel_hi:[1,0]
	global_store_dwordx4 v[110:111], v[104:107], off
	v_pk_mul_f32 v[102:103], v[102:103], v[108:109] op_sel_hi:[1,0]
	s_nop 0
	v_pk_mul_f32 v[104:105], v[98:99], v[108:109] op_sel_hi:[1,0]
	v_pk_mul_f32 v[98:99], v[96:97], v[108:109] op_sel_hi:[1,0]
	v_cvt_pk_bf16_f32 v96, v100, v101
	v_cvt_pk_bf16_f32 v97, v102, v103
	v_cvt_pk_bf16_f32 v98, v98, v99
	v_cvt_pk_bf16_f32 v99, v104, v105
	global_store_dwordx4 v[110:111], v[96:99], off offset:256
	s_nop 1
	v_mov_b32_e32 v100, v232
	v_mad_i64_i32 v[96:97], s[18:19], v154, s42, v[164:165]
	v_lshl_add_u64 v[102:103], v[96:97], 0, v[166:167]
	v_pk_mul_f32 v[98:99], v[30:31], v[100:101] op_sel_hi:[1,0]
	v_pk_mul_f32 v[96:97], v[28:29], v[100:101] op_sel_hi:[1,0]
	v_pk_mul_f32 v[104:105], v[26:27], v[100:101] op_sel_hi:[1,0]
	v_pk_mul_f32 v[106:107], v[24:25], v[100:101] op_sel_hi:[1,0]
	v_cvt_pk_bf16_f32 v96, v96, v97
	v_cvt_pk_bf16_f32 v97, v98, v99
	v_cvt_pk_bf16_f32 v98, v106, v107
	v_cvt_pk_bf16_f32 v99, v104, v105
	v_pk_mul_f32 v[92:93], v[92:93], v[100:101] op_sel_hi:[1,0]
	global_store_dwordx4 v[102:103], v[96:99], off
	v_pk_mul_f32 v[94:95], v[94:95], v[100:101] op_sel_hi:[1,0]
	s_nop 0
	v_pk_mul_f32 v[96:97], v[90:91], v[100:101] op_sel_hi:[1,0]
	v_pk_mul_f32 v[90:91], v[88:89], v[100:101] op_sel_hi:[1,0]
	v_cvt_pk_bf16_f32 v88, v92, v93
	v_cvt_pk_bf16_f32 v89, v94, v95
	v_cvt_pk_bf16_f32 v90, v90, v91
	v_cvt_pk_bf16_f32 v91, v96, v97
	global_store_dwordx4 v[102:103], v[88:91], off offset:256
	s_nop 1
	v_mov_b32_e32 v92, v233
	v_mad_i64_i32 v[88:89], s[18:19], v150, s42, v[164:165]
	v_lshl_add_u64 v[94:95], v[88:89], 0, v[166:167]
	v_pk_mul_f32 v[90:91], v[22:23], v[92:93] op_sel_hi:[1,0]
	v_pk_mul_f32 v[88:89], v[20:21], v[92:93] op_sel_hi:[1,0]
	v_pk_mul_f32 v[96:97], v[18:19], v[92:93] op_sel_hi:[1,0]
	v_pk_mul_f32 v[98:99], v[16:17], v[92:93] op_sel_hi:[1,0]
	v_cvt_pk_bf16_f32 v88, v88, v89
	v_cvt_pk_bf16_f32 v89, v90, v91
	v_cvt_pk_bf16_f32 v90, v98, v99
	v_cvt_pk_bf16_f32 v91, v96, v97
	v_pk_mul_f32 v[84:85], v[84:85], v[92:93] op_sel_hi:[1,0]
	global_store_dwordx4 v[94:95], v[88:91], off
	v_pk_mul_f32 v[86:87], v[86:87], v[92:93] op_sel_hi:[1,0]
	s_nop 0
	v_pk_mul_f32 v[88:89], v[82:83], v[92:93] op_sel_hi:[1,0]
	v_pk_mul_f32 v[82:83], v[80:81], v[92:93] op_sel_hi:[1,0]
	v_cvt_pk_bf16_f32 v80, v84, v85
	v_cvt_pk_bf16_f32 v81, v86, v87
	v_cvt_pk_bf16_f32 v82, v82, v83
	v_cvt_pk_bf16_f32 v83, v88, v89
	global_store_dwordx4 v[94:95], v[80:83], off offset:256
	s_nop 1
	v_mov_b32_e32 v84, v234
	v_mad_i64_i32 v[80:81], s[18:19], v148, s42, v[164:165]
	v_lshl_add_u64 v[86:87], v[80:81], 0, v[166:167]
	v_pk_mul_f32 v[82:83], v[14:15], v[84:85] op_sel_hi:[1,0]
	v_pk_mul_f32 v[80:81], v[12:13], v[84:85] op_sel_hi:[1,0]
	v_pk_mul_f32 v[88:89], v[10:11], v[84:85] op_sel_hi:[1,0]
	v_pk_mul_f32 v[90:91], v[8:9], v[84:85] op_sel_hi:[1,0]
	v_cvt_pk_bf16_f32 v80, v80, v81
	v_cvt_pk_bf16_f32 v81, v82, v83
	v_cvt_pk_bf16_f32 v82, v90, v91
	v_cvt_pk_bf16_f32 v83, v88, v89
	v_pk_mul_f32 v[72:73], v[72:73], v[84:85] op_sel_hi:[1,0]
	global_store_dwordx4 v[86:87], v[80:83], off
	v_pk_mul_f32 v[74:75], v[74:75], v[84:85] op_sel_hi:[1,0]
	s_nop 0
	v_pk_mul_f32 v[80:81], v[70:71], v[84:85] op_sel_hi:[1,0]
	v_pk_mul_f32 v[70:71], v[68:69], v[84:85] op_sel_hi:[1,0]
	v_cvt_pk_bf16_f32 v68, v72, v73
	v_cvt_pk_bf16_f32 v69, v74, v75
	v_cvt_pk_bf16_f32 v70, v70, v71
	v_cvt_pk_bf16_f32 v71, v80, v81
	global_store_dwordx4 v[86:87], v[68:71], off offset:256
	s_nop 1
	v_mov_b32_e32 v72, v235
	v_mad_i64_i32 v[68:69], s[18:19], v146, s42, v[164:165]
	v_lshl_add_u64 v[74:75], v[68:69], 0, v[166:167]
	v_pk_mul_f32 v[70:71], v[6:7], v[72:73] op_sel_hi:[1,0]
	v_pk_mul_f32 v[68:69], v[4:5], v[72:73] op_sel_hi:[1,0]
	v_pk_mul_f32 v[80:81], v[2:3], v[72:73] op_sel_hi:[1,0]
	v_pk_mul_f32 v[82:83], v[0:1], v[72:73] op_sel_hi:[1,0]
	v_cvt_pk_bf16_f32 v68, v68, v69
	v_cvt_pk_bf16_f32 v69, v70, v71
	v_cvt_pk_bf16_f32 v70, v82, v83
	v_cvt_pk_bf16_f32 v71, v80, v81
	global_store_dwordx4 v[74:75], v[68:71], off
	v_pk_mul_f32 v[54:55], v[54:55], v[72:73] op_sel_hi:[1,0]
	v_pk_mul_f32 v[52:53], v[52:53], v[72:73] op_sel_hi:[1,0]
	v_pk_mul_f32 v[68:69], v[46:47], v[72:73] op_sel_hi:[1,0]
	v_pk_mul_f32 v[46:47], v[44:45], v[72:73] op_sel_hi:[1,0]
	v_cvt_pk_bf16_f32 v44, v52, v53
	v_cvt_pk_bf16_f32 v45, v54, v55
	v_cvt_pk_bf16_f32 v46, v46, v47
	v_cvt_pk_bf16_f32 v47, v68, v69
	global_store_dwordx4 v[74:75], v[44:47], off offset:256
	s_mov_b64 s[18:19], 0

; #define PG8_STAGE(bufoff, gbase, voff) do { _Pragma("unroll") for (int _i = 0; _i < 2; ++_i) \
;         __builtin_amdgcn_global_load_lds((const unsigned*)((const char*)(gbase) + (voff)[_i]), (LAS unsigned*)(lds + (bufoff) + ldsw + _i * 8192), 16, 0, 0); } while (0)
; #define PG8_LDA(dst, b, h) do { _Pragma("unroll") for (int m = 0; m < 4; ++m) _Pragma("unroll") for (int k = 0; k < 2; ++k) dst[m][k] = *(const LAS bf16x8*)(lds + PG8_SA(b, h) + aoff + m * 2048 + k * 1024); } while (0)
; #define PG8_LDB(dst, b, h) do { _Pragma("unroll") for (int n = 0; n < 2; ++n) _Pragma("unroll") for (int k = 0; k < 2; ++k) dst[n][k] = *(const LAS bf16x8*)(lds + PG8_SB(b, h) + boff + n * 2048 + k * 1024); } while (0)
; #define PG8_MMA(ai, bj, At, Bt) do { __builtin_amdgcn_s_setprio(1); _Pragma("unroll") for (int m = 0; m < 4; ++m) _Pragma("unroll") for (int n = 0; n < 2; ++n) _Pragma("unroll") for (int k = 0; k < 2; ++k) \
;         acc[ai][bj][m][n] = __builtin_amdgcn_mfma_f32_16x16x32_bf16(Bt[n][k], At[m][k], acc[ai][bj][m][n], 0, 0, 0); __builtin_amdgcn_s_setprio(0); } while (0)
; #define PG8_WAIT_V(n) asm volatile("s_waitcnt vmcnt(" #n ")" ::: "memory")
; #define PG8_BAR __builtin_amdgcn_s_barrier()
; template <class Epi>
; __device__ __forceinline__ void gemm_phase(LAS unsigned char* lds, const Gemm g, const StaticOrder& S, const Epi& E) {
;     ...
;         for (int t = 0; t < nt; t += 2) {
;             const bool last = (t == nt - 2);
;             const char* a1 = cA + (size_t)(t + 1) * kstep;
;             const char* a2 = last ? nA : cA + (size_t)(t + 2) * kstep; const char* b2 = last ? nB : cB + (size_t)(t + 2) * kstep;
;             const char* a3 = a2 + kstep; const char* b3 = b2 + kstep;
;             if (last) E.pre(cur, wr, fr, epre);
;             PG8_LDB(B0, 0, 0); PG8_SCHED; PG8_LDA(At, 0, 0); PG8_STAGE(PG8_SA(1, 1), a1 + hstepA, voffA);
;             PG8_WAIT_L(8); PG8_BAR; PG8_WAIT_L(0); PG8_MMA(0, 0, At, B0); PG8_BAR; PG8_SCHED;
;             PG8_LDB(B1, 0, 1); PG8_STAGE(PG8_SB(0, 0), b2, voffB);
;             PG8_BAR; PG8_WAIT_L(0); PG8_MMA(0, 1, At, B1); PG8_BAR;
;             PG8_LDA(At, 0, 1); PG8_STAGE(PG8_SA(0, 0), a2, voffA);
;             PG8_BAR; PG8_WAIT_L(0); PG8_MMA(1, 0, At, B0); PG8_BAR; PG8_SCHED;
;             PG8_STAGE(PG8_SB(0, 1), b2 + hstepB, voffB);
;             PG8_WAIT_V(6); PG8_BAR; PG8_MMA(1, 1, At, B1); PG8_BAR;
.LBB0_684:
	ds_read_b128 v[128:131], v191
	ds_read_b128 v[132:135], v191 offset:1024
	ds_read_b128 v[136:139], v191 offset:2048
	ds_read_b128 v[140:143], v191 offset:3072
	s_add_u32 s22, s4, 0xffec0080
	s_addc_u32 s23, s5, -1
	s_cmp_eq_u32 s48, 28
	s_cselect_b32 s25, s19, s23
	s_cselect_b32 s24, s18, s22
	s_cselect_b32 s23, s17, s47
	s_cselect_b32 s22, s45, s46
	v_lshl_add_u64 v[186:187], s[4:5], 0, v[162:163]
	s_add_i32 m0, s11, 0xc000
	ds_read_b128 v[144:147], v192
	ds_read_b128 v[148:151], v192 offset:1024
	ds_read_b128 v[170:173], v192 offset:2048
	ds_read_b128 v[174:177], v192 offset:3072
	ds_read_b128 v[178:181], v192 offset:4096
	ds_read_b128 v[182:185], v192 offset:5120
	ds_read_b128 v[196:199], v192 offset:6144
	ds_read_b128 v[200:203], v192 offset:7168
	global_load_lds_dwordx4 v[186:187], off
	v_lshl_add_u64 v[186:187], s[4:5], 0, v[164:165]
	s_add_i32 m0, s11, 0xe000
	s_nop 0
	global_load_lds_dwordx4 v[186:187], off
	s_waitcnt lgkmcnt(8)
	s_barrier
	s_waitcnt lgkmcnt(0)
	v_mfma_f32_16x16x32_bf16 v[124:127], v[128:131], v[144:147], v[124:127]
	v_mfma_f32_16x16x32_bf16 v[120:123], v[136:139], v[144:147], v[120:123]
	v_mfma_f32_16x16x32_bf16 v[108:111], v[128:131], v[170:173], v[108:111]
	v_mfma_f32_16x16x32_bf16 v[104:107], v[136:139], v[170:173], v[104:107]
	v_mfma_f32_16x16x32_bf16 v[92:95], v[128:131], v[178:181], v[92:95]
	v_mfma_f32_16x16x32_bf16 v[88:91], v[136:139], v[178:181], v[88:91]
	v_mfma_f32_16x16x32_bf16 v[76:79], v[128:131], v[196:199], v[76:79]
	v_mfma_f32_16x16x32_bf16 v[72:75], v[136:139], v[196:199], v[72:75]
	v_mfma_f32_16x16x32_bf16 v[124:127], v[132:135], v[148:151], v[124:127]
	v_mfma_f32_16x16x32_bf16 v[120:123], v[140:143], v[148:151], v[120:123]
	v_mfma_f32_16x16x32_bf16 v[108:111], v[132:135], v[174:177], v[108:111]
	v_mfma_f32_16x16x32_bf16 v[104:107], v[140:143], v[174:177], v[104:107]
	v_mfma_f32_16x16x32_bf16 v[92:95], v[132:135], v[182:185], v[92:95]
	v_mfma_f32_16x16x32_bf16 v[88:91], v[140:143], v[182:185], v[88:91]
	v_mfma_f32_16x16x32_bf16 v[76:79], v[132:135], v[200:203], v[76:79]
	v_mfma_f32_16x16x32_bf16 v[72:75], v[140:143], v[200:203], v[72:75]
	s_barrier
	s_add_i32 s49, s42, s31
	v_lshl_add_u64 v[186:187], s[22:23], 0, v[156:157]
	s_mov_b32 m0, s49
	ds_read_b128 v[204:207], v193
	ds_read_b128 v[208:211], v193 offset:1024
	ds_read_b128 v[212:215], v193 offset:2048
	ds_read_b128 v[216:219], v193 offset:3072
	global_load_lds_dwordx4 v[186:187], off
	v_lshl_add_u64 v[220:221], s[22:23], 0, v[160:161]
	s_add_i32 m0, s49, 0x2000
	s_nop 0
	global_load_lds_dwordx4 v[220:221], off
	s_barrier
	s_waitcnt lgkmcnt(0)
	v_mfma_f32_16x16x32_bf16 v[116:119], v[204:207], v[144:147], v[116:119]
	v_mfma_f32_16x16x32_bf16 v[112:115], v[212:215], v[144:147], v[112:115]
	v_mfma_f32_16x16x32_bf16 v[100:103], v[204:207], v[170:173], v[100:103]
	v_mfma_f32_16x16x32_bf16 v[96:99], v[212:215], v[170:173], v[96:99]
	v_mfma_f32_16x16x32_bf16 v[84:87], v[204:207], v[178:181], v[84:87]
	v_mfma_f32_16x16x32_bf16 v[80:83], v[212:215], v[178:181], v[80:83]
	v_mfma_f32_16x16x32_bf16 v[68:71], v[204:207], v[196:199], v[68:71]
	v_mfma_f32_16x16x32_bf16 v[64:67], v[212:215], v[196:199], v[64:67]
	v_mfma_f32_16x16x32_bf16 v[116:119], v[208:211], v[148:151], v[116:119]
	v_mfma_f32_16x16x32_bf16 v[112:115], v[216:219], v[148:151], v[112:115]
	v_mfma_f32_16x16x32_bf16 v[100:103], v[208:211], v[174:177], v[100:103]
	v_mfma_f32_16x16x32_bf16 v[96:99], v[216:219], v[174:177], v[96:99]
	v_mfma_f32_16x16x32_bf16 v[84:87], v[208:211], v[182:185], v[84:87]
	v_mfma_f32_16x16x32_bf16 v[80:83], v[216:219], v[182:185], v[80:83]
	v_mfma_f32_16x16x32_bf16 v[68:71], v[208:211], v[200:203], v[68:71]
	v_mfma_f32_16x16x32_bf16 v[64:67], v[216:219], v[200:203], v[64:67]
	s_mov_b32 m0, s11
	v_lshl_add_u64 v[222:223], s[24:25], 0, v[154:155]
	s_barrier
	ds_read_b128 v[144:147], v192 offset:16384
	ds_read_b128 v[148:151], v192 offset:17408
	ds_read_b128 v[170:173], v192 offset:18432
	ds_read_b128 v[174:177], v192 offset:19456
	ds_read_b128 v[178:181], v192 offset:20480
	ds_read_b128 v[182:185], v192 offset:21504
	ds_read_b128 v[196:199], v192 offset:22528
	ds_read_b128 v[200:203], v192 offset:23552
	global_load_lds_dwordx4 v[222:223], off
	v_lshl_add_u64 v[224:225], s[24:25], 0, v[158:159]
	s_mov_b32 m0, s34
	s_nop 0
	global_load_lds_dwordx4 v[224:225], off
	s_barrier
	s_waitcnt lgkmcnt(0)
	v_mfma_f32_16x16x32_bf16 v[60:63], v[128:131], v[144:147], v[60:63]
	v_mfma_f32_16x16x32_bf16 v[56:59], v[136:139], v[144:147], v[56:59]
	v_mfma_f32_16x16x32_bf16 v[44:47], v[128:131], v[170:173], v[44:47]
	v_mfma_f32_16x16x32_bf16 v[40:43], v[136:139], v[170:173], v[40:43]
	v_mfma_f32_16x16x32_bf16 v[28:31], v[128:131], v[178:181], v[28:31]
	v_mfma_f32_16x16x32_bf16 v[24:27], v[136:139], v[178:181], v[24:27]
	v_mfma_f32_16x16x32_bf16 v[12:15], v[128:131], v[196:199], v[12:15]
	v_mfma_f32_16x16x32_bf16 v[8:11], v[136:139], v[196:199], v[8:11]
	v_mfma_f32_16x16x32_bf16 v[60:63], v[132:135], v[148:151], v[60:63]
	v_mfma_f32_16x16x32_bf16 v[56:59], v[140:143], v[148:151], v[56:59]
	v_mfma_f32_16x16x32_bf16 v[44:47], v[132:135], v[174:177], v[44:47]
	v_mfma_f32_16x16x32_bf16 v[40:43], v[140:143], v[174:177], v[40:43]
	v_mfma_f32_16x16x32_bf16 v[28:31], v[132:135], v[182:185], v[28:31]
	v_mfma_f32_16x16x32_bf16 v[24:27], v[140:143], v[182:185], v[24:27]
	v_mfma_f32_16x16x32_bf16 v[12:15], v[132:135], v[200:203], v[12:15]
	v_mfma_f32_16x16x32_bf16 v[8:11], v[140:143], v[200:203], v[8:11]
	s_barrier
; #define PG8_STAGE(bufoff, gbase, voff) do { _Pragma("unroll") for (int _i = 0; _i < 2; ++_i) \
;         __builtin_amdgcn_global_load_lds((const unsigned*)((const char*)(gbase) + (voff)[_i]), (LAS unsigned*)(lds + (bufoff) + ldsw + _i * 8192), 16, 0, 0); } while (0)
; #define PG8_LDA(dst, b, h) do { _Pragma("unroll") for (int m = 0; m < 4; ++m) _Pragma("unroll") for (int k = 0; k < 2; ++k) dst[m][k] = *(const LAS bf16x8*)(lds + PG8_SA(b, h) + aoff + m * 2048 + k * 1024); } while (0)
; #define PG8_LDB(dst, b, h) do { _Pragma("unroll") for (int n = 0; n < 2; ++n) _Pragma("unroll") for (int k = 0; k < 2; ++k) dst[n][k] = *(const LAS bf16x8*)(lds + PG8_SB(b, h) + boff + n * 2048 + k * 1024); } while (0)
; #define PG8_MMA(ai, bj, At, Bt) do { __builtin_amdgcn_s_setprio(1); _Pragma("unroll") for (int m = 0; m < 4; ++m) _Pragma("unroll") for (int n = 0; n < 2; ++n) _Pragma("unroll") for (int k = 0; k < 2; ++k) \
;         acc[ai][bj][m][n] = __builtin_amdgcn_mfma_f32_16x16x32_bf16(Bt[n][k], At[m][k], acc[ai][bj][m][n], 0, 0, 0); __builtin_amdgcn_s_setprio(0); } while (0)
; #define PG8_WAIT_V(n) asm volatile("s_waitcnt vmcnt(" #n ")" ::: "memory")
; #define PG8_WAIT_L(n) asm volatile("s_waitcnt lgkmcnt(" #n ")" ::: "memory")
; #define PG8_BAR __builtin_amdgcn_s_barrier()
; #define PG8_SCHED __builtin_amdgcn_sched_barrier(0)
; template <class Epi>
; __device__ __forceinline__ void gemm_phase(LAS unsigned char* lds, const Gemm g, const StaticOrder& S, const Epi& E) {
;     ...
;             PG8_WAIT_V(6); PG8_BAR; PG8_MMA(1, 1, At, B1); PG8_BAR;
;             PG8_LDB(B0, 1, 0); PG8_SCHED; PG8_LDA(At, 1, 0); PG8_STAGE(PG8_SA(0, 1), a2 + hstepA, voffA);
;             PG8_WAIT_L(8); PG8_BAR; PG8_WAIT_L(0); PG8_MMA(0, 0, At, B0); PG8_BAR; PG8_SCHED;
;             PG8_LDB(B1, 1, 1); PG8_STAGE(PG8_SB(1, 0), b3, voffB);
;             PG8_BAR; PG8_WAIT_L(0); PG8_MMA(0, 1, At, B1); PG8_BAR;
;             PG8_LDA(At, 1, 1); PG8_STAGE(PG8_SA(1, 0), a3, voffA);
;             PG8_BAR; PG8_WAIT_L(0); PG8_MMA(1, 0, At, B0); PG8_BAR; PG8_SCHED;
	s_add_u32 s50, s22, 0x80000
	s_addc_u32 s51, s23, 0
	s_add_i32 s49, s43, s31
	v_lshl_add_u64 v[128:129], s[50:51], 0, v[156:157]
	s_mov_b32 m0, s49
	s_nop 0
	global_load_lds_dwordx4 v[128:129], off
	v_lshl_add_u64 v[128:129], s[50:51], 0, v[160:161]
	s_add_i32 m0, s49, 0x2000
	s_nop 0
	global_load_lds_dwordx4 v[128:129], off
	s_waitcnt vmcnt(6)
	s_barrier
	v_mfma_f32_16x16x32_bf16 v[52:55], v[204:207], v[144:147], v[52:55]
	v_mfma_f32_16x16x32_bf16 v[48:51], v[212:215], v[144:147], v[48:51]
	v_mfma_f32_16x16x32_bf16 v[36:39], v[204:207], v[170:173], v[36:39]
	v_mfma_f32_16x16x32_bf16 v[32:35], v[212:215], v[170:173], v[32:35]
	v_mfma_f32_16x16x32_bf16 v[20:23], v[204:207], v[178:181], v[20:23]
	v_mfma_f32_16x16x32_bf16 v[16:19], v[212:215], v[178:181], v[16:19]
	v_mfma_f32_16x16x32_bf16 v[4:7], v[204:207], v[196:199], v[4:7]
	v_mfma_f32_16x16x32_bf16 v[0:3], v[212:215], v[196:199], v[0:3]
	v_mfma_f32_16x16x32_bf16 v[52:55], v[208:211], v[148:151], v[52:55]
	v_mfma_f32_16x16x32_bf16 v[48:51], v[216:219], v[148:151], v[48:51]
	v_mfma_f32_16x16x32_bf16 v[36:39], v[208:211], v[174:177], v[36:39]
	v_mfma_f32_16x16x32_bf16 v[32:35], v[216:219], v[174:177], v[32:35]
	v_mfma_f32_16x16x32_bf16 v[20:23], v[208:211], v[182:185], v[20:23]
	v_mfma_f32_16x16x32_bf16 v[16:19], v[216:219], v[182:185], v[16:19]
	v_mfma_f32_16x16x32_bf16 v[4:7], v[208:211], v[200:203], v[4:7]
	v_mfma_f32_16x16x32_bf16 v[0:3], v[216:219], v[200:203], v[0:3]
	s_add_i32 s49, 0, 0x18000
	v_add_u32_e32 v140, s49, v189
	s_barrier
	ds_read_b128 v[128:131], v140
	ds_read_b128 v[132:135], v140 offset:1024
	ds_read_b128 v[136:139], v140 offset:2048
	ds_read_b128 v[140:143], v140 offset:3072
	s_add_u32 s24, s24, 0x140000
	s_addc_u32 s25, s25, 0
	s_mov_b32 m0, s35
	v_lshl_add_u64 v[204:205], s[24:25], 0, v[154:155]
	ds_read_b128 v[144:147], v192 offset:32768
	ds_read_b128 v[148:151], v192 offset:33792
	ds_read_b128 v[170:173], v192 offset:34816
	ds_read_b128 v[174:177], v192 offset:35840
	ds_read_b128 v[178:181], v192 offset:36864
	ds_read_b128 v[182:185], v192 offset:37888
	ds_read_b128 v[196:199], v192 offset:38912
	ds_read_b128 v[200:203], v192 offset:39936
	global_load_lds_dwordx4 v[204:205], off
	v_lshl_add_u64 v[204:205], s[24:25], 0, v[158:159]
	s_mov_b32 m0, s36
	s_nop 0
	global_load_lds_dwordx4 v[204:205], off
	s_waitcnt lgkmcnt(8)
	s_barrier
	s_waitcnt lgkmcnt(0)
	v_mfma_f32_16x16x32_bf16 v[124:127], v[128:131], v[144:147], v[124:127]
	v_mfma_f32_16x16x32_bf16 v[120:123], v[136:139], v[144:147], v[120:123]
	v_mfma_f32_16x16x32_bf16 v[108:111], v[128:131], v[170:173], v[108:111]
	v_mfma_f32_16x16x32_bf16 v[104:107], v[136:139], v[170:173], v[104:107]
	v_mfma_f32_16x16x32_bf16 v[92:95], v[128:131], v[178:181], v[92:95]
	v_mfma_f32_16x16x32_bf16 v[88:91], v[136:139], v[178:181], v[88:91]
	v_mfma_f32_16x16x32_bf16 v[76:79], v[128:131], v[196:199], v[76:79]
	v_mfma_f32_16x16x32_bf16 v[72:75], v[136:139], v[196:199], v[72:75]
	v_mfma_f32_16x16x32_bf16 v[124:127], v[132:135], v[148:151], v[124:127]
	v_mfma_f32_16x16x32_bf16 v[120:123], v[140:143], v[148:151], v[120:123]
	v_mfma_f32_16x16x32_bf16 v[108:111], v[132:135], v[174:177], v[108:111]
	v_mfma_f32_16x16x32_bf16 v[104:107], v[140:143], v[174:177], v[104:107]
	v_mfma_f32_16x16x32_bf16 v[92:95], v[132:135], v[182:185], v[92:95]
	v_mfma_f32_16x16x32_bf16 v[88:91], v[140:143], v[182:185], v[88:91]
	v_mfma_f32_16x16x32_bf16 v[76:79], v[132:135], v[200:203], v[76:79]
	v_mfma_f32_16x16x32_bf16 v[72:75], v[140:143], v[200:203], v[72:75]
	s_barrier
	s_add_i32 s24, 0, 0x1c000
	s_add_i32 s25, s49, s31
	v_add_u32_e32 v195, s24, v189
	v_lshl_add_u64 v[186:187], v[186:187], 0, s[14:15]
	s_mov_b32 m0, s25
	ds_read_b128 v[204:207], v195
	ds_read_b128 v[208:211], v195 offset:1024
	ds_read_b128 v[212:215], v195 offset:2048
	ds_read_b128 v[216:219], v195 offset:3072
	global_load_lds_dwordx4 v[186:187], off
	v_lshl_add_u64 v[186:187], v[220:221], 0, s[14:15]
	s_add_i32 m0, s25, 0x2000
	s_nop 0
	global_load_lds_dwordx4 v[186:187], off
	s_barrier
	s_waitcnt lgkmcnt(0)
	v_mfma_f32_16x16x32_bf16 v[116:119], v[204:207], v[144:147], v[116:119]
	v_mfma_f32_16x16x32_bf16 v[112:115], v[212:215], v[144:147], v[112:115]
	v_mfma_f32_16x16x32_bf16 v[100:103], v[204:207], v[170:173], v[100:103]
	v_mfma_f32_16x16x32_bf16 v[96:99], v[212:215], v[170:173], v[96:99]
	v_mfma_f32_16x16x32_bf16 v[84:87], v[204:207], v[178:181], v[84:87]
	v_mfma_f32_16x16x32_bf16 v[80:83], v[212:215], v[178:181], v[80:83]
	v_mfma_f32_16x16x32_bf16 v[68:71], v[204:207], v[196:199], v[68:71]
	v_mfma_f32_16x16x32_bf16 v[64:67], v[212:215], v[196:199], v[64:67]
	v_mfma_f32_16x16x32_bf16 v[116:119], v[208:211], v[148:151], v[116:119]
	v_mfma_f32_16x16x32_bf16 v[112:115], v[216:219], v[148:151], v[112:115]
	v_mfma_f32_16x16x32_bf16 v[100:103], v[208:211], v[174:177], v[100:103]
	v_mfma_f32_16x16x32_bf16 v[96:99], v[216:219], v[174:177], v[96:99]
	v_mfma_f32_16x16x32_bf16 v[84:87], v[208:211], v[182:185], v[84:87]
	v_mfma_f32_16x16x32_bf16 v[80:83], v[216:219], v[182:185], v[80:83]
	v_mfma_f32_16x16x32_bf16 v[68:71], v[208:211], v[200:203], v[68:71]
	v_mfma_f32_16x16x32_bf16 v[64:67], v[216:219], v[200:203], v[64:67]
	s_mov_b32 m0, s38
	v_lshl_add_u64 v[186:187], v[222:223], 0, s[14:15]
	s_barrier
	ds_read_b128 v[144:147], v192 offset:49152
	ds_read_b128 v[148:151], v192 offset:50176
	ds_read_b128 v[170:173], v192 offset:51200
	ds_read_b128 v[174:177], v192 offset:52224
	ds_read_b128 v[178:181], v192 offset:53248
	ds_read_b128 v[182:185], v192 offset:54272
	ds_read_b128 v[196:199], v192 offset:55296
	ds_read_b128 v[200:203], v192 offset:56320
	global_load_lds_dwordx4 v[186:187], off
	v_lshl_add_u64 v[186:187], v[224:225], 0, s[14:15]
	s_mov_b32 m0, s39
	s_nop 0
	global_load_lds_dwordx4 v[186:187], off
	s_barrier
; #define PG8_STAGE(bufoff, gbase, voff) do { _Pragma("unroll") for (int _i = 0; _i < 2; ++_i) \
;         __builtin_amdgcn_global_load_lds((const unsigned*)((const char*)(gbase) + (voff)[_i]), (LAS unsigned*)(lds + (bufoff) + ldsw + _i * 8192), 16, 0, 0); } while (0)
; #define PG8_LDA(dst, b, h) do { _Pragma("unroll") for (int m = 0; m < 4; ++m) _Pragma("unroll") for (int k = 0; k < 2; ++k) dst[m][k] = *(const LAS bf16x8*)(lds + PG8_SA(b, h) + aoff + m * 2048 + k * 1024); } while (0)
; #define PG8_LDB(dst, b, h) do { _Pragma("unroll") for (int n = 0; n < 2; ++n) _Pragma("unroll") for (int k = 0; k < 2; ++k) dst[n][k] = *(const LAS bf16x8*)(lds + PG8_SB(b, h) + boff + n * 2048 + k * 1024); } while (0)
; #define PG8_MMA(ai, bj, At, Bt) do { __builtin_amdgcn_s_setprio(1); _Pragma("unroll") for (int m = 0; m < 4; ++m) _Pragma("unroll") for (int n = 0; n < 2; ++n) _Pragma("unroll") for (int k = 0; k < 2; ++k) \
;         acc[ai][bj][m][n] = __builtin_amdgcn_mfma_f32_16x16x32_bf16(Bt[n][k], At[m][k], acc[ai][bj][m][n], 0, 0, 0); __builtin_amdgcn_s_setprio(0); } while (0)
; #define PG8_WAIT_V(n) asm volatile("s_waitcnt vmcnt(" #n ")" ::: "memory")
; #define PG8_WAIT_L(n) asm volatile("s_waitcnt lgkmcnt(" #n ")" ::: "memory")
; #define PG8_BAR __builtin_amdgcn_s_barrier()
; #define PG8_SCHED __builtin_amdgcn_sched_barrier(0)
; template <class Epi>
; __device__ __forceinline__ void gemm_phase(LAS unsigned char* lds, const Gemm g, const StaticOrder& S, const Epi& E) {
;     ...
;             PG8_WAIT_V(6); PG8_BAR; PG8_MMA(1, 1, At, B1); PG8_BAR;
;             PG8_LDB(B0, 1, 0); PG8_SCHED; PG8_LDA(At, 1, 0); PG8_STAGE(PG8_SA(0, 1), a2 + hstepA, voffA);
;             PG8_WAIT_L(8); PG8_BAR; PG8_WAIT_L(0); PG8_MMA(0, 0, At, B0); PG8_BAR; PG8_SCHED;
;             PG8_LDB(B1, 1, 1); PG8_STAGE(PG8_SB(1, 0), b3, voffB);
;             PG8_BAR; PG8_WAIT_L(0); PG8_MMA(0, 1, At, B1); PG8_BAR;
;             PG8_LDA(At, 1, 1); PG8_STAGE(PG8_SA(1, 0), a3, voffA);
;             PG8_BAR; PG8_WAIT_L(0); PG8_MMA(1, 0, At, B0); PG8_BAR; PG8_SCHED;
;             PG8_STAGE(PG8_SB(1, 1), b3 + hstepB, voffB);
;             PG8_WAIT_V(6); PG8_BAR; PG8_MMA(1, 1, At, B1); PG8_BAR;
	s_waitcnt lgkmcnt(0)
	v_mfma_f32_16x16x32_bf16 v[60:63], v[128:131], v[144:147], v[60:63]
	v_mfma_f32_16x16x32_bf16 v[56:59], v[136:139], v[144:147], v[56:59]
	v_mfma_f32_16x16x32_bf16 v[44:47], v[128:131], v[170:173], v[44:47]
	v_mfma_f32_16x16x32_bf16 v[40:43], v[136:139], v[170:173], v[40:43]
	v_mfma_f32_16x16x32_bf16 v[28:31], v[128:131], v[178:181], v[28:31]
	v_mfma_f32_16x16x32_bf16 v[24:27], v[136:139], v[178:181], v[24:27]
	v_mfma_f32_16x16x32_bf16 v[12:15], v[128:131], v[196:199], v[12:15]
	v_mfma_f32_16x16x32_bf16 v[8:11], v[136:139], v[196:199], v[8:11]
	v_mfma_f32_16x16x32_bf16 v[60:63], v[132:135], v[148:151], v[60:63]
	v_mfma_f32_16x16x32_bf16 v[56:59], v[140:143], v[148:151], v[56:59]
	v_mfma_f32_16x16x32_bf16 v[44:47], v[132:135], v[174:177], v[44:47]
	v_mfma_f32_16x16x32_bf16 v[40:43], v[140:143], v[174:177], v[40:43]
	v_mfma_f32_16x16x32_bf16 v[28:31], v[132:135], v[182:185], v[28:31]
	v_mfma_f32_16x16x32_bf16 v[24:27], v[140:143], v[182:185], v[24:27]
	v_mfma_f32_16x16x32_bf16 v[12:15], v[132:135], v[200:203], v[12:15]
	v_mfma_f32_16x16x32_bf16 v[8:11], v[140:143], v[200:203], v[8:11]
	s_barrier
	s_add_u32 s22, s22, 0x80080
	s_addc_u32 s23, s23, 0
	s_add_i32 s24, s24, s31
	v_lshl_add_u64 v[128:129], s[22:23], 0, v[156:157]
	s_mov_b32 m0, s24
	s_nop 0
	global_load_lds_dwordx4 v[128:129], off
	v_lshl_add_u64 v[128:129], s[22:23], 0, v[160:161]
	s_add_i32 m0, s24, 0x2000
	s_nop 0
	global_load_lds_dwordx4 v[128:129], off
	s_waitcnt vmcnt(6)
	s_barrier
	v_mfma_f32_16x16x32_bf16 v[52:55], v[204:207], v[144:147], v[52:55]
	v_mfma_f32_16x16x32_bf16 v[48:51], v[212:215], v[144:147], v[48:51]
	v_mfma_f32_16x16x32_bf16 v[36:39], v[204:207], v[170:173], v[36:39]
	v_mfma_f32_16x16x32_bf16 v[32:35], v[212:215], v[170:173], v[32:35]
	v_mfma_f32_16x16x32_bf16 v[20:23], v[204:207], v[178:181], v[20:23]
	v_mfma_f32_16x16x32_bf16 v[16:19], v[212:215], v[178:181], v[16:19]
	v_mfma_f32_16x16x32_bf16 v[4:7], v[204:207], v[196:199], v[4:7]
	v_mfma_f32_16x16x32_bf16 v[0:3], v[212:215], v[196:199], v[0:3]
	v_mfma_f32_16x16x32_bf16 v[52:55], v[208:211], v[148:151], v[52:55]
	v_mfma_f32_16x16x32_bf16 v[48:51], v[216:219], v[148:151], v[48:51]
	v_mfma_f32_16x16x32_bf16 v[36:39], v[208:211], v[174:177], v[36:39]
	v_mfma_f32_16x16x32_bf16 v[32:35], v[216:219], v[174:177], v[32:35]
	v_mfma_f32_16x16x32_bf16 v[20:23], v[208:211], v[182:185], v[20:23]
	v_mfma_f32_16x16x32_bf16 v[16:19], v[216:219], v[182:185], v[16:19]
	v_mfma_f32_16x16x32_bf16 v[4:7], v[208:211], v[200:203], v[4:7]
	v_mfma_f32_16x16x32_bf16 v[0:3], v[216:219], v[200:203], v[0:3]
	s_add_i32 s48, s48, 2
	s_add_u32 s4, s4, 0x100
	s_addc_u32 s5, s5, 0
	s_add_u32 s46, s46, 0x100
	s_addc_u32 s47, s47, 0
	s_cmp_gt_u32 s48, 29
	s_barrier
	s_cbranch_scc0 .LBB0_684
; __device__ __forceinline__ unsigned pk2(float lo, float hi) { const f32x2 v = (f32x2){lo, hi}; const bf16x2_t b = __builtin_convertvector(v, bf16x2_t); return __builtin_bit_cast(unsigned, b); }
; __device__ __forceinline__ void unpack8(const u32x4 v, float* f) { f[0] = bf_lo(v.x); f[1] = bf_hi(v.x); f[2] = bf_lo(v.y); f[3] = bf_hi(v.y); f[4] = bf_lo(v.z); f[5] = bf_hi(v.z); f[6] = bf_lo(v.w); f[7] = bf_hi(v.w); }
;     __device__ __forceinline__ void operator()(const f32x4 (&acc)[2][2][4][2], const Unit& u, int wr, int wc, int fr, int fq, const float (&)[8]) const {
;         const int row0 = u.pm * BM + wr * 64 + fr, col0 = u.pn * BM + wc * 32 + 8 * fq;
; #pragma unroll
;         for (int ai = 0; ai < 2; ++ai) {
;             u32x4 bv[4][2];
; #pragma unroll
;             for (int m = 0; m < 4; ++m)
; #pragma unroll
;                 for (int bj = 0; bj < 2; ++bj) bv[m][bj] = *(const u32x4*)(xb + (size_t)(row0 + ai * HALF + m * 16) * DM + col0 + bj * HALF);
; #pragma unroll
;             for (int m = 0; m < 4; ++m) { const int row = row0 + ai * HALF + m * 16; const size_t ro = (size_t)row * DM + col0; float s = 0.f;
; #pragma unroll
;                 for (int bj = 0; bj < 2; ++bj) { float b8[8]; unpack8(bv[m][bj], b8);
;                     const f32x4 v0 = (f32x4){b8[0], b8[1], b8[2], b8[3]} + acc[ai][bj][m][0], v1 = (f32x4){b8[4], b8[5], b8[6], b8[7]} + acc[ai][bj][m][1];
;                     s += v0[0] * v0[0] + v0[1] * v0[1] + v0[2] * v0[2] + v0[3] * v0[3] + v1[0] * v1[0] + v1[1] * v1[1] + v1[2] * v1[2] + v1[3] * v1[3];
;                     if (LAST) { *(f32x4*)(out + ro + bj * HALF) = v0; *(f32x4*)(out + ro + bj * HALF + 4) = v1; }
;                     else { u32x4 w; w.x = pk2(v0[0], v0[1]); w.y = pk2(v0[2], v0[3]); w.z = pk2(v1[0], v1[1]); w.w = pk2(v1[2], v1[3]); *(u32x4*)(xb + ro + bj * HALF) = w; } }
;                 s += __shfl_xor(s, 16); s += __shfl_xor(s, 32);
;                 if (fq == 0) ss[(size_t)row * 16 + u.pn * 4 + wc] = s; }
	s_setprio 0
	v_lshl_or_b32 v170, s10, 8, v190
	v_lshl_add_u32 v172, s12, 8, v188
	v_ashrrev_i32_e32 v171, 31, v170
	v_lshlrev_b64 v[206:207], 1, v[170:171]
	v_ashrrev_i32_e32 v173, 31, v172
	v_lshl_add_u64 v[174:175], s[76:77], 0, v[206:207]
	v_lshlrev_b64 v[208:209], 11, v[172:173]
	v_lshl_add_u64 v[128:129], v[174:175], 0, v[208:209]
	global_load_dwordx4 v[198:201], v[128:129], off
	global_load_dwordx4 v[202:205], v[128:129], off offset:256
	v_or_b32_e32 v184, 16, v172
	v_or_b32_e32 v180, 32, v172
	v_or_b32_e32 v176, 48, v172
	v_ashrrev_i32_e32 v185, 31, v184
	v_ashrrev_i32_e32 v181, 31, v180
	v_ashrrev_i32_e32 v177, 31, v176
	v_lshlrev_b64 v[186:187], 11, v[184:185]
	v_lshlrev_b64 v[182:183], 11, v[180:181]
	v_lshlrev_b64 v[178:179], 11, v[176:177]
	v_lshl_add_u64 v[128:129], v[174:175], 0, v[186:187]
	v_lshl_add_u64 v[130:131], v[174:175], 0, v[182:183]
	v_lshl_add_u64 v[196:197], v[174:175], 0, v[178:179]
	global_load_dwordx4 v[148:151], v[128:129], off
	global_load_dwordx4 v[144:147], v[128:129], off offset:256
	global_load_dwordx4 v[140:143], v[130:131], off
	global_load_dwordx4 v[136:139], v[130:131], off offset:256
	global_load_dwordx4 v[132:135], v[196:197], off
	s_nop 0
	global_load_dwordx4 v[128:131], v[196:197], off offset:256
	v_add_u32_e32 v218, 0x80, v172
	v_ashrrev_i32_e32 v219, 31, v218
	v_lshlrev_b64 v[218:219], 11, v[218:219]
	v_lshl_add_u64 v[218:219], v[174:175], 0, v[218:219]
	global_load_dwordx4 v[220:223], v[218:219], off
	global_load_dwordx4 v[224:227], v[218:219], off offset:256
	v_add_u32_e32 v218, 0x90, v172
	v_ashrrev_i32_e32 v219, 31, v218
	v_lshlrev_b64 v[218:219], 11, v[218:219]
	v_lshl_add_u64 v[218:219], v[174:175], 0, v[218:219]
	global_load_dwordx4 v[228:231], v[218:219], off
	global_load_dwordx4 v[232:235], v[218:219], off offset:256
	v_add_u32_e32 v218, 0xa0, v172
	v_ashrrev_i32_e32 v219, 31, v218
	v_lshlrev_b64 v[218:219], 11, v[218:219]
	v_lshl_add_u64 v[218:219], v[174:175], 0, v[218:219]
	global_load_dwordx4 v[236:239], v[218:219], off
	global_load_dwordx4 v[240:243], v[218:219], off offset:256
	v_add_u32_e32 v218, 0xb0, v172
	v_ashrrev_i32_e32 v219, 31, v218
	v_lshlrev_b64 v[218:219], 11, v[218:219]
	v_lshl_add_u64 v[218:219], v[174:175], 0, v[218:219]
	global_load_dwordx4 v[244:247], v[218:219], off
	global_load_dwordx4 v[252:255], v[218:219], off offset:256
	v_and_b32_e32 v196, 64, v194
	v_xor_b32_e32 v195, 16, v194
	v_add_u32_e32 v196, 64, v196
	v_xor_b32_e32 v197, 32, v194
	v_cmp_lt_i32_e32 vcc, v195, v196
	s_waitcnt vmcnt(15)
	v_lshlrev_b32_e32 v210, 16, v198
	v_cndmask_b32_e32 v195, v194, v195, vcc
	v_cmp_lt_i32_e32 vcc, v197, v196
	v_and_b32_e32 v211, 0xffff0000, v198
	s_waitcnt vmcnt(14)
	v_lshlrev_b32_e32 v214, 16, v202
	v_and_b32_e32 v215, 0xffff0000, v202
	v_cndmask_b32_e32 v197, v194, v197, vcc
	v_lshlrev_b32_e32 v212, 16, v200
	v_and_b32_e32 v213, 0xffff0000, v200
	v_lshlrev_b32_e32 v200, 16, v201
	v_and_b32_e32 v201, 0xffff0000, v201
	v_lshlrev_b32_e32 v216, 16, v204
	v_and_b32_e32 v217, 0xffff0000, v204
	v_pk_add_f32 v[124:125], v[124:125], v[210:211]
	v_pk_add_f32 v[116:117], v[116:117], v[214:215]
	v_lshlrev_b32_e32 v196, 2, v195
	v_lshlrev_b32_e32 v195, 2, v197
	v_lshlrev_b32_e32 v198, 16, v199
	v_and_b32_e32 v199, 0xffff0000, v199
	v_lshlrev_b32_e32 v202, 16, v203
	v_and_b32_e32 v203, 0xffff0000, v203
	v_pk_add_f32 v[122:123], v[122:123], v[200:201]
	v_pk_add_f32 v[200:201], v[112:113], v[216:217]
	v_mul_f32_e32 v197, v125, v125
	v_cvt_pk_bf16_f32 v112, v124, v125
	v_mul_f32_e32 v125, v117, v117
	v_pk_add_f32 v[126:127], v[126:127], v[198:199]
	v_pk_add_f32 v[118:119], v[118:119], v[202:203]
	v_fmac_f32_e32 v197, v124, v124
	v_fmac_f32_e32 v125, v116, v116
	v_fmac_f32_e32 v197, v126, v126
	v_fmac_f32_e32 v125, v118, v118
	v_pk_add_f32 v[120:121], v[120:121], v[212:213]
	v_fmac_f32_e32 v197, v127, v127
	v_fmac_f32_e32 v125, v119, v119
	v_lshlrev_b32_e32 v204, 16, v205
	v_and_b32_e32 v205, 0xffff0000, v205
	v_fmac_f32_e32 v197, v120, v120
	v_fmac_f32_e32 v125, v200, v200
	v_pk_add_f32 v[198:199], v[114:115], v[204:205]
	v_fmac_f32_e32 v197, v121, v121
	v_fmac_f32_e32 v125, v201, v201
	v_fmac_f32_e32 v197, v122, v122
	v_fmac_f32_e32 v125, v198, v198
	v_fmac_f32_e32 v197, v123, v123
	v_fmac_f32_e32 v125, v199, v199
	v_cvt_pk_bf16_f32 v115, v122, v123
	v_add_f32_e32 v122, v197, v125
	ds_bpermute_b32 v123, v196, v122
	v_cvt_pk_bf16_f32 v114, v120, v121
	v_lshl_add_u64 v[120:121], s[76:77], 0, v[208:209]
	v_cvt_pk_bf16_f32 v113, v126, v127
	v_lshl_add_u64 v[120:121], v[120:121], 0, v[206:207]
	global_store_dwordx4 v[120:121], v[112:115], off
	s_waitcnt lgkmcnt(0)
	s_nop 0
	v_add_f32_e32 v112, v122, v123
	ds_bpermute_b32 v113, v195, v112
	v_cvt_pk_bf16_f32 v114, v116, v117
	v_cvt_pk_bf16_f32 v115, v118, v119
	v_cvt_pk_bf16_f32 v116, v200, v201
	v_cvt_pk_bf16_f32 v117, v198, v199
	global_store_dwordx4 v[120:121], v[114:117], off offset:256
	s_and_saveexec_b64 s[4:5], s[0:1]
	s_cbranch_execz .LBB0_687
	s_waitcnt lgkmcnt(0)
	v_add_f32_e32 v114, v112, v113
	s_lshl_b32 s22, s10, 2
	v_lshlrev_b64 v[112:113], 6, v[172:173]
	s_ashr_i32 s23, s22, 31
	v_lshl_add_u64 v[112:113], s[6:7], 0, v[112:113]
	v_lshl_add_u64 v[112:113], s[22:23], 2, v[112:113]
	s_lshl_b32 s12, s37, 2
	v_lshl_add_u64 v[112:113], v[112:113], 0, s[12:13]
	global_store_dword v[112:113], v114, off

; #define PG8_STAGE(bufoff, gbase, voff) do { _Pragma("unroll") for (int _i = 0; _i < 2; ++_i) \
;         __builtin_amdgcn_global_load_lds((const unsigned*)((const char*)(gbase) + (voff)[_i]), (LAS unsigned*)(lds + (bufoff) + ldsw + _i * 8192), 16, 0, 0); } while (0)
; #define PG8_LDA(dst, b, h) do { _Pragma("unroll") for (int m = 0; m < 4; ++m) _Pragma("unroll") for (int k = 0; k < 2; ++k) dst[m][k] = *(const LAS bf16x8*)(lds + PG8_SA(b, h) + aoff + m * 2048 + k * 1024); } while (0)
; #define PG8_LDB(dst, b, h) do { _Pragma("unroll") for (int n = 0; n < 2; ++n) _Pragma("unroll") for (int k = 0; k < 2; ++k) dst[n][k] = *(const LAS bf16x8*)(lds + PG8_SB(b, h) + boff + n * 2048 + k * 1024); } while (0)
; #define PG8_MMA(ai, bj, At, Bt) do { __builtin_amdgcn_s_setprio(1); _Pragma("unroll") for (int m = 0; m < 4; ++m) _Pragma("unroll") for (int n = 0; n < 2; ++n) _Pragma("unroll") for (int k = 0; k < 2; ++k) \
;         acc[ai][bj][m][n] = __builtin_amdgcn_mfma_f32_16x16x32_bf16(Bt[n][k], At[m][k], acc[ai][bj][m][n], 0, 0, 0); __builtin_amdgcn_s_setprio(0); } while (0)
; #define PG8_WAIT_V(n) asm volatile("s_waitcnt vmcnt(" #n ")" ::: "memory")
; #define PG8_BAR __builtin_amdgcn_s_barrier()
; template <class Epi>
; __device__ __forceinline__ void gemm_phase(LAS unsigned char* lds, const Gemm g, const StaticOrder& S, const Epi& E) {
;     ...
;         for (int t = 0; t < nt; t += 2) {
;             const bool last = (t == nt - 2);
;             const char* a1 = cA + (size_t)(t + 1) * kstep;
;             const char* a2 = last ? nA : cA + (size_t)(t + 2) * kstep; const char* b2 = last ? nB : cB + (size_t)(t + 2) * kstep;
;             const char* a3 = a2 + kstep; const char* b3 = b2 + kstep;
;             if (last) E.pre(cur, wr, fr, epre);
;             PG8_LDB(B0, 0, 0); PG8_SCHED; PG8_LDA(At, 0, 0); PG8_STAGE(PG8_SA(1, 1), a1 + hstepA, voffA);
;             PG8_WAIT_L(8); PG8_BAR; PG8_WAIT_L(0); PG8_MMA(0, 0, At, B0); PG8_BAR; PG8_SCHED;
;             PG8_LDB(B1, 0, 1); PG8_STAGE(PG8_SB(0, 0), b2, voffB);
;             PG8_BAR; PG8_WAIT_L(0); PG8_MMA(0, 1, At, B1); PG8_BAR;
;             PG8_LDA(At, 0, 1); PG8_STAGE(PG8_SA(0, 0), a2, voffA);
;             PG8_BAR; PG8_WAIT_L(0); PG8_MMA(1, 0, At, B0); PG8_BAR; PG8_SCHED;
;             PG8_STAGE(PG8_SB(0, 1), b2 + hstepB, voffB);
;             PG8_WAIT_V(6); PG8_BAR; PG8_MMA(1, 1, At, B1); PG8_BAR;
.LBB0_770:
	ds_read_b128 v[146:149], v177
	ds_read_b128 v[154:157], v177 offset:1024
	ds_read_b128 v[158:161], v177 offset:2048
	ds_read_b128 v[162:165], v177 offset:3072
	s_add_u32 s22, s20, 0xfffc0080
	s_addc_u32 s23, s21, -1
	s_cmp_eq_u32 s45, 12
	s_cselect_b32 s25, s13, s23
	s_cselect_b32 s24, s41, s22
	s_cselect_b32 s23, s11, s44
	s_cselect_b32 s22, s42, s43
	v_lshl_add_u64 v[150:151], s[20:21], 0, v[138:139]
	s_add_i32 m0, s19, 0xc000
	ds_read_b128 v[166:169], v178
	ds_read_b128 v[170:173], v178 offset:1024
	ds_read_b128 v[182:185], v178 offset:2048
	ds_read_b128 v[186:189], v178 offset:3072
	ds_read_b128 v[190:193], v178 offset:4096
	ds_read_b128 v[194:197], v178 offset:5120
	ds_read_b128 v[198:201], v178 offset:6144
	ds_read_b128 v[202:205], v178 offset:7168
	global_load_lds_dwordx4 v[150:151], off
	v_lshl_add_u64 v[150:151], s[20:21], 0, v[140:141]
	s_add_i32 m0, s19, 0xe000
	s_nop 0
	global_load_lds_dwordx4 v[150:151], off
	s_waitcnt lgkmcnt(8)
	s_barrier
	s_waitcnt lgkmcnt(0)
	v_mfma_f32_16x16x32_bf16 v[124:127], v[146:149], v[166:169], v[124:127]
	v_mfma_f32_16x16x32_bf16 v[120:123], v[158:161], v[166:169], v[120:123]
	v_mfma_f32_16x16x32_bf16 v[108:111], v[146:149], v[182:185], v[108:111]
	v_mfma_f32_16x16x32_bf16 v[104:107], v[158:161], v[182:185], v[104:107]
	v_mfma_f32_16x16x32_bf16 v[92:95], v[146:149], v[190:193], v[92:95]
	v_mfma_f32_16x16x32_bf16 v[88:91], v[158:161], v[190:193], v[88:91]
	v_mfma_f32_16x16x32_bf16 v[76:79], v[146:149], v[198:201], v[76:79]
	v_mfma_f32_16x16x32_bf16 v[72:75], v[158:161], v[198:201], v[72:75]
	v_mfma_f32_16x16x32_bf16 v[124:127], v[154:157], v[170:173], v[124:127]
	v_mfma_f32_16x16x32_bf16 v[120:123], v[162:165], v[170:173], v[120:123]
	v_mfma_f32_16x16x32_bf16 v[108:111], v[154:157], v[186:189], v[108:111]
	v_mfma_f32_16x16x32_bf16 v[104:107], v[162:165], v[186:189], v[104:107]
	v_mfma_f32_16x16x32_bf16 v[92:95], v[154:157], v[194:197], v[92:95]
	v_mfma_f32_16x16x32_bf16 v[88:91], v[162:165], v[194:197], v[88:91]
	v_mfma_f32_16x16x32_bf16 v[76:79], v[154:157], v[202:205], v[76:79]
	v_mfma_f32_16x16x32_bf16 v[72:75], v[162:165], v[202:205], v[72:75]
	s_barrier
	s_add_i32 s46, s7, s29
	v_lshl_add_u64 v[150:151], s[22:23], 0, v[130:131]
	s_mov_b32 m0, s46
	ds_read_b128 v[206:209], v179
	ds_read_b128 v[210:213], v179 offset:1024
	ds_read_b128 v[214:217], v179 offset:2048
	ds_read_b128 v[218:221], v179 offset:3072
	global_load_lds_dwordx4 v[150:151], off
	v_lshl_add_u64 v[222:223], s[22:23], 0, v[134:135]
	s_add_i32 m0, s46, 0x2000
	s_nop 0
	global_load_lds_dwordx4 v[222:223], off
	s_barrier
	s_waitcnt lgkmcnt(0)
	v_mfma_f32_16x16x32_bf16 v[116:119], v[206:209], v[166:169], v[116:119]
	v_mfma_f32_16x16x32_bf16 v[112:115], v[214:217], v[166:169], v[112:115]
	v_mfma_f32_16x16x32_bf16 v[100:103], v[206:209], v[182:185], v[100:103]
	v_mfma_f32_16x16x32_bf16 v[96:99], v[214:217], v[182:185], v[96:99]
	v_mfma_f32_16x16x32_bf16 v[84:87], v[206:209], v[190:193], v[84:87]
	v_mfma_f32_16x16x32_bf16 v[80:83], v[214:217], v[190:193], v[80:83]
	v_mfma_f32_16x16x32_bf16 v[68:71], v[206:209], v[198:201], v[68:71]
	v_mfma_f32_16x16x32_bf16 v[64:67], v[214:217], v[198:201], v[64:67]
	v_mfma_f32_16x16x32_bf16 v[116:119], v[210:213], v[170:173], v[116:119]
	v_mfma_f32_16x16x32_bf16 v[112:115], v[218:221], v[170:173], v[112:115]
	v_mfma_f32_16x16x32_bf16 v[100:103], v[210:213], v[186:189], v[100:103]
	v_mfma_f32_16x16x32_bf16 v[96:99], v[218:221], v[186:189], v[96:99]
	v_mfma_f32_16x16x32_bf16 v[84:87], v[210:213], v[194:197], v[84:87]
	v_mfma_f32_16x16x32_bf16 v[80:83], v[218:221], v[194:197], v[80:83]
	v_mfma_f32_16x16x32_bf16 v[68:71], v[210:213], v[202:205], v[68:71]
	v_mfma_f32_16x16x32_bf16 v[64:67], v[218:221], v[202:205], v[64:67]
	s_mov_b32 m0, s19
	v_lshl_add_u64 v[224:225], s[24:25], 0, v[128:129]
	s_barrier
	ds_read_b128 v[166:169], v178 offset:16384
	ds_read_b128 v[170:173], v178 offset:17408
	ds_read_b128 v[182:185], v178 offset:18432
	ds_read_b128 v[186:189], v178 offset:19456
	ds_read_b128 v[190:193], v178 offset:20480
	ds_read_b128 v[194:197], v178 offset:21504
	ds_read_b128 v[198:201], v178 offset:22528
	ds_read_b128 v[202:205], v178 offset:23552
	global_load_lds_dwordx4 v[224:225], off
	v_lshl_add_u64 v[226:227], s[24:25], 0, v[132:133]
	s_mov_b32 m0, s30
	s_nop 0
	global_load_lds_dwordx4 v[226:227], off
	s_barrier
	s_waitcnt lgkmcnt(0)
	v_mfma_f32_16x16x32_bf16 v[60:63], v[146:149], v[166:169], v[60:63]
	v_mfma_f32_16x16x32_bf16 v[56:59], v[158:161], v[166:169], v[56:59]
	v_mfma_f32_16x16x32_bf16 v[44:47], v[146:149], v[182:185], v[44:47]
	v_mfma_f32_16x16x32_bf16 v[40:43], v[158:161], v[182:185], v[40:43]
	v_mfma_f32_16x16x32_bf16 v[28:31], v[146:149], v[190:193], v[28:31]
	v_mfma_f32_16x16x32_bf16 v[24:27], v[158:161], v[190:193], v[24:27]
	v_mfma_f32_16x16x32_bf16 v[12:15], v[146:149], v[198:201], v[12:15]
	v_mfma_f32_16x16x32_bf16 v[8:11], v[158:161], v[198:201], v[8:11]
	v_mfma_f32_16x16x32_bf16 v[60:63], v[154:157], v[170:173], v[60:63]
	v_mfma_f32_16x16x32_bf16 v[56:59], v[162:165], v[170:173], v[56:59]
	v_mfma_f32_16x16x32_bf16 v[44:47], v[154:157], v[186:189], v[44:47]
	v_mfma_f32_16x16x32_bf16 v[40:43], v[162:165], v[186:189], v[40:43]
	v_mfma_f32_16x16x32_bf16 v[28:31], v[154:157], v[194:197], v[28:31]
	v_mfma_f32_16x16x32_bf16 v[24:27], v[162:165], v[194:197], v[24:27]
	v_mfma_f32_16x16x32_bf16 v[12:15], v[154:157], v[202:205], v[12:15]
	v_mfma_f32_16x16x32_bf16 v[8:11], v[162:165], v[202:205], v[8:11]
	s_barrier
; #define PG8_STAGE(bufoff, gbase, voff) do { _Pragma("unroll") for (int _i = 0; _i < 2; ++_i) \
;         __builtin_amdgcn_global_load_lds((const unsigned*)((const char*)(gbase) + (voff)[_i]), (LAS unsigned*)(lds + (bufoff) + ldsw + _i * 8192), 16, 0, 0); } while (0)
; #define PG8_LDA(dst, b, h) do { _Pragma("unroll") for (int m = 0; m < 4; ++m) _Pragma("unroll") for (int k = 0; k < 2; ++k) dst[m][k] = *(const LAS bf16x8*)(lds + PG8_SA(b, h) + aoff + m * 2048 + k * 1024); } while (0)
; #define PG8_LDB(dst, b, h) do { _Pragma("unroll") for (int n = 0; n < 2; ++n) _Pragma("unroll") for (int k = 0; k < 2; ++k) dst[n][k] = *(const LAS bf16x8*)(lds + PG8_SB(b, h) + boff + n * 2048 + k * 1024); } while (0)
; #define PG8_MMA(ai, bj, At, Bt) do { __builtin_amdgcn_s_setprio(1); _Pragma("unroll") for (int m = 0; m < 4; ++m) _Pragma("unroll") for (int n = 0; n < 2; ++n) _Pragma("unroll") for (int k = 0; k < 2; ++k) \
;         acc[ai][bj][m][n] = __builtin_amdgcn_mfma_f32_16x16x32_bf16(Bt[n][k], At[m][k], acc[ai][bj][m][n], 0, 0, 0); __builtin_amdgcn_s_setprio(0); } while (0)
; #define PG8_WAIT_V(n) asm volatile("s_waitcnt vmcnt(" #n ")" ::: "memory")
; #define PG8_WAIT_L(n) asm volatile("s_waitcnt lgkmcnt(" #n ")" ::: "memory")
; #define PG8_BAR __builtin_amdgcn_s_barrier()
; #define PG8_SCHED __builtin_amdgcn_sched_barrier(0)
; template <class Epi>
; __device__ __forceinline__ void gemm_phase(LAS unsigned char* lds, const Gemm g, const StaticOrder& S, const Epi& E) {
;     ...
;             PG8_WAIT_V(6); PG8_BAR; PG8_MMA(1, 1, At, B1); PG8_BAR;
;             PG8_LDB(B0, 1, 0); PG8_SCHED; PG8_LDA(At, 1, 0); PG8_STAGE(PG8_SA(0, 1), a2 + hstepA, voffA);
;             PG8_WAIT_L(8); PG8_BAR; PG8_WAIT_L(0); PG8_MMA(0, 0, At, B0); PG8_BAR; PG8_SCHED;
;             PG8_LDB(B1, 1, 1); PG8_STAGE(PG8_SB(1, 0), b3, voffB);
;             PG8_BAR; PG8_WAIT_L(0); PG8_MMA(0, 1, At, B1); PG8_BAR;
;             PG8_LDA(At, 1, 1); PG8_STAGE(PG8_SA(1, 0), a3, voffA);
;             PG8_BAR; PG8_WAIT_L(0); PG8_MMA(1, 0, At, B0); PG8_BAR; PG8_SCHED;
	s_add_u32 s46, s22, 0x40000
	s_addc_u32 s47, s23, 0
	s_add_i32 s48, s38, s29
	v_lshl_add_u64 v[146:147], s[46:47], 0, v[130:131]
	s_mov_b32 m0, s48
	s_nop 0
	global_load_lds_dwordx4 v[146:147], off
	v_lshl_add_u64 v[146:147], s[46:47], 0, v[134:135]
	s_add_i32 m0, s48, 0x2000
	s_nop 0
	global_load_lds_dwordx4 v[146:147], off
	s_waitcnt vmcnt(6)
	s_barrier
	v_mfma_f32_16x16x32_bf16 v[52:55], v[206:209], v[166:169], v[52:55]
	v_mfma_f32_16x16x32_bf16 v[48:51], v[214:217], v[166:169], v[48:51]
	v_mfma_f32_16x16x32_bf16 v[36:39], v[206:209], v[182:185], v[36:39]
	v_mfma_f32_16x16x32_bf16 v[32:35], v[214:217], v[182:185], v[32:35]
	v_mfma_f32_16x16x32_bf16 v[20:23], v[206:209], v[190:193], v[20:23]
	v_mfma_f32_16x16x32_bf16 v[16:19], v[214:217], v[190:193], v[16:19]
	v_mfma_f32_16x16x32_bf16 v[4:7], v[206:209], v[198:201], v[4:7]
	v_mfma_f32_16x16x32_bf16 v[0:3], v[214:217], v[198:201], v[0:3]
	v_mfma_f32_16x16x32_bf16 v[52:55], v[210:213], v[170:173], v[52:55]
	v_mfma_f32_16x16x32_bf16 v[48:51], v[218:221], v[170:173], v[48:51]
	v_mfma_f32_16x16x32_bf16 v[36:39], v[210:213], v[186:189], v[36:39]
	v_mfma_f32_16x16x32_bf16 v[32:35], v[218:221], v[186:189], v[32:35]
	v_mfma_f32_16x16x32_bf16 v[20:23], v[210:213], v[194:197], v[20:23]
	v_mfma_f32_16x16x32_bf16 v[16:19], v[218:221], v[194:197], v[16:19]
	v_mfma_f32_16x16x32_bf16 v[4:7], v[210:213], v[202:205], v[4:7]
	v_mfma_f32_16x16x32_bf16 v[0:3], v[218:221], v[202:205], v[0:3]
	s_add_i32 s46, 0, 0x18000
	v_add_u32_e32 v162, s46, v175
	s_barrier
	ds_read_b128 v[146:149], v162
	ds_read_b128 v[154:157], v162 offset:1024
	ds_read_b128 v[158:161], v162 offset:2048
	ds_read_b128 v[162:165], v162 offset:3072
	s_add_u32 s24, s24, 0x40000
	s_addc_u32 s25, s25, 0
	s_mov_b32 m0, s31
	v_lshl_add_u64 v[206:207], s[24:25], 0, v[128:129]
	ds_read_b128 v[166:169], v178 offset:32768
	ds_read_b128 v[170:173], v178 offset:33792
	ds_read_b128 v[182:185], v178 offset:34816
	ds_read_b128 v[186:189], v178 offset:35840
	ds_read_b128 v[190:193], v178 offset:36864
	ds_read_b128 v[194:197], v178 offset:37888
	ds_read_b128 v[198:201], v178 offset:38912
	ds_read_b128 v[202:205], v178 offset:39936
	global_load_lds_dwordx4 v[206:207], off
	v_lshl_add_u64 v[206:207], s[24:25], 0, v[132:133]
	s_mov_b32 m0, s33
	s_nop 0
	global_load_lds_dwordx4 v[206:207], off
	s_waitcnt lgkmcnt(8)
	s_barrier
	s_waitcnt lgkmcnt(0)
	v_mfma_f32_16x16x32_bf16 v[124:127], v[146:149], v[166:169], v[124:127]
	v_mfma_f32_16x16x32_bf16 v[120:123], v[158:161], v[166:169], v[120:123]
	v_mfma_f32_16x16x32_bf16 v[108:111], v[146:149], v[182:185], v[108:111]
	v_mfma_f32_16x16x32_bf16 v[104:107], v[158:161], v[182:185], v[104:107]
	v_mfma_f32_16x16x32_bf16 v[92:95], v[146:149], v[190:193], v[92:95]
	v_mfma_f32_16x16x32_bf16 v[88:91], v[158:161], v[190:193], v[88:91]
	v_mfma_f32_16x16x32_bf16 v[76:79], v[146:149], v[198:201], v[76:79]
	v_mfma_f32_16x16x32_bf16 v[72:75], v[158:161], v[198:201], v[72:75]
	v_mfma_f32_16x16x32_bf16 v[124:127], v[154:157], v[170:173], v[124:127]
	v_mfma_f32_16x16x32_bf16 v[120:123], v[162:165], v[170:173], v[120:123]
	v_mfma_f32_16x16x32_bf16 v[108:111], v[154:157], v[186:189], v[108:111]
	v_mfma_f32_16x16x32_bf16 v[104:107], v[162:165], v[186:189], v[104:107]
	v_mfma_f32_16x16x32_bf16 v[92:95], v[154:157], v[194:197], v[92:95]
	v_mfma_f32_16x16x32_bf16 v[88:91], v[162:165], v[194:197], v[88:91]
	v_mfma_f32_16x16x32_bf16 v[76:79], v[154:157], v[202:205], v[76:79]
	v_mfma_f32_16x16x32_bf16 v[72:75], v[162:165], v[202:205], v[72:75]
	s_barrier
	s_add_i32 s24, 0, 0x1c000
	s_add_i32 s25, s46, s29
	v_add_u32_e32 v181, s24, v175
	v_lshl_add_u64 v[150:151], v[150:151], 0, s[4:5]
	s_mov_b32 m0, s25
	ds_read_b128 v[206:209], v181
	ds_read_b128 v[210:213], v181 offset:1024
	ds_read_b128 v[214:217], v181 offset:2048
	ds_read_b128 v[218:221], v181 offset:3072
	global_load_lds_dwordx4 v[150:151], off
	v_lshl_add_u64 v[150:151], v[222:223], 0, s[4:5]
	s_add_i32 m0, s25, 0x2000
	s_nop 0
	global_load_lds_dwordx4 v[150:151], off
	s_barrier
	s_waitcnt lgkmcnt(0)
	v_mfma_f32_16x16x32_bf16 v[116:119], v[206:209], v[166:169], v[116:119]
	v_mfma_f32_16x16x32_bf16 v[112:115], v[214:217], v[166:169], v[112:115]
	v_mfma_f32_16x16x32_bf16 v[100:103], v[206:209], v[182:185], v[100:103]
	v_mfma_f32_16x16x32_bf16 v[96:99], v[214:217], v[182:185], v[96:99]
	v_mfma_f32_16x16x32_bf16 v[84:87], v[206:209], v[190:193], v[84:87]
	v_mfma_f32_16x16x32_bf16 v[80:83], v[214:217], v[190:193], v[80:83]
	v_mfma_f32_16x16x32_bf16 v[68:71], v[206:209], v[198:201], v[68:71]
	v_mfma_f32_16x16x32_bf16 v[64:67], v[214:217], v[198:201], v[64:67]
	v_mfma_f32_16x16x32_bf16 v[116:119], v[210:213], v[170:173], v[116:119]
	v_mfma_f32_16x16x32_bf16 v[112:115], v[218:221], v[170:173], v[112:115]
	v_mfma_f32_16x16x32_bf16 v[100:103], v[210:213], v[186:189], v[100:103]
	v_mfma_f32_16x16x32_bf16 v[96:99], v[218:221], v[186:189], v[96:99]
	v_mfma_f32_16x16x32_bf16 v[84:87], v[210:213], v[194:197], v[84:87]
	v_mfma_f32_16x16x32_bf16 v[80:83], v[218:221], v[194:197], v[80:83]
	v_mfma_f32_16x16x32_bf16 v[68:71], v[210:213], v[202:205], v[68:71]
	v_mfma_f32_16x16x32_bf16 v[64:67], v[218:221], v[202:205], v[64:67]
	s_mov_b32 m0, s35
	v_lshl_add_u64 v[150:151], v[224:225], 0, s[4:5]
	s_barrier
	ds_read_b128 v[166:169], v178 offset:49152
	ds_read_b128 v[170:173], v178 offset:50176
	ds_read_b128 v[182:185], v178 offset:51200
	ds_read_b128 v[186:189], v178 offset:52224
	ds_read_b128 v[190:193], v178 offset:53248
	ds_read_b128 v[194:197], v178 offset:54272
	ds_read_b128 v[198:201], v178 offset:55296
	ds_read_b128 v[202:205], v178 offset:56320
	global_load_lds_dwordx4 v[150:151], off
	v_lshl_add_u64 v[150:151], v[226:227], 0, s[4:5]
	s_mov_b32 m0, s36
	s_nop 0
	global_load_lds_dwordx4 v[150:151], off
	s_barrier
; __device__ __forceinline__ unsigned pk2(float lo, float hi) { const f32x2 v = (f32x2){lo, hi}; const bf16x2_t b = __builtin_convertvector(v, bf16x2_t); return __builtin_bit_cast(unsigned, b); }
; #define PG8_STAGE(bufoff, gbase, voff) do { _Pragma("unroll") for (int _i = 0; _i < 2; ++_i) \
;         __builtin_amdgcn_global_load_lds((const unsigned*)((const char*)(gbase) + (voff)[_i]), (LAS unsigned*)(lds + (bufoff) + ldsw + _i * 8192), 16, 0, 0); } while (0)
; #define PG8_LDA(dst, b, h) do { _Pragma("unroll") for (int m = 0; m < 4; ++m) _Pragma("unroll") for (int k = 0; k < 2; ++k) dst[m][k] = *(const LAS bf16x8*)(lds + PG8_SA(b, h) + aoff + m * 2048 + k * 1024); } while (0)
; #define PG8_WAIT_V(n) asm volatile("s_waitcnt vmcnt(" #n ")" ::: "memory")
; #define PG8_WAIT_L(n) asm volatile("s_waitcnt lgkmcnt(" #n ")" ::: "memory")
; #define PG8_BAR __builtin_amdgcn_s_barrier()
; #define PG8_SCHED __builtin_amdgcn_sched_barrier(0)
;     __device__ __forceinline__ void operator()(const f32x4 (&acc)[2][2][4][2], const Unit& u, int wr, int wc, int fr, int fq, const float (&)[8]) const {
;     ...
;         const int col0 = u.pn * BM + wc * 32 + 8 * fq;
; #pragma unroll
;         for (int ai = 0; ai < 2; ++ai)
; #pragma unroll
;             for (int m = 0; m < 4; ++m) { const int row = row0 + ai * HALF + m * 16; const float rs = rsqrtf(ep[ai * 4 + m] * (1.0f / 1024.0f) + EPS);
;                 u16* rowp = O + (size_t)row * ldc + col0;
; #pragma unroll
;                 for (int bj = 0; bj < 2; ++bj) { f32x4 v0 = acc[ai][bj][m][0] * rs, v1 = acc[ai][bj][m][1] * rs;
;                     if (ACT == 1) {
; #pragma unroll
;                         for (int j = 0; j < 4; ++j) { const float a0 = fmaxf(v0[j], 0.f), a1 = fmaxf(v1[j], 0.f); v0[j] = a0 * a0; v1[j] = a1 * a1; } }
;                     u32x4 w; w.x = pk2(v0[0], v0[1]); w.y = pk2(v0[2], v0[3]); w.z = pk2(v1[0], v1[1]); w.w = pk2(v1[2], v1[3]);
;                     *(u32x4*)(rowp + bj * HALF) = w; } }
; template <class Epi>
; __device__ __forceinline__ void gemm_phase(LAS unsigned char* lds, const Gemm g, const StaticOrder& S, const Epi& E) {
;     ...
;             PG8_LDA(At, 1, 1); PG8_STAGE(PG8_SA(1, 0), a3, voffA);
;             PG8_BAR; PG8_WAIT_L(0); PG8_MMA(1, 0, At, B0); PG8_BAR; PG8_SCHED;
;             PG8_STAGE(PG8_SB(1, 1), b3 + hstepB, voffB);
;             PG8_WAIT_V(6); PG8_BAR; PG8_MMA(1, 1, At, B1); PG8_BAR;
	s_waitcnt lgkmcnt(0)
	v_mfma_f32_16x16x32_bf16 v[60:63], v[146:149], v[166:169], v[60:63]
	v_mfma_f32_16x16x32_bf16 v[56:59], v[158:161], v[166:169], v[56:59]
	v_mfma_f32_16x16x32_bf16 v[44:47], v[146:149], v[182:185], v[44:47]
	v_mfma_f32_16x16x32_bf16 v[40:43], v[158:161], v[182:185], v[40:43]
	v_mfma_f32_16x16x32_bf16 v[28:31], v[146:149], v[190:193], v[28:31]
	v_mfma_f32_16x16x32_bf16 v[24:27], v[158:161], v[190:193], v[24:27]
	v_mfma_f32_16x16x32_bf16 v[12:15], v[146:149], v[198:201], v[12:15]
	v_mfma_f32_16x16x32_bf16 v[8:11], v[158:161], v[198:201], v[8:11]
	v_mfma_f32_16x16x32_bf16 v[60:63], v[154:157], v[170:173], v[60:63]
	v_mfma_f32_16x16x32_bf16 v[56:59], v[162:165], v[170:173], v[56:59]
	v_mfma_f32_16x16x32_bf16 v[44:47], v[154:157], v[186:189], v[44:47]
	v_mfma_f32_16x16x32_bf16 v[40:43], v[162:165], v[186:189], v[40:43]
	v_mfma_f32_16x16x32_bf16 v[28:31], v[154:157], v[194:197], v[28:31]
	v_mfma_f32_16x16x32_bf16 v[24:27], v[162:165], v[194:197], v[24:27]
	v_mfma_f32_16x16x32_bf16 v[12:15], v[154:157], v[202:205], v[12:15]
	v_mfma_f32_16x16x32_bf16 v[8:11], v[162:165], v[202:205], v[8:11]
	s_barrier
	s_add_u32 s22, s22, 0x40080
	s_addc_u32 s23, s23, 0
	s_add_i32 s24, s24, s29
	v_lshl_add_u64 v[146:147], s[22:23], 0, v[130:131]
	s_mov_b32 m0, s24
	s_nop 0
	global_load_lds_dwordx4 v[146:147], off
	v_lshl_add_u64 v[146:147], s[22:23], 0, v[134:135]
	s_add_i32 m0, s24, 0x2000
	s_nop 0
	global_load_lds_dwordx4 v[146:147], off
	s_waitcnt vmcnt(6)
	s_barrier
	v_mfma_f32_16x16x32_bf16 v[52:55], v[206:209], v[166:169], v[52:55]
	v_mfma_f32_16x16x32_bf16 v[48:51], v[214:217], v[166:169], v[48:51]
	v_mfma_f32_16x16x32_bf16 v[36:39], v[206:209], v[182:185], v[36:39]
	v_mfma_f32_16x16x32_bf16 v[32:35], v[214:217], v[182:185], v[32:35]
	v_mfma_f32_16x16x32_bf16 v[20:23], v[206:209], v[190:193], v[20:23]
	v_mfma_f32_16x16x32_bf16 v[16:19], v[214:217], v[190:193], v[16:19]
	v_mfma_f32_16x16x32_bf16 v[4:7], v[206:209], v[198:201], v[4:7]
	v_mfma_f32_16x16x32_bf16 v[0:3], v[214:217], v[198:201], v[0:3]
	v_mfma_f32_16x16x32_bf16 v[52:55], v[210:213], v[170:173], v[52:55]
	v_mfma_f32_16x16x32_bf16 v[48:51], v[218:221], v[170:173], v[48:51]
	v_mfma_f32_16x16x32_bf16 v[36:39], v[210:213], v[186:189], v[36:39]
	v_mfma_f32_16x16x32_bf16 v[32:35], v[218:221], v[186:189], v[32:35]
	v_mfma_f32_16x16x32_bf16 v[20:23], v[210:213], v[194:197], v[20:23]
	v_mfma_f32_16x16x32_bf16 v[16:19], v[218:221], v[194:197], v[16:19]
	v_mfma_f32_16x16x32_bf16 v[4:7], v[210:213], v[202:205], v[4:7]
	v_mfma_f32_16x16x32_bf16 v[0:3], v[218:221], v[202:205], v[0:3]
	s_add_i32 s45, s45, 2
	s_add_u32 s20, s20, 0x100
	s_addc_u32 s21, s21, 0
	s_add_u32 s43, s43, 0x100
	s_addc_u32 s44, s44, 0
	s_cmp_gt_u32 s45, 13
	s_barrier
	s_cbranch_scc0 .LBB0_770
	s_setprio 0
	s_bfe_u32 vcc_lo, s18, 0x20003
	s_lshl_b32 vcc_lo, vcc_lo, 10
	s_add_i32 vcc_lo, vcc_lo, 0x20010
	v_lshl_add_u32 v236, v174, 2, vcc_lo
	ds_read_b32 v228, v236
	ds_read_b32 v229, v236 offset:64
	ds_read_b32 v230, v236 offset:128
	ds_read_b32 v231, v236 offset:192
	ds_read_b32 v232, v236 offset:512
	ds_read_b32 v233, v236 offset:576
	ds_read_b32 v234, v236 offset:640
	ds_read_b32 v235, v236 offset:704
	s_waitcnt lgkmcnt(0)
	v_lshl_add_u32 v148, s18, 8, v174
	v_ashrrev_i32_e32 v149, 31, v148
	v_or_b32_e32 v172, 16, v148
	v_ashrrev_i32_e32 v173, 31, v172
	v_or_b32_e32 v168, 32, v148
	v_or_b32_e32 v164, 48, v148
	v_ashrrev_i32_e32 v169, 31, v168
	v_ashrrev_i32_e32 v165, 31, v164
	v_add_u32_e32 v162, 0x80, v148
	v_add_u32_e32 v156, 0x90, v148
	v_ashrrev_i32_e32 v163, 31, v162
	v_ashrrev_i32_e32 v157, 31, v156
	v_add_u32_e32 v150, 0xa0, v148
	v_ashrrev_i32_e32 v151, 31, v150
	v_add_u32_e32 v146, 0xb0, v148
	v_ashrrev_i32_e32 v147, 31, v146
	v_lshl_or_b32 v166, s40, 8, v176
	v_ashrrev_i32_e32 v167, 31, v166
	v_lshlrev_b64 v[170:171], 13, v[148:149]
	v_lshlrev_b64 v[148:149], 1, v[166:167]
	v_lshl_add_u64 v[166:167], s[96:97], 0, v[170:171]
	v_lshl_add_u64 v[212:213], v[166:167], 0, v[148:149]
	s_mov_b32 s40, s10
	s_mov_b32 s18, s12
	s_mov_b64 s[22:23], s[16:17]
	s_mov_b64 s[20:21], s[14:15]
	s_waitcnt vmcnt(8)
	s_waitcnt lgkmcnt(0)
	s_waitcnt lgkmcnt(0)
	v_mov_b32_e32 v184, v228
	v_pk_mul_f32 v[120:121], v[120:121], v[184:185] op_sel_hi:[1,0]
	v_pk_mul_f32 v[126:127], v[126:127], v[184:185] op_sel_hi:[1,0]
	v_pk_mul_f32 v[124:125], v[124:125], v[184:185] op_sel_hi:[1,0]
	v_pk_mul_f32 v[122:123], v[122:123], v[184:185] op_sel_hi:[1,0]
	v_max_f32_e32 v120, 0, v120
	v_max_f32_e32 v121, 0, v121
	v_max_f32_e32 v124, 0, v124
	v_max_f32_e32 v125, 0, v125
	v_pk_mul_f32 v[190:191], v[120:121], v[120:121]
	v_max_f32_e32 v120, 0, v126
	v_max_f32_e32 v122, 0, v122
	v_max_f32_e32 v121, 0, v127
	v_max_f32_e32 v123, 0, v123
	v_pk_mul_f32 v[124:125], v[124:125], v[124:125]
	v_pk_mul_f32 v[126:127], v[120:121], v[120:121]
	v_pk_mul_f32 v[194:195], v[122:123], v[122:123]
	v_pk_mul_f32 v[114:115], v[114:115], v[184:185] op_sel_hi:[1,0]
	v_cvt_pk_bf16_f32 v120, v124, v125
	v_cvt_pk_bf16_f32 v121, v126, v127
	v_cvt_pk_bf16_f32 v122, v190, v191
	v_cvt_pk_bf16_f32 v123, v194, v195
	v_pk_mul_f32 v[116:117], v[116:117], v[184:185] op_sel_hi:[1,0]
	v_pk_mul_f32 v[112:113], v[112:113], v[184:185] op_sel_hi:[1,0]
	v_max_f32_e32 v114, 0, v114
	v_max_f32_e32 v115, 0, v115
	global_store_dwordx4 v[212:213], v[120:123], off
	v_pk_mul_f32 v[118:119], v[118:119], v[184:185] op_sel_hi:[1,0]
	v_max_f32_e32 v116, 0, v116
	v_max_f32_e32 v112, 0, v112
	v_max_f32_e32 v117, 0, v117
	v_max_f32_e32 v113, 0, v113
	v_pk_mul_f32 v[122:123], v[114:115], v[114:115]
	v_pk_mul_f32 v[116:117], v[116:117], v[116:117]
	v_pk_mul_f32 v[120:121], v[112:113], v[112:113]
; __device__ __forceinline__ unsigned pk2(float lo, float hi) { const f32x2 v = (f32x2){lo, hi}; const bf16x2_t b = __builtin_convertvector(v, bf16x2_t); return __builtin_bit_cast(unsigned, b); }
;     __device__ __forceinline__ void operator()(const f32x4 (&acc)[2][2][4][2], const Unit& u, int wr, int wc, int fr, int fq, const float (&)[8]) const {
;     ...
;             for (int m = 0; m < 4; ++m) { const int row = row0 + ai * HALF + m * 16; const float rs = rsqrtf(ep[ai * 4 + m] * (1.0f / 1024.0f) + EPS);
;                 u16* rowp = O + (size_t)row * ldc + col0;
; #pragma unroll
;                 for (int bj = 0; bj < 2; ++bj) { f32x4 v0 = acc[ai][bj][m][0] * rs, v1 = acc[ai][bj][m][1] * rs;
;                     if (ACT == 1) {
; #pragma unroll
;                         for (int j = 0; j < 4; ++j) { const float a0 = fmaxf(v0[j], 0.f), a1 = fmaxf(v1[j], 0.f); v0[j] = a0 * a0; v1[j] = a1 * a1; } }
;                     u32x4 w; w.x = pk2(v0[0], v0[1]); w.y = pk2(v0[2], v0[3]); w.z = pk2(v1[0], v1[1]); w.w = pk2(v1[2], v1[3]);
;                     *(u32x4*)(rowp + bj * HALF) = w; } }
	v_max_f32_e32 v112, 0, v118
	v_max_f32_e32 v113, 0, v119
	v_pk_mul_f32 v[118:119], v[112:113], v[112:113]
	v_cvt_pk_bf16_f32 v112, v116, v117
	v_cvt_pk_bf16_f32 v113, v118, v119
	v_cvt_pk_bf16_f32 v114, v120, v121
	v_cvt_pk_bf16_f32 v115, v122, v123
	global_store_dwordx4 v[212:213], v[112:115], off offset:256
	s_nop 1
	v_mov_b32_e32 v112, v229
	v_pk_mul_f32 v[104:105], v[104:105], v[112:113] op_sel_hi:[1,0]
	v_pk_mul_f32 v[110:111], v[110:111], v[112:113] op_sel_hi:[1,0]
	v_pk_mul_f32 v[108:109], v[108:109], v[112:113] op_sel_hi:[1,0]
	v_pk_mul_f32 v[106:107], v[106:107], v[112:113] op_sel_hi:[1,0]
	v_max_f32_e32 v104, 0, v104
	v_max_f32_e32 v105, 0, v105
	v_lshlrev_b64 v[114:115], 13, v[172:173]
	v_max_f32_e32 v108, 0, v108
	v_max_f32_e32 v109, 0, v109
	v_pk_mul_f32 v[116:117], v[104:105], v[104:105]
	v_max_f32_e32 v104, 0, v110
	v_max_f32_e32 v106, 0, v106
	v_max_f32_e32 v105, 0, v111
	v_max_f32_e32 v107, 0, v107
	v_lshl_add_u64 v[114:115], s[96:97], 0, v[114:115]
	v_pk_mul_f32 v[108:109], v[108:109], v[108:109]
	v_pk_mul_f32 v[110:111], v[104:105], v[104:105]
	v_pk_mul_f32 v[118:119], v[106:107], v[106:107]
	v_pk_mul_f32 v[96:97], v[96:97], v[112:113] op_sel_hi:[1,0]
	v_lshl_add_u64 v[114:115], v[114:115], 0, v[148:149]
	v_cvt_pk_bf16_f32 v104, v108, v109
	v_cvt_pk_bf16_f32 v105, v110, v111
	v_cvt_pk_bf16_f32 v106, v116, v117
	v_cvt_pk_bf16_f32 v107, v118, v119
	v_pk_mul_f32 v[102:103], v[102:103], v[112:113] op_sel_hi:[1,0]
	v_max_f32_e32 v96, 0, v96
	v_max_f32_e32 v97, 0, v97
	global_store_dwordx4 v[114:115], v[104:107], off
	v_pk_mul_f32 v[100:101], v[100:101], v[112:113] op_sel_hi:[1,0]
	v_pk_mul_f32 v[98:99], v[98:99], v[112:113] op_sel_hi:[1,0]
	v_pk_mul_f32 v[104:105], v[96:97], v[96:97]
	v_max_f32_e32 v96, 0, v102
	v_max_f32_e32 v97, 0, v103
	v_max_f32_e32 v100, 0, v100
	v_max_f32_e32 v101, 0, v101
	v_pk_mul_f32 v[100:101], v[100:101], v[100:101]
	v_pk_mul_f32 v[108:109], v[96:97], v[96:97]
	v_cvt_pk_bf16_f32 v96, v100, v101
	s_waitcnt lgkmcnt(0)
	v_max_f32_e32 v98, 0, v98
	v_max_f32_e32 v99, 0, v99
	v_pk_mul_f32 v[110:111], v[98:99], v[98:99]
	v_cvt_pk_bf16_f32 v97, v108, v109
	v_cvt_pk_bf16_f32 v98, v104, v105
	v_cvt_pk_bf16_f32 v99, v110, v111
	global_store_dwordx4 v[114:115], v[96:99], off offset:256
	s_waitcnt lgkmcnt(0)
	s_nop 0
	s_nop 0
	s_nop 0
	s_nop 1
	v_lshlrev_b64 v[98:99], 13, v[168:169]
	v_lshl_add_u64 v[98:99], s[96:97], 0, v[98:99]
	v_lshl_add_u64 v[98:99], v[98:99], 0, v[148:149]
	v_mov_b32_e32 v100, v230
	v_pk_mul_f32 v[88:89], v[88:89], v[100:101] op_sel_hi:[1,0]
	v_pk_mul_f32 v[94:95], v[94:95], v[100:101] op_sel_hi:[1,0]
	v_pk_mul_f32 v[92:93], v[92:93], v[100:101] op_sel_hi:[1,0]
	v_pk_mul_f32 v[90:91], v[90:91], v[100:101] op_sel_hi:[1,0]
	v_max_f32_e32 v88, 0, v88
	v_max_f32_e32 v89, 0, v89
	v_max_f32_e32 v92, 0, v92
	v_max_f32_e32 v93, 0, v93
	v_pk_mul_f32 v[102:103], v[88:89], v[88:89]
	v_max_f32_e32 v88, 0, v94
	v_max_f32_e32 v90, 0, v90
	v_max_f32_e32 v89, 0, v95
	v_max_f32_e32 v91, 0, v91
	v_pk_mul_f32 v[92:93], v[92:93], v[92:93]
	v_pk_mul_f32 v[94:95], v[88:89], v[88:89]
	v_pk_mul_f32 v[104:105], v[90:91], v[90:91]
	v_pk_mul_f32 v[82:83], v[82:83], v[100:101] op_sel_hi:[1,0]
	v_cvt_pk_bf16_f32 v88, v92, v93
	v_cvt_pk_bf16_f32 v89, v94, v95
	v_cvt_pk_bf16_f32 v90, v102, v103
	v_cvt_pk_bf16_f32 v91, v104, v105
	v_pk_mul_f32 v[84:85], v[84:85], v[100:101] op_sel_hi:[1,0]
	v_pk_mul_f32 v[80:81], v[80:81], v[100:101] op_sel_hi:[1,0]
	v_max_f32_e32 v82, 0, v82
	v_max_f32_e32 v83, 0, v83
	global_store_dwordx4 v[98:99], v[88:91], off
	v_pk_mul_f32 v[86:87], v[86:87], v[100:101] op_sel_hi:[1,0]
	v_max_f32_e32 v84, 0, v84
	v_max_f32_e32 v80, 0, v80
	v_max_f32_e32 v85, 0, v85
	v_max_f32_e32 v81, 0, v81
	v_pk_mul_f32 v[90:91], v[82:83], v[82:83]
	v_pk_mul_f32 v[84:85], v[84:85], v[84:85]
	v_pk_mul_f32 v[88:89], v[80:81], v[80:81]
	v_max_f32_e32 v80, 0, v86
	v_max_f32_e32 v81, 0, v87
	v_pk_mul_f32 v[86:87], v[80:81], v[80:81]
	v_cvt_pk_bf16_f32 v80, v84, v85
	v_cvt_pk_bf16_f32 v81, v86, v87
	v_cvt_pk_bf16_f32 v82, v88, v89
	v_cvt_pk_bf16_f32 v83, v90, v91
	global_store_dwordx4 v[98:99], v[80:83], off offset:256
	s_nop 1
	v_mov_b32_e32 v80, v231
	v_pk_mul_f32 v[72:73], v[72:73], v[80:81] op_sel_hi:[1,0]
	v_pk_mul_f32 v[78:79], v[78:79], v[80:81] op_sel_hi:[1,0]
	v_pk_mul_f32 v[76:77], v[76:77], v[80:81] op_sel_hi:[1,0]
	v_pk_mul_f32 v[74:75], v[74:75], v[80:81] op_sel_hi:[1,0]
	v_max_f32_e32 v72, 0, v72
	v_max_f32_e32 v73, 0, v73
	v_lshlrev_b64 v[82:83], 13, v[164:165]
	v_max_f32_e32 v76, 0, v76
	v_max_f32_e32 v77, 0, v77
	v_pk_mul_f32 v[84:85], v[72:73], v[72:73]
	v_max_f32_e32 v72, 0, v78
	v_max_f32_e32 v74, 0, v74
	v_max_f32_e32 v73, 0, v79
	v_max_f32_e32 v75, 0, v75
	v_lshl_add_u64 v[82:83], s[96:97], 0, v[82:83]
	v_pk_mul_f32 v[76:77], v[76:77], v[76:77]
	v_pk_mul_f32 v[78:79], v[72:73], v[72:73]
	v_pk_mul_f32 v[86:87], v[74:75], v[74:75]
	v_pk_mul_f32 v[64:65], v[64:65], v[80:81] op_sel_hi:[1,0]
	v_lshl_add_u64 v[82:83], v[82:83], 0, v[148:149]
	v_cvt_pk_bf16_f32 v72, v76, v77
	v_cvt_pk_bf16_f32 v73, v78, v79
	v_cvt_pk_bf16_f32 v74, v84, v85
	v_cvt_pk_bf16_f32 v75, v86, v87
	v_pk_mul_f32 v[70:71], v[70:71], v[80:81] op_sel_hi:[1,0]
	v_max_f32_e32 v64, 0, v64
	v_max_f32_e32 v65, 0, v65
	global_store_dwordx4 v[82:83], v[72:75], off
	v_pk_mul_f32 v[68:69], v[68:69], v[80:81] op_sel_hi:[1,0]
	v_pk_mul_f32 v[66:67], v[66:67], v[80:81] op_sel_hi:[1,0]
	v_pk_mul_f32 v[72:73], v[64:65], v[64:65]
	v_max_f32_e32 v64, 0, v70
	v_max_f32_e32 v65, 0, v71
	v_max_f32_e32 v68, 0, v68
	v_max_f32_e32 v69, 0, v69
	v_pk_mul_f32 v[68:69], v[68:69], v[68:69]
	v_pk_mul_f32 v[76:77], v[64:65], v[64:65]
	v_cvt_pk_bf16_f32 v64, v68, v69
	s_waitcnt lgkmcnt(0)
; __device__ __forceinline__ unsigned pk2(float lo, float hi) { const f32x2 v = (f32x2){lo, hi}; const bf16x2_t b = __builtin_convertvector(v, bf16x2_t); return __builtin_bit_cast(unsigned, b); }
;     __device__ __forceinline__ void operator()(const f32x4 (&acc)[2][2][4][2], const Unit& u, int wr, int wc, int fr, int fq, const float (&)[8]) const {
;     ...
;             for (int m = 0; m < 4; ++m) { const int row = row0 + ai * HALF + m * 16; const float rs = rsqrtf(ep[ai * 4 + m] * (1.0f / 1024.0f) + EPS);
;                 u16* rowp = O + (size_t)row * ldc + col0;
; #pragma unroll
;                 for (int bj = 0; bj < 2; ++bj) { f32x4 v0 = acc[ai][bj][m][0] * rs, v1 = acc[ai][bj][m][1] * rs;
;                     if (ACT == 1) {
; #pragma unroll
;                         for (int j = 0; j < 4; ++j) { const float a0 = fmaxf(v0[j], 0.f), a1 = fmaxf(v1[j], 0.f); v0[j] = a0 * a0; v1[j] = a1 * a1; } }
;                     u32x4 w; w.x = pk2(v0[0], v0[1]); w.y = pk2(v0[2], v0[3]); w.z = pk2(v1[0], v1[1]); w.w = pk2(v1[2], v1[3]);
;                     *(u32x4*)(rowp + bj * HALF) = w; } }
	v_max_f32_e32 v66, 0, v66
	v_max_f32_e32 v67, 0, v67
	v_pk_mul_f32 v[78:79], v[66:67], v[66:67]
	v_cvt_pk_bf16_f32 v65, v76, v77
	v_cvt_pk_bf16_f32 v66, v72, v73
	v_cvt_pk_bf16_f32 v67, v78, v79
	global_store_dwordx4 v[82:83], v[64:67], off offset:256
	s_waitcnt lgkmcnt(0)
	s_nop 0
	s_nop 0
	s_nop 0
	s_nop 1
	v_lshlrev_b64 v[66:67], 13, v[162:163]
	v_lshl_add_u64 v[66:67], s[96:97], 0, v[66:67]
	v_lshl_add_u64 v[66:67], v[66:67], 0, v[148:149]
	v_mov_b32_e32 v68, v232
	v_pk_mul_f32 v[56:57], v[56:57], v[68:69] op_sel_hi:[1,0]
	v_pk_mul_f32 v[62:63], v[62:63], v[68:69] op_sel_hi:[1,0]
	v_pk_mul_f32 v[60:61], v[60:61], v[68:69] op_sel_hi:[1,0]
	v_pk_mul_f32 v[58:59], v[58:59], v[68:69] op_sel_hi:[1,0]
	v_max_f32_e32 v56, 0, v56
	v_max_f32_e32 v57, 0, v57
	v_max_f32_e32 v60, 0, v60
	v_max_f32_e32 v61, 0, v61
	v_pk_mul_f32 v[70:71], v[56:57], v[56:57]
	v_max_f32_e32 v56, 0, v62
	v_max_f32_e32 v58, 0, v58
	v_max_f32_e32 v57, 0, v63
	v_max_f32_e32 v59, 0, v59
	v_pk_mul_f32 v[60:61], v[60:61], v[60:61]
	v_pk_mul_f32 v[62:63], v[56:57], v[56:57]
	v_pk_mul_f32 v[72:73], v[58:59], v[58:59]
	v_pk_mul_f32 v[50:51], v[50:51], v[68:69] op_sel_hi:[1,0]
	v_cvt_pk_bf16_f32 v56, v60, v61
	v_cvt_pk_bf16_f32 v57, v62, v63
	v_cvt_pk_bf16_f32 v58, v70, v71
	v_cvt_pk_bf16_f32 v59, v72, v73
	v_pk_mul_f32 v[52:53], v[52:53], v[68:69] op_sel_hi:[1,0]
	v_pk_mul_f32 v[48:49], v[48:49], v[68:69] op_sel_hi:[1,0]
	v_max_f32_e32 v50, 0, v50
	v_max_f32_e32 v51, 0, v51
	global_store_dwordx4 v[66:67], v[56:59], off
	v_pk_mul_f32 v[54:55], v[54:55], v[68:69] op_sel_hi:[1,0]
	v_max_f32_e32 v52, 0, v52
	v_max_f32_e32 v48, 0, v48
	v_max_f32_e32 v53, 0, v53
	v_max_f32_e32 v49, 0, v49
	v_pk_mul_f32 v[58:59], v[50:51], v[50:51]
	v_pk_mul_f32 v[52:53], v[52:53], v[52:53]
	v_pk_mul_f32 v[56:57], v[48:49], v[48:49]
	v_max_f32_e32 v48, 0, v54
	v_max_f32_e32 v49, 0, v55
	v_pk_mul_f32 v[54:55], v[48:49], v[48:49]
	v_cvt_pk_bf16_f32 v48, v52, v53
	v_cvt_pk_bf16_f32 v49, v54, v55
	v_cvt_pk_bf16_f32 v50, v56, v57
	v_cvt_pk_bf16_f32 v51, v58, v59
	global_store_dwordx4 v[66:67], v[48:51], off offset:256
	s_nop 1
	v_mov_b32_e32 v48, v233
	v_pk_mul_f32 v[40:41], v[40:41], v[48:49] op_sel_hi:[1,0]
	v_pk_mul_f32 v[46:47], v[46:47], v[48:49] op_sel_hi:[1,0]
	v_pk_mul_f32 v[44:45], v[44:45], v[48:49] op_sel_hi:[1,0]
	v_pk_mul_f32 v[42:43], v[42:43], v[48:49] op_sel_hi:[1,0]
	v_max_f32_e32 v40, 0, v40
	v_max_f32_e32 v41, 0, v41
	v_lshlrev_b64 v[50:51], 13, v[156:157]
	v_max_f32_e32 v44, 0, v44
	v_max_f32_e32 v45, 0, v45
	v_pk_mul_f32 v[52:53], v[40:41], v[40:41]
	v_max_f32_e32 v40, 0, v46
	v_max_f32_e32 v42, 0, v42
	v_max_f32_e32 v41, 0, v47
	v_max_f32_e32 v43, 0, v43
	v_lshl_add_u64 v[50:51], s[96:97], 0, v[50:51]
	v_pk_mul_f32 v[44:45], v[44:45], v[44:45]
	v_pk_mul_f32 v[46:47], v[40:41], v[40:41]
	v_pk_mul_f32 v[54:55], v[42:43], v[42:43]
	v_pk_mul_f32 v[32:33], v[32:33], v[48:49] op_sel_hi:[1,0]
	v_lshl_add_u64 v[50:51], v[50:51], 0, v[148:149]
	v_cvt_pk_bf16_f32 v40, v44, v45
	v_cvt_pk_bf16_f32 v41, v46, v47
	v_cvt_pk_bf16_f32 v42, v52, v53
	v_cvt_pk_bf16_f32 v43, v54, v55
	v_pk_mul_f32 v[38:39], v[38:39], v[48:49] op_sel_hi:[1,0]
	v_max_f32_e32 v32, 0, v32
	v_max_f32_e32 v33, 0, v33
	global_store_dwordx4 v[50:51], v[40:43], off
	v_pk_mul_f32 v[36:37], v[36:37], v[48:49] op_sel_hi:[1,0]
	v_pk_mul_f32 v[34:35], v[34:35], v[48:49] op_sel_hi:[1,0]
	v_pk_mul_f32 v[40:41], v[32:33], v[32:33]
	v_max_f32_e32 v32, 0, v38
	v_max_f32_e32 v33, 0, v39
	v_max_f32_e32 v36, 0, v36
	v_max_f32_e32 v37, 0, v37
	v_pk_mul_f32 v[36:37], v[36:37], v[36:37]
	v_pk_mul_f32 v[44:45], v[32:33], v[32:33]
	v_cvt_pk_bf16_f32 v32, v36, v37
	s_waitcnt lgkmcnt(0)
	v_max_f32_e32 v34, 0, v34
	v_max_f32_e32 v35, 0, v35
	v_pk_mul_f32 v[46:47], v[34:35], v[34:35]
	v_cvt_pk_bf16_f32 v33, v44, v45
	v_cvt_pk_bf16_f32 v34, v40, v41
	v_cvt_pk_bf16_f32 v35, v46, v47
	global_store_dwordx4 v[50:51], v[32:35], off offset:256
	s_waitcnt lgkmcnt(0)
; __device__ __forceinline__ unsigned pk2(float lo, float hi) { const f32x2 v = (f32x2){lo, hi}; const bf16x2_t b = __builtin_convertvector(v, bf16x2_t); return __builtin_bit_cast(unsigned, b); }
; #define PG8_WAIT_V(n) asm volatile("s_waitcnt vmcnt(" #n ")" ::: "memory")
; #define PG8_BAR __builtin_amdgcn_s_barrier()
;     __device__ __forceinline__ void operator()(const f32x4 (&acc)[2][2][4][2], const Unit& u, int wr, int wc, int fr, int fq, const float (&)[8]) const {
;     ...
;             for (int m = 0; m < 4; ++m) { const int row = row0 + ai * HALF + m * 16; const float rs = rsqrtf(ep[ai * 4 + m] * (1.0f / 1024.0f) + EPS);
;                 u16* rowp = O + (size_t)row * ldc + col0;
; #pragma unroll
;                 for (int bj = 0; bj < 2; ++bj) { f32x4 v0 = acc[ai][bj][m][0] * rs, v1 = acc[ai][bj][m][1] * rs;
;                     if (ACT == 1) {
; #pragma unroll
;                         for (int j = 0; j < 4; ++j) { const float a0 = fmaxf(v0[j], 0.f), a1 = fmaxf(v1[j], 0.f); v0[j] = a0 * a0; v1[j] = a1 * a1; } }
;                     u32x4 w; w.x = pk2(v0[0], v0[1]); w.y = pk2(v0[2], v0[3]); w.z = pk2(v1[0], v1[1]); w.w = pk2(v1[2], v1[3]);
;                     *(u32x4*)(rowp + bj * HALF) = w; } }
; template <class Epi>
; __device__ __forceinline__ void gemm_phase(LAS unsigned char* lds, const Gemm g, const StaticOrder& S, const Epi& E) {
;     ...
;         E(acc, cur, wr, wc, fr, fq, epre);
;         if (!has_next) break;
; #pragma unroll
;         for (int a = 0; a < 2; ++a)
; #pragma unroll
;             for (int b = 0; b < 2; ++b)
; #pragma unroll
;                 for (int m = 0; m < 4; ++m)
; #pragma unroll
;                     for (int n = 0; n < 2; ++n) acc[a][b][m][n] = (f32x4){0.f, 0.f, 0.f, 0.f};
;         cur = nxt; cA = nA; cB = nB; ++ui;
;     }
;     PG8_WAIT_V(0);
;     if (wr == 0) PG8_BAR;
	s_nop 0
	s_nop 0
	s_nop 0
	s_nop 1
	v_lshlrev_b64 v[34:35], 13, v[150:151]
	v_lshl_add_u64 v[34:35], s[96:97], 0, v[34:35]
	v_lshl_add_u64 v[34:35], v[34:35], 0, v[148:149]
	v_mov_b32_e32 v36, v234
	v_pk_mul_f32 v[24:25], v[24:25], v[36:37] op_sel_hi:[1,0]
	v_pk_mul_f32 v[30:31], v[30:31], v[36:37] op_sel_hi:[1,0]
	v_pk_mul_f32 v[28:29], v[28:29], v[36:37] op_sel_hi:[1,0]
	v_pk_mul_f32 v[26:27], v[26:27], v[36:37] op_sel_hi:[1,0]
	v_max_f32_e32 v24, 0, v24
	v_max_f32_e32 v25, 0, v25
	v_max_f32_e32 v28, 0, v28
	v_max_f32_e32 v29, 0, v29
	v_pk_mul_f32 v[38:39], v[24:25], v[24:25]
	v_max_f32_e32 v24, 0, v30
	v_max_f32_e32 v26, 0, v26
	v_max_f32_e32 v25, 0, v31
	v_max_f32_e32 v27, 0, v27
	v_pk_mul_f32 v[28:29], v[28:29], v[28:29]
	v_pk_mul_f32 v[30:31], v[24:25], v[24:25]
	v_pk_mul_f32 v[40:41], v[26:27], v[26:27]
	v_pk_mul_f32 v[18:19], v[18:19], v[36:37] op_sel_hi:[1,0]
	v_cvt_pk_bf16_f32 v24, v28, v29
	v_cvt_pk_bf16_f32 v25, v30, v31
	v_cvt_pk_bf16_f32 v26, v38, v39
	v_cvt_pk_bf16_f32 v27, v40, v41
	v_pk_mul_f32 v[20:21], v[20:21], v[36:37] op_sel_hi:[1,0]
	v_pk_mul_f32 v[16:17], v[16:17], v[36:37] op_sel_hi:[1,0]
	v_max_f32_e32 v18, 0, v18
	v_max_f32_e32 v19, 0, v19
	global_store_dwordx4 v[34:35], v[24:27], off
	v_pk_mul_f32 v[22:23], v[22:23], v[36:37] op_sel_hi:[1,0]
	v_max_f32_e32 v20, 0, v20
	v_max_f32_e32 v16, 0, v16
	v_max_f32_e32 v21, 0, v21
	v_max_f32_e32 v17, 0, v17
	v_pk_mul_f32 v[26:27], v[18:19], v[18:19]
	v_pk_mul_f32 v[20:21], v[20:21], v[20:21]
	v_pk_mul_f32 v[24:25], v[16:17], v[16:17]
	v_max_f32_e32 v16, 0, v22
	v_max_f32_e32 v17, 0, v23
	v_pk_mul_f32 v[22:23], v[16:17], v[16:17]
	v_cvt_pk_bf16_f32 v16, v20, v21
	v_cvt_pk_bf16_f32 v17, v22, v23
	v_cvt_pk_bf16_f32 v18, v24, v25
	v_cvt_pk_bf16_f32 v19, v26, v27
	global_store_dwordx4 v[34:35], v[16:19], off offset:256
	s_nop 1
	v_mov_b32_e32 v16, v235
	v_pk_mul_f32 v[8:9], v[8:9], v[16:17] op_sel_hi:[1,0]
	v_pk_mul_f32 v[14:15], v[14:15], v[16:17] op_sel_hi:[1,0]
	v_pk_mul_f32 v[12:13], v[12:13], v[16:17] op_sel_hi:[1,0]
	v_pk_mul_f32 v[10:11], v[10:11], v[16:17] op_sel_hi:[1,0]
	v_max_f32_e32 v8, 0, v8
	v_max_f32_e32 v9, 0, v9
	v_lshlrev_b64 v[18:19], 13, v[146:147]
	v_max_f32_e32 v12, 0, v12
	v_max_f32_e32 v13, 0, v13
	v_pk_mul_f32 v[20:21], v[8:9], v[8:9]
	v_max_f32_e32 v8, 0, v14
	v_max_f32_e32 v10, 0, v10
	v_max_f32_e32 v9, 0, v15
	v_max_f32_e32 v11, 0, v11
	v_lshl_add_u64 v[18:19], s[96:97], 0, v[18:19]
	v_pk_mul_f32 v[12:13], v[12:13], v[12:13]
	v_pk_mul_f32 v[14:15], v[8:9], v[8:9]
	v_pk_mul_f32 v[22:23], v[10:11], v[10:11]
	v_pk_mul_f32 v[0:1], v[0:1], v[16:17] op_sel_hi:[1,0]
	v_lshl_add_u64 v[18:19], v[18:19], 0, v[148:149]
	v_cvt_pk_bf16_f32 v8, v12, v13
	v_cvt_pk_bf16_f32 v9, v14, v15
	v_cvt_pk_bf16_f32 v10, v20, v21
	v_cvt_pk_bf16_f32 v11, v22, v23
	v_pk_mul_f32 v[6:7], v[6:7], v[16:17] op_sel_hi:[1,0]
	v_pk_mul_f32 v[4:5], v[4:5], v[16:17] op_sel_hi:[1,0]
	v_pk_mul_f32 v[2:3], v[2:3], v[16:17] op_sel_hi:[1,0]
	v_max_f32_e32 v0, 0, v0
	v_max_f32_e32 v1, 0, v1
	global_store_dwordx4 v[18:19], v[8:11], off
	v_max_f32_e32 v4, 0, v4
	v_max_f32_e32 v5, 0, v5
	v_pk_mul_f32 v[8:9], v[0:1], v[0:1]
	v_max_f32_e32 v0, 0, v6
	v_max_f32_e32 v2, 0, v2
	v_max_f32_e32 v1, 0, v7
	v_max_f32_e32 v3, 0, v3
	v_pk_mul_f32 v[4:5], v[4:5], v[4:5]
	v_pk_mul_f32 v[6:7], v[0:1], v[0:1]
	v_pk_mul_f32 v[10:11], v[2:3], v[2:3]
	v_cvt_pk_bf16_f32 v0, v4, v5
	v_cvt_pk_bf16_f32 v1, v6, v7
	v_cvt_pk_bf16_f32 v2, v8, v9
	v_cvt_pk_bf16_f32 v3, v10, v11
	s_and_b64 vcc, exec, s[0:1]
	global_store_dwordx4 v[18:19], v[0:3], off offset:256
	s_cbranch_vccz .LBB0_763
	s_waitcnt vmcnt(0)
	s_cmpk_gt_u32 s9, 0xff
	s_cbranch_scc1 .LBB0_774
	s_barrier

; #define PG8_STAGE(bufoff, gbase, voff) do { _Pragma("unroll") for (int _i = 0; _i < 2; ++_i) \
;         __builtin_amdgcn_global_load_lds((const unsigned*)((const char*)(gbase) + (voff)[_i]), (LAS unsigned*)(lds + (bufoff) + ldsw + _i * 8192), 16, 0, 0); } while (0)
; #define PG8_LDA(dst, b, h) do { _Pragma("unroll") for (int m = 0; m < 4; ++m) _Pragma("unroll") for (int k = 0; k < 2; ++k) dst[m][k] = *(const LAS bf16x8*)(lds + PG8_SA(b, h) + aoff + m * 2048 + k * 1024); } while (0)
; #define PG8_LDB(dst, b, h) do { _Pragma("unroll") for (int n = 0; n < 2; ++n) _Pragma("unroll") for (int k = 0; k < 2; ++k) dst[n][k] = *(const LAS bf16x8*)(lds + PG8_SB(b, h) + boff + n * 2048 + k * 1024); } while (0)
; #define PG8_MMA(ai, bj, At, Bt) do { __builtin_amdgcn_s_setprio(1); _Pragma("unroll") for (int m = 0; m < 4; ++m) _Pragma("unroll") for (int n = 0; n < 2; ++n) _Pragma("unroll") for (int k = 0; k < 2; ++k) \
;         acc[ai][bj][m][n] = __builtin_amdgcn_mfma_f32_16x16x32_bf16(Bt[n][k], At[m][k], acc[ai][bj][m][n], 0, 0, 0); __builtin_amdgcn_s_setprio(0); } while (0)
; #define PG8_WAIT_L(n) asm volatile("s_waitcnt lgkmcnt(" #n ")" ::: "memory")
; #define PG8_BAR __builtin_amdgcn_s_barrier()
; #define PG8_SCHED __builtin_amdgcn_sched_barrier(0)
; template <class Epi>
; __device__ __forceinline__ void gemm_phase(LAS unsigned char* lds, const Gemm g, const StaticOrder& S, const Epi& E) {
;     ...
;         for (int t = 0; t < nt; t += 2) {
;             const bool last = (t == nt - 2);
;             const char* a1 = cA + (size_t)(t + 1) * kstep;
;             const char* a2 = last ? nA : cA + (size_t)(t + 2) * kstep; const char* b2 = last ? nB : cB + (size_t)(t + 2) * kstep;
;             const char* a3 = a2 + kstep; const char* b3 = b2 + kstep;
;             if (last) E.pre(cur, wr, fr, epre);
;             PG8_LDB(B0, 0, 0); PG8_SCHED; PG8_LDA(At, 0, 0); PG8_STAGE(PG8_SA(1, 1), a1 + hstepA, voffA);
;             PG8_WAIT_L(8); PG8_BAR; PG8_WAIT_L(0); PG8_MMA(0, 0, At, B0); PG8_BAR; PG8_SCHED;
;             PG8_LDB(B1, 0, 1); PG8_STAGE(PG8_SB(0, 0), b2, voffB);
;             PG8_BAR; PG8_WAIT_L(0); PG8_MMA(0, 1, At, B1); PG8_BAR;
;             PG8_LDA(At, 0, 1); PG8_STAGE(PG8_SA(0, 0), a2, voffA);
;             PG8_BAR; PG8_WAIT_L(0); PG8_MMA(1, 0, At, B0); PG8_BAR; PG8_SCHED;
.LBB0_844:
	ds_read_b128 v[128:131], v191
	ds_read_b128 v[132:135], v191 offset:1024
	ds_read_b128 v[136:139], v191 offset:2048
	ds_read_b128 v[140:143], v191 offset:3072
	s_add_u32 s24, s22, 0xfff00080
	s_addc_u32 s25, s23, -1
	s_cmp_eq_u32 s48, 60
	s_cselect_b32 s27, s17, s25
	s_cselect_b32 s26, s44, s24
	s_cselect_b32 s25, s15, s47
	s_cselect_b32 s24, s45, s46
	v_lshl_add_u64 v[186:187], s[22:23], 0, v[162:163]
	s_add_i32 m0, s7, 0xc000
	ds_read_b128 v[144:147], v192
	ds_read_b128 v[148:151], v192 offset:1024
	ds_read_b128 v[170:173], v192 offset:2048
	ds_read_b128 v[174:177], v192 offset:3072
	ds_read_b128 v[178:181], v192 offset:4096
	ds_read_b128 v[182:185], v192 offset:5120
	ds_read_b128 v[196:199], v192 offset:6144
	ds_read_b128 v[200:203], v192 offset:7168
	global_load_lds_dwordx4 v[186:187], off
	v_lshl_add_u64 v[186:187], s[22:23], 0, v[164:165]
	s_add_i32 m0, s7, 0xe000
	s_nop 0
	global_load_lds_dwordx4 v[186:187], off
	s_waitcnt lgkmcnt(8)
	s_barrier
	s_waitcnt lgkmcnt(0)
	v_mfma_f32_16x16x32_bf16 v[124:127], v[128:131], v[144:147], v[124:127]
	v_mfma_f32_16x16x32_bf16 v[120:123], v[136:139], v[144:147], v[120:123]
	v_mfma_f32_16x16x32_bf16 v[108:111], v[128:131], v[170:173], v[108:111]
	v_mfma_f32_16x16x32_bf16 v[104:107], v[136:139], v[170:173], v[104:107]
	v_mfma_f32_16x16x32_bf16 v[92:95], v[128:131], v[178:181], v[92:95]
	v_mfma_f32_16x16x32_bf16 v[88:91], v[136:139], v[178:181], v[88:91]
	v_mfma_f32_16x16x32_bf16 v[76:79], v[128:131], v[196:199], v[76:79]
	v_mfma_f32_16x16x32_bf16 v[72:75], v[136:139], v[196:199], v[72:75]
	v_mfma_f32_16x16x32_bf16 v[124:127], v[132:135], v[148:151], v[124:127]
	v_mfma_f32_16x16x32_bf16 v[120:123], v[140:143], v[148:151], v[120:123]
	v_mfma_f32_16x16x32_bf16 v[108:111], v[132:135], v[174:177], v[108:111]
	v_mfma_f32_16x16x32_bf16 v[104:107], v[140:143], v[174:177], v[104:107]
	v_mfma_f32_16x16x32_bf16 v[92:95], v[132:135], v[182:185], v[92:95]
	v_mfma_f32_16x16x32_bf16 v[88:91], v[140:143], v[182:185], v[88:91]
	v_mfma_f32_16x16x32_bf16 v[76:79], v[132:135], v[200:203], v[76:79]
	v_mfma_f32_16x16x32_bf16 v[72:75], v[140:143], v[200:203], v[72:75]
	s_barrier
	s_add_i32 s49, s42, s31
	v_lshl_add_u64 v[186:187], s[24:25], 0, v[156:157]
	s_mov_b32 m0, s49
	ds_read_b128 v[204:207], v193
	ds_read_b128 v[208:211], v193 offset:1024
	ds_read_b128 v[212:215], v193 offset:2048
	ds_read_b128 v[216:219], v193 offset:3072
	global_load_lds_dwordx4 v[186:187], off
	v_lshl_add_u64 v[220:221], s[24:25], 0, v[160:161]
	s_add_i32 m0, s49, 0x2000
	s_nop 0
	global_load_lds_dwordx4 v[220:221], off
	s_barrier
	s_waitcnt lgkmcnt(0)
	v_mfma_f32_16x16x32_bf16 v[116:119], v[204:207], v[144:147], v[116:119]
	v_mfma_f32_16x16x32_bf16 v[112:115], v[212:215], v[144:147], v[112:115]
	v_mfma_f32_16x16x32_bf16 v[100:103], v[204:207], v[170:173], v[100:103]
	v_mfma_f32_16x16x32_bf16 v[96:99], v[212:215], v[170:173], v[96:99]
	v_mfma_f32_16x16x32_bf16 v[84:87], v[204:207], v[178:181], v[84:87]
	v_mfma_f32_16x16x32_bf16 v[80:83], v[212:215], v[178:181], v[80:83]
	v_mfma_f32_16x16x32_bf16 v[68:71], v[204:207], v[196:199], v[68:71]
	v_mfma_f32_16x16x32_bf16 v[64:67], v[212:215], v[196:199], v[64:67]
	v_mfma_f32_16x16x32_bf16 v[116:119], v[208:211], v[148:151], v[116:119]
	v_mfma_f32_16x16x32_bf16 v[112:115], v[216:219], v[148:151], v[112:115]
	v_mfma_f32_16x16x32_bf16 v[100:103], v[208:211], v[174:177], v[100:103]
	v_mfma_f32_16x16x32_bf16 v[96:99], v[216:219], v[174:177], v[96:99]
	v_mfma_f32_16x16x32_bf16 v[84:87], v[208:211], v[182:185], v[84:87]
	v_mfma_f32_16x16x32_bf16 v[80:83], v[216:219], v[182:185], v[80:83]
	v_mfma_f32_16x16x32_bf16 v[68:71], v[208:211], v[200:203], v[68:71]
	v_mfma_f32_16x16x32_bf16 v[64:67], v[216:219], v[200:203], v[64:67]
	s_mov_b32 m0, s7
	v_lshl_add_u64 v[222:223], s[26:27], 0, v[154:155]
	s_barrier
	ds_read_b128 v[144:147], v192 offset:16384
	ds_read_b128 v[148:151], v192 offset:17408
	ds_read_b128 v[170:173], v192 offset:18432
	ds_read_b128 v[174:177], v192 offset:19456
	ds_read_b128 v[178:181], v192 offset:20480
	ds_read_b128 v[182:185], v192 offset:21504
	ds_read_b128 v[196:199], v192 offset:22528
	ds_read_b128 v[200:203], v192 offset:23552
	global_load_lds_dwordx4 v[222:223], off
	v_lshl_add_u64 v[224:225], s[26:27], 0, v[158:159]
	s_mov_b32 m0, s34
	s_nop 0
	global_load_lds_dwordx4 v[224:225], off
	s_barrier
	s_waitcnt lgkmcnt(0)
	v_mfma_f32_16x16x32_bf16 v[60:63], v[128:131], v[144:147], v[60:63]
	v_mfma_f32_16x16x32_bf16 v[56:59], v[136:139], v[144:147], v[56:59]
	v_mfma_f32_16x16x32_bf16 v[44:47], v[128:131], v[170:173], v[44:47]
	v_mfma_f32_16x16x32_bf16 v[40:43], v[136:139], v[170:173], v[40:43]
	v_mfma_f32_16x16x32_bf16 v[28:31], v[128:131], v[178:181], v[28:31]
	v_mfma_f32_16x16x32_bf16 v[24:27], v[136:139], v[178:181], v[24:27]
	v_mfma_f32_16x16x32_bf16 v[12:15], v[128:131], v[196:199], v[12:15]
	v_mfma_f32_16x16x32_bf16 v[8:11], v[136:139], v[196:199], v[8:11]
	v_mfma_f32_16x16x32_bf16 v[60:63], v[132:135], v[148:151], v[60:63]
	v_mfma_f32_16x16x32_bf16 v[56:59], v[140:143], v[148:151], v[56:59]
	v_mfma_f32_16x16x32_bf16 v[44:47], v[132:135], v[174:177], v[44:47]
	v_mfma_f32_16x16x32_bf16 v[40:43], v[140:143], v[174:177], v[40:43]
	v_mfma_f32_16x16x32_bf16 v[28:31], v[132:135], v[182:185], v[28:31]
	v_mfma_f32_16x16x32_bf16 v[24:27], v[140:143], v[182:185], v[24:27]
	v_mfma_f32_16x16x32_bf16 v[12:15], v[132:135], v[200:203], v[12:15]
	v_mfma_f32_16x16x32_bf16 v[8:11], v[140:143], v[200:203], v[8:11]
	s_barrier
; #define PG8_STAGE(bufoff, gbase, voff) do { _Pragma("unroll") for (int _i = 0; _i < 2; ++_i) \
;         __builtin_amdgcn_global_load_lds((const unsigned*)((const char*)(gbase) + (voff)[_i]), (LAS unsigned*)(lds + (bufoff) + ldsw + _i * 8192), 16, 0, 0); } while (0)
; #define PG8_LDA(dst, b, h) do { _Pragma("unroll") for (int m = 0; m < 4; ++m) _Pragma("unroll") for (int k = 0; k < 2; ++k) dst[m][k] = *(const LAS bf16x8*)(lds + PG8_SA(b, h) + aoff + m * 2048 + k * 1024); } while (0)
; #define PG8_LDB(dst, b, h) do { _Pragma("unroll") for (int n = 0; n < 2; ++n) _Pragma("unroll") for (int k = 0; k < 2; ++k) dst[n][k] = *(const LAS bf16x8*)(lds + PG8_SB(b, h) + boff + n * 2048 + k * 1024); } while (0)
; #define PG8_MMA(ai, bj, At, Bt) do { __builtin_amdgcn_s_setprio(1); _Pragma("unroll") for (int m = 0; m < 4; ++m) _Pragma("unroll") for (int n = 0; n < 2; ++n) _Pragma("unroll") for (int k = 0; k < 2; ++k) \
;         acc[ai][bj][m][n] = __builtin_amdgcn_mfma_f32_16x16x32_bf16(Bt[n][k], At[m][k], acc[ai][bj][m][n], 0, 0, 0); __builtin_amdgcn_s_setprio(0); } while (0)
; #define PG8_WAIT_V(n) asm volatile("s_waitcnt vmcnt(" #n ")" ::: "memory")
; #define PG8_WAIT_L(n) asm volatile("s_waitcnt lgkmcnt(" #n ")" ::: "memory")
; #define PG8_BAR __builtin_amdgcn_s_barrier()
; #define PG8_SCHED __builtin_amdgcn_sched_barrier(0)
; template <class Epi>
; __device__ __forceinline__ void gemm_phase(LAS unsigned char* lds, const Gemm g, const StaticOrder& S, const Epi& E) {
;     ...
;             PG8_STAGE(PG8_SB(0, 1), b2 + hstepB, voffB);
;             PG8_WAIT_V(6); PG8_BAR; PG8_MMA(1, 1, At, B1); PG8_BAR;
;             PG8_LDB(B0, 1, 0); PG8_SCHED; PG8_LDA(At, 1, 0); PG8_STAGE(PG8_SA(0, 1), a2 + hstepA, voffA);
;             PG8_WAIT_L(8); PG8_BAR; PG8_WAIT_L(0); PG8_MMA(0, 0, At, B0); PG8_BAR; PG8_SCHED;
;             PG8_LDB(B1, 1, 1); PG8_STAGE(PG8_SB(1, 0), b3, voffB);
;             PG8_BAR; PG8_WAIT_L(0); PG8_MMA(0, 1, At, B1); PG8_BAR;
;             PG8_LDA(At, 1, 1); PG8_STAGE(PG8_SA(1, 0), a3, voffA);
	s_add_u32 s50, s24, 0x100000
	s_addc_u32 s51, s25, 0
	s_add_i32 s49, s43, s31
	v_lshl_add_u64 v[128:129], s[50:51], 0, v[156:157]
	s_mov_b32 m0, s49
	s_nop 0
	global_load_lds_dwordx4 v[128:129], off
	v_lshl_add_u64 v[128:129], s[50:51], 0, v[160:161]
	s_add_i32 m0, s49, 0x2000
	s_nop 0
	global_load_lds_dwordx4 v[128:129], off
	s_waitcnt vmcnt(6)
	s_barrier
	v_mfma_f32_16x16x32_bf16 v[52:55], v[204:207], v[144:147], v[52:55]
	v_mfma_f32_16x16x32_bf16 v[48:51], v[212:215], v[144:147], v[48:51]
	v_mfma_f32_16x16x32_bf16 v[36:39], v[204:207], v[170:173], v[36:39]
	v_mfma_f32_16x16x32_bf16 v[32:35], v[212:215], v[170:173], v[32:35]
	v_mfma_f32_16x16x32_bf16 v[20:23], v[204:207], v[178:181], v[20:23]
	v_mfma_f32_16x16x32_bf16 v[16:19], v[212:215], v[178:181], v[16:19]
	v_mfma_f32_16x16x32_bf16 v[4:7], v[204:207], v[196:199], v[4:7]
	v_mfma_f32_16x16x32_bf16 v[0:3], v[212:215], v[196:199], v[0:3]
	v_mfma_f32_16x16x32_bf16 v[52:55], v[208:211], v[148:151], v[52:55]
	v_mfma_f32_16x16x32_bf16 v[48:51], v[216:219], v[148:151], v[48:51]
	v_mfma_f32_16x16x32_bf16 v[36:39], v[208:211], v[174:177], v[36:39]
	v_mfma_f32_16x16x32_bf16 v[32:35], v[216:219], v[174:177], v[32:35]
	v_mfma_f32_16x16x32_bf16 v[20:23], v[208:211], v[182:185], v[20:23]
	v_mfma_f32_16x16x32_bf16 v[16:19], v[216:219], v[182:185], v[16:19]
	v_mfma_f32_16x16x32_bf16 v[4:7], v[208:211], v[200:203], v[4:7]
	v_mfma_f32_16x16x32_bf16 v[0:3], v[216:219], v[200:203], v[0:3]
	s_add_i32 s49, 0, 0x18000
	v_add_u32_e32 v140, s49, v189
	s_barrier
	ds_read_b128 v[128:131], v140
	ds_read_b128 v[132:135], v140 offset:1024
	ds_read_b128 v[136:139], v140 offset:2048
	ds_read_b128 v[140:143], v140 offset:3072
	s_add_u32 s26, s26, 0x100000
	s_addc_u32 s27, s27, 0
	s_mov_b32 m0, s35
	v_lshl_add_u64 v[204:205], s[26:27], 0, v[154:155]
	ds_read_b128 v[144:147], v192 offset:32768
	ds_read_b128 v[148:151], v192 offset:33792
	ds_read_b128 v[170:173], v192 offset:34816
	ds_read_b128 v[174:177], v192 offset:35840
	ds_read_b128 v[178:181], v192 offset:36864
	ds_read_b128 v[182:185], v192 offset:37888
	ds_read_b128 v[196:199], v192 offset:38912
	ds_read_b128 v[200:203], v192 offset:39936
	global_load_lds_dwordx4 v[204:205], off
	v_lshl_add_u64 v[204:205], s[26:27], 0, v[158:159]
	s_mov_b32 m0, s36
	s_nop 0
	global_load_lds_dwordx4 v[204:205], off
	s_waitcnt lgkmcnt(8)
	s_barrier
	s_waitcnt lgkmcnt(0)
	v_mfma_f32_16x16x32_bf16 v[124:127], v[128:131], v[144:147], v[124:127]
	v_mfma_f32_16x16x32_bf16 v[120:123], v[136:139], v[144:147], v[120:123]
	v_mfma_f32_16x16x32_bf16 v[108:111], v[128:131], v[170:173], v[108:111]
	v_mfma_f32_16x16x32_bf16 v[104:107], v[136:139], v[170:173], v[104:107]
	v_mfma_f32_16x16x32_bf16 v[92:95], v[128:131], v[178:181], v[92:95]
	v_mfma_f32_16x16x32_bf16 v[88:91], v[136:139], v[178:181], v[88:91]
	v_mfma_f32_16x16x32_bf16 v[76:79], v[128:131], v[196:199], v[76:79]
	v_mfma_f32_16x16x32_bf16 v[72:75], v[136:139], v[196:199], v[72:75]
	v_mfma_f32_16x16x32_bf16 v[124:127], v[132:135], v[148:151], v[124:127]
	v_mfma_f32_16x16x32_bf16 v[120:123], v[140:143], v[148:151], v[120:123]
	v_mfma_f32_16x16x32_bf16 v[108:111], v[132:135], v[174:177], v[108:111]
	v_mfma_f32_16x16x32_bf16 v[104:107], v[140:143], v[174:177], v[104:107]
	v_mfma_f32_16x16x32_bf16 v[92:95], v[132:135], v[182:185], v[92:95]
	v_mfma_f32_16x16x32_bf16 v[88:91], v[140:143], v[182:185], v[88:91]
	v_mfma_f32_16x16x32_bf16 v[76:79], v[132:135], v[200:203], v[76:79]
	v_mfma_f32_16x16x32_bf16 v[72:75], v[140:143], v[200:203], v[72:75]
	s_barrier
	s_add_i32 s26, 0, 0x1c000
	s_add_i32 s27, s49, s31
	v_add_u32_e32 v195, s26, v189
	v_lshl_add_u64 v[186:187], v[186:187], 0, s[12:13]
	s_mov_b32 m0, s27
	ds_read_b128 v[204:207], v195
	ds_read_b128 v[208:211], v195 offset:1024
	ds_read_b128 v[212:215], v195 offset:2048
	ds_read_b128 v[216:219], v195 offset:3072
	global_load_lds_dwordx4 v[186:187], off
	v_lshl_add_u64 v[186:187], v[220:221], 0, s[12:13]
	s_add_i32 m0, s27, 0x2000
	s_nop 0
	global_load_lds_dwordx4 v[186:187], off
	s_barrier
	s_waitcnt lgkmcnt(0)
	v_mfma_f32_16x16x32_bf16 v[116:119], v[204:207], v[144:147], v[116:119]
	v_mfma_f32_16x16x32_bf16 v[112:115], v[212:215], v[144:147], v[112:115]
	v_mfma_f32_16x16x32_bf16 v[100:103], v[204:207], v[170:173], v[100:103]
	v_mfma_f32_16x16x32_bf16 v[96:99], v[212:215], v[170:173], v[96:99]
	v_mfma_f32_16x16x32_bf16 v[84:87], v[204:207], v[178:181], v[84:87]
	v_mfma_f32_16x16x32_bf16 v[80:83], v[212:215], v[178:181], v[80:83]
	v_mfma_f32_16x16x32_bf16 v[68:71], v[204:207], v[196:199], v[68:71]
	v_mfma_f32_16x16x32_bf16 v[64:67], v[212:215], v[196:199], v[64:67]
	v_mfma_f32_16x16x32_bf16 v[116:119], v[208:211], v[148:151], v[116:119]
	v_mfma_f32_16x16x32_bf16 v[112:115], v[216:219], v[148:151], v[112:115]
	v_mfma_f32_16x16x32_bf16 v[100:103], v[208:211], v[174:177], v[100:103]
	v_mfma_f32_16x16x32_bf16 v[96:99], v[216:219], v[174:177], v[96:99]
	v_mfma_f32_16x16x32_bf16 v[84:87], v[208:211], v[182:185], v[84:87]
	v_mfma_f32_16x16x32_bf16 v[80:83], v[216:219], v[182:185], v[80:83]
	v_mfma_f32_16x16x32_bf16 v[68:71], v[208:211], v[200:203], v[68:71]
	v_mfma_f32_16x16x32_bf16 v[64:67], v[216:219], v[200:203], v[64:67]
	s_mov_b32 m0, s38
	v_lshl_add_u64 v[186:187], v[222:223], 0, s[12:13]
	s_barrier
	ds_read_b128 v[144:147], v192 offset:49152
	ds_read_b128 v[148:151], v192 offset:50176
	ds_read_b128 v[170:173], v192 offset:51200
	ds_read_b128 v[174:177], v192 offset:52224
	ds_read_b128 v[178:181], v192 offset:53248
	ds_read_b128 v[182:185], v192 offset:54272
	ds_read_b128 v[196:199], v192 offset:55296
	ds_read_b128 v[200:203], v192 offset:56320
	global_load_lds_dwordx4 v[186:187], off
	v_lshl_add_u64 v[186:187], v[224:225], 0, s[12:13]
	s_mov_b32 m0, s39
	s_nop 0
	global_load_lds_dwordx4 v[186:187], off
	s_barrier
; #define PG8_STAGE(bufoff, gbase, voff) do { _Pragma("unroll") for (int _i = 0; _i < 2; ++_i) \
;         __builtin_amdgcn_global_load_lds((const unsigned*)((const char*)(gbase) + (voff)[_i]), (LAS unsigned*)(lds + (bufoff) + ldsw + _i * 8192), 16, 0, 0); } while (0)
; #define PG8_MMA(ai, bj, At, Bt) do { __builtin_amdgcn_s_setprio(1); _Pragma("unroll") for (int m = 0; m < 4; ++m) _Pragma("unroll") for (int n = 0; n < 2; ++n) _Pragma("unroll") for (int k = 0; k < 2; ++k) \
;         acc[ai][bj][m][n] = __builtin_amdgcn_mfma_f32_16x16x32_bf16(Bt[n][k], At[m][k], acc[ai][bj][m][n], 0, 0, 0); __builtin_amdgcn_s_setprio(0); } while (0)
; #define PG8_WAIT_V(n) asm volatile("s_waitcnt vmcnt(" #n ")" ::: "memory")
; #define PG8_WAIT_L(n) asm volatile("s_waitcnt lgkmcnt(" #n ")" ::: "memory")
; #define PG8_BAR __builtin_amdgcn_s_barrier()
; #define PG8_SCHED __builtin_amdgcn_sched_barrier(0)
; template <class Epi>
; __device__ __forceinline__ void gemm_phase(LAS unsigned char* lds, const Gemm g, const StaticOrder& S, const Epi& E) {
;     ...
;             PG8_BAR; PG8_WAIT_L(0); PG8_MMA(1, 0, At, B0); PG8_BAR; PG8_SCHED;
;             PG8_STAGE(PG8_SB(1, 1), b3 + hstepB, voffB);
;             PG8_WAIT_V(6); PG8_BAR; PG8_MMA(1, 1, At, B1); PG8_BAR;
;         }
	s_waitcnt lgkmcnt(0)
	v_mfma_f32_16x16x32_bf16 v[60:63], v[128:131], v[144:147], v[60:63]
	v_mfma_f32_16x16x32_bf16 v[56:59], v[136:139], v[144:147], v[56:59]
	v_mfma_f32_16x16x32_bf16 v[44:47], v[128:131], v[170:173], v[44:47]
	v_mfma_f32_16x16x32_bf16 v[40:43], v[136:139], v[170:173], v[40:43]
	v_mfma_f32_16x16x32_bf16 v[28:31], v[128:131], v[178:181], v[28:31]
	v_mfma_f32_16x16x32_bf16 v[24:27], v[136:139], v[178:181], v[24:27]
	v_mfma_f32_16x16x32_bf16 v[12:15], v[128:131], v[196:199], v[12:15]
	v_mfma_f32_16x16x32_bf16 v[8:11], v[136:139], v[196:199], v[8:11]
	v_mfma_f32_16x16x32_bf16 v[60:63], v[132:135], v[148:151], v[60:63]
	v_mfma_f32_16x16x32_bf16 v[56:59], v[140:143], v[148:151], v[56:59]
	v_mfma_f32_16x16x32_bf16 v[44:47], v[132:135], v[174:177], v[44:47]
	v_mfma_f32_16x16x32_bf16 v[40:43], v[140:143], v[174:177], v[40:43]
	v_mfma_f32_16x16x32_bf16 v[28:31], v[132:135], v[182:185], v[28:31]
	v_mfma_f32_16x16x32_bf16 v[24:27], v[140:143], v[182:185], v[24:27]
	v_mfma_f32_16x16x32_bf16 v[12:15], v[132:135], v[200:203], v[12:15]
	v_mfma_f32_16x16x32_bf16 v[8:11], v[140:143], v[200:203], v[8:11]
	s_barrier
	s_add_u32 s24, s24, 0x100080
	s_addc_u32 s25, s25, 0
	s_add_i32 s26, s26, s31
	v_lshl_add_u64 v[128:129], s[24:25], 0, v[156:157]
	s_mov_b32 m0, s26
	s_nop 0
	global_load_lds_dwordx4 v[128:129], off
	v_lshl_add_u64 v[128:129], s[24:25], 0, v[160:161]
	s_add_i32 m0, s26, 0x2000
	s_nop 0
	global_load_lds_dwordx4 v[128:129], off
	s_waitcnt vmcnt(6)
	s_barrier
	v_mfma_f32_16x16x32_bf16 v[52:55], v[204:207], v[144:147], v[52:55]
	v_mfma_f32_16x16x32_bf16 v[48:51], v[212:215], v[144:147], v[48:51]
	v_mfma_f32_16x16x32_bf16 v[36:39], v[204:207], v[170:173], v[36:39]
	v_mfma_f32_16x16x32_bf16 v[32:35], v[212:215], v[170:173], v[32:35]
	v_mfma_f32_16x16x32_bf16 v[20:23], v[204:207], v[178:181], v[20:23]
	v_mfma_f32_16x16x32_bf16 v[16:19], v[212:215], v[178:181], v[16:19]
	v_mfma_f32_16x16x32_bf16 v[4:7], v[204:207], v[196:199], v[4:7]
	v_mfma_f32_16x16x32_bf16 v[0:3], v[212:215], v[196:199], v[0:3]
	v_mfma_f32_16x16x32_bf16 v[52:55], v[208:211], v[148:151], v[52:55]
	v_mfma_f32_16x16x32_bf16 v[48:51], v[216:219], v[148:151], v[48:51]
	v_mfma_f32_16x16x32_bf16 v[36:39], v[208:211], v[174:177], v[36:39]
	v_mfma_f32_16x16x32_bf16 v[32:35], v[216:219], v[174:177], v[32:35]
	v_mfma_f32_16x16x32_bf16 v[20:23], v[208:211], v[182:185], v[20:23]
	v_mfma_f32_16x16x32_bf16 v[16:19], v[216:219], v[182:185], v[16:19]
	v_mfma_f32_16x16x32_bf16 v[4:7], v[208:211], v[200:203], v[4:7]
	v_mfma_f32_16x16x32_bf16 v[0:3], v[216:219], v[200:203], v[0:3]
	s_add_i32 s48, s48, 2
	s_add_u32 s22, s22, 0x100
	s_addc_u32 s23, s23, 0
	s_add_u32 s46, s46, 0x100
	s_addc_u32 s47, s47, 0
	s_cmp_gt_u32 s48, 61
	s_barrier
	s_cbranch_scc0 .LBB0_844
; __device__ __forceinline__ unsigned pk2(float lo, float hi) { const f32x2 v = (f32x2){lo, hi}; const bf16x2_t b = __builtin_convertvector(v, bf16x2_t); return __builtin_bit_cast(unsigned, b); }
; __device__ __forceinline__ void unpack8(const u32x4 v, float* f) { f[0] = bf_lo(v.x); f[1] = bf_hi(v.x); f[2] = bf_lo(v.y); f[3] = bf_hi(v.y); f[4] = bf_lo(v.z); f[5] = bf_hi(v.z); f[6] = bf_lo(v.w); f[7] = bf_hi(v.w); }
;     __device__ __forceinline__ void operator()(const f32x4 (&acc)[2][2][4][2], const Unit& u, int wr, int wc, int fr, int fq, const float (&)[8]) const {
;         const int row0 = u.pm * BM + wr * 64 + fr, col0 = u.pn * BM + wc * 32 + 8 * fq;
; #pragma unroll
;         for (int ai = 0; ai < 2; ++ai) {
;             u32x4 bv[4][2];
; #pragma unroll
;             for (int m = 0; m < 4; ++m)
; #pragma unroll
;                 for (int bj = 0; bj < 2; ++bj) bv[m][bj] = *(const u32x4*)(xb + (size_t)(row0 + ai * HALF + m * 16) * DM + col0 + bj * HALF);
; #pragma unroll
;             for (int m = 0; m < 4; ++m) { const int row = row0 + ai * HALF + m * 16; const size_t ro = (size_t)row * DM + col0; float s = 0.f;
; #pragma unroll
;                 for (int bj = 0; bj < 2; ++bj) { float b8[8]; unpack8(bv[m][bj], b8);
;                     const f32x4 v0 = (f32x4){b8[0], b8[1], b8[2], b8[3]} + acc[ai][bj][m][0], v1 = (f32x4){b8[4], b8[5], b8[6], b8[7]} + acc[ai][bj][m][1];
;                     s += v0[0] * v0[0] + v0[1] * v0[1] + v0[2] * v0[2] + v0[3] * v0[3] + v1[0] * v1[0] + v1[1] * v1[1] + v1[2] * v1[2] + v1[3] * v1[3];
;                     if (LAST) { *(f32x4*)(out + ro + bj * HALF) = v0; *(f32x4*)(out + ro + bj * HALF + 4) = v1; }
;                     else { u32x4 w; w.x = pk2(v0[0], v0[1]); w.y = pk2(v0[2], v0[3]); w.z = pk2(v1[0], v1[1]); w.w = pk2(v1[2], v1[3]); *(u32x4*)(xb + ro + bj * HALF) = w; } }
;                 s += __shfl_xor(s, 16); s += __shfl_xor(s, 32);
;                 if (fq == 0) ss[(size_t)row * 16 + u.pn * 4 + wc] = s; }
	s_setprio 0
	v_lshl_or_b32 v170, s6, 8, v190
	v_lshl_add_u32 v172, s8, 8, v188
	v_ashrrev_i32_e32 v171, 31, v170
	v_lshlrev_b64 v[206:207], 1, v[170:171]
	v_ashrrev_i32_e32 v173, 31, v172
	v_lshl_add_u64 v[174:175], s[76:77], 0, v[206:207]
	v_lshlrev_b64 v[208:209], 11, v[172:173]
	v_lshl_add_u64 v[128:129], v[174:175], 0, v[208:209]
	global_load_dwordx4 v[198:201], v[128:129], off
	global_load_dwordx4 v[202:205], v[128:129], off offset:256
	v_or_b32_e32 v184, 16, v172
	v_or_b32_e32 v180, 32, v172
	v_or_b32_e32 v176, 48, v172
	v_ashrrev_i32_e32 v185, 31, v184
	v_ashrrev_i32_e32 v181, 31, v180
	v_ashrrev_i32_e32 v177, 31, v176
	v_lshlrev_b64 v[186:187], 11, v[184:185]
	v_lshlrev_b64 v[182:183], 11, v[180:181]
	v_lshlrev_b64 v[178:179], 11, v[176:177]
	v_lshl_add_u64 v[128:129], v[174:175], 0, v[186:187]
	v_lshl_add_u64 v[130:131], v[174:175], 0, v[182:183]
	v_lshl_add_u64 v[196:197], v[174:175], 0, v[178:179]
	global_load_dwordx4 v[148:151], v[128:129], off
	global_load_dwordx4 v[144:147], v[128:129], off offset:256
	global_load_dwordx4 v[140:143], v[130:131], off
	global_load_dwordx4 v[136:139], v[130:131], off offset:256
	global_load_dwordx4 v[132:135], v[196:197], off
	s_nop 0
	global_load_dwordx4 v[128:131], v[196:197], off offset:256
	v_add_u32_e32 v218, 0x80, v172
	v_ashrrev_i32_e32 v219, 31, v218
	v_lshlrev_b64 v[218:219], 11, v[218:219]
	v_lshl_add_u64 v[218:219], v[174:175], 0, v[218:219]
	global_load_dwordx4 v[220:223], v[218:219], off
	global_load_dwordx4 v[224:227], v[218:219], off offset:256
	v_add_u32_e32 v218, 0x90, v172
	v_ashrrev_i32_e32 v219, 31, v218
	v_lshlrev_b64 v[218:219], 11, v[218:219]
	v_lshl_add_u64 v[218:219], v[174:175], 0, v[218:219]
	global_load_dwordx4 v[228:231], v[218:219], off
	global_load_dwordx4 v[232:235], v[218:219], off offset:256
	v_add_u32_e32 v218, 0xa0, v172
	v_ashrrev_i32_e32 v219, 31, v218
	v_lshlrev_b64 v[218:219], 11, v[218:219]
	v_lshl_add_u64 v[218:219], v[174:175], 0, v[218:219]
	global_load_dwordx4 v[236:239], v[218:219], off
	global_load_dwordx4 v[240:243], v[218:219], off offset:256
	v_add_u32_e32 v218, 0xb0, v172
	v_ashrrev_i32_e32 v219, 31, v218
	v_lshlrev_b64 v[218:219], 11, v[218:219]
	v_lshl_add_u64 v[218:219], v[174:175], 0, v[218:219]
	global_load_dwordx4 v[244:247], v[218:219], off
	global_load_dwordx4 v[252:255], v[218:219], off offset:256
	v_and_b32_e32 v196, 64, v194
	v_xor_b32_e32 v195, 16, v194
	v_add_u32_e32 v196, 64, v196
	v_xor_b32_e32 v197, 32, v194
	v_cmp_lt_i32_e32 vcc, v195, v196
	s_waitcnt vmcnt(15)
	v_lshlrev_b32_e32 v210, 16, v198
	v_cndmask_b32_e32 v195, v194, v195, vcc
	v_cmp_lt_i32_e32 vcc, v197, v196
	v_and_b32_e32 v211, 0xffff0000, v198
	s_waitcnt vmcnt(14)
	v_lshlrev_b32_e32 v214, 16, v202
	v_and_b32_e32 v215, 0xffff0000, v202
	v_cndmask_b32_e32 v197, v194, v197, vcc
	v_lshlrev_b32_e32 v212, 16, v200
	v_and_b32_e32 v213, 0xffff0000, v200
	v_lshlrev_b32_e32 v200, 16, v201
	v_and_b32_e32 v201, 0xffff0000, v201
	v_lshlrev_b32_e32 v216, 16, v204
	v_and_b32_e32 v217, 0xffff0000, v204
	v_pk_add_f32 v[124:125], v[124:125], v[210:211]
	v_pk_add_f32 v[116:117], v[116:117], v[214:215]
	v_lshlrev_b32_e32 v196, 2, v195
	v_lshlrev_b32_e32 v195, 2, v197
	v_lshlrev_b32_e32 v198, 16, v199
	v_and_b32_e32 v199, 0xffff0000, v199
	v_lshlrev_b32_e32 v202, 16, v203
	v_and_b32_e32 v203, 0xffff0000, v203
	v_pk_add_f32 v[122:123], v[122:123], v[200:201]
	v_pk_add_f32 v[200:201], v[112:113], v[216:217]
	v_mul_f32_e32 v197, v125, v125
	v_cvt_pk_bf16_f32 v112, v124, v125
	v_mul_f32_e32 v125, v117, v117
	v_pk_add_f32 v[126:127], v[126:127], v[198:199]
	v_pk_add_f32 v[118:119], v[118:119], v[202:203]
	v_fmac_f32_e32 v197, v124, v124
	v_fmac_f32_e32 v125, v116, v116
	v_fmac_f32_e32 v197, v126, v126
	v_fmac_f32_e32 v125, v118, v118
	v_pk_add_f32 v[120:121], v[120:121], v[212:213]
	v_fmac_f32_e32 v197, v127, v127
	v_fmac_f32_e32 v125, v119, v119
	v_lshlrev_b32_e32 v204, 16, v205
	v_and_b32_e32 v205, 0xffff0000, v205
	v_fmac_f32_e32 v197, v120, v120
	v_fmac_f32_e32 v125, v200, v200
	v_pk_add_f32 v[198:199], v[114:115], v[204:205]
	v_fmac_f32_e32 v197, v121, v121
	v_fmac_f32_e32 v125, v201, v201
	v_fmac_f32_e32 v197, v122, v122
	v_fmac_f32_e32 v125, v198, v198
	v_fmac_f32_e32 v197, v123, v123
	v_fmac_f32_e32 v125, v199, v199
	v_cvt_pk_bf16_f32 v115, v122, v123
	v_add_f32_e32 v122, v197, v125
	ds_bpermute_b32 v123, v196, v122
	v_cvt_pk_bf16_f32 v114, v120, v121
	v_lshl_add_u64 v[120:121], s[76:77], 0, v[208:209]
	v_cvt_pk_bf16_f32 v113, v126, v127
	v_lshl_add_u64 v[120:121], v[120:121], 0, v[206:207]
	global_store_dwordx4 v[120:121], v[112:115], off
	s_waitcnt lgkmcnt(0)
	s_nop 0
	v_add_f32_e32 v112, v122, v123
	ds_bpermute_b32 v113, v195, v112
	v_cvt_pk_bf16_f32 v114, v116, v117
	v_cvt_pk_bf16_f32 v115, v118, v119
	v_cvt_pk_bf16_f32 v116, v200, v201
	v_cvt_pk_bf16_f32 v117, v198, v199
	global_store_dwordx4 v[120:121], v[114:117], off offset:256
	s_and_saveexec_b64 s[22:23], s[0:1]
	s_cbranch_execz .LBB0_847
	s_waitcnt lgkmcnt(0)
	v_add_f32_e32 v114, v112, v113
	s_lshl_b32 s24, s6, 2
	v_lshlrev_b64 v[112:113], 6, v[172:173]
	s_ashr_i32 s25, s24, 31
	v_lshl_add_u64 v[112:113], s[10:11], 0, v[112:113]
	v_lshl_add_u64 v[112:113], s[24:25], 2, v[112:113]
	s_lshl_b32 s8, s37, 2
	v_lshl_add_u64 v[112:113], v[112:113], 0, s[8:9]
	global_store_dword v[112:113], v114, off

; #define PG8_STAGE(bufoff, gbase, voff) do { _Pragma("unroll") for (int _i = 0; _i < 2; ++_i) \
;         __builtin_amdgcn_global_load_lds((const unsigned*)((const char*)(gbase) + (voff)[_i]), (LAS unsigned*)(lds + (bufoff) + ldsw + _i * 8192), 16, 0, 0); } while (0)
; #define PG8_LDA(dst, b, h) do { _Pragma("unroll") for (int m = 0; m < 4; ++m) _Pragma("unroll") for (int k = 0; k < 2; ++k) dst[m][k] = *(const LAS bf16x8*)(lds + PG8_SA(b, h) + aoff + m * 2048 + k * 1024); } while (0)
; #define PG8_LDB(dst, b, h) do { _Pragma("unroll") for (int n = 0; n < 2; ++n) _Pragma("unroll") for (int k = 0; k < 2; ++k) dst[n][k] = *(const LAS bf16x8*)(lds + PG8_SB(b, h) + boff + n * 2048 + k * 1024); } while (0)
; #define PG8_MMA(ai, bj, At, Bt) do { __builtin_amdgcn_s_setprio(1); _Pragma("unroll") for (int m = 0; m < 4; ++m) _Pragma("unroll") for (int n = 0; n < 2; ++n) _Pragma("unroll") for (int k = 0; k < 2; ++k) \
;         acc[ai][bj][m][n] = __builtin_amdgcn_mfma_f32_16x16x32_bf16(Bt[n][k], At[m][k], acc[ai][bj][m][n], 0, 0, 0); __builtin_amdgcn_s_setprio(0); } while (0)
; #define PG8_WAIT_L(n) asm volatile("s_waitcnt lgkmcnt(" #n ")" ::: "memory")
; #define PG8_BAR __builtin_amdgcn_s_barrier()
; #define PG8_SCHED __builtin_amdgcn_sched_barrier(0)
; template <class Epi>
; __device__ __forceinline__ void gemm_phase(LAS unsigned char* lds, const Gemm g, const StaticOrder& S, const Epi& E) {
;     ...
;         for (int t = 0; t < nt; t += 2) {
;             const bool last = (t == nt - 2);
;             const char* a1 = cA + (size_t)(t + 1) * kstep;
;             const char* a2 = last ? nA : cA + (size_t)(t + 2) * kstep; const char* b2 = last ? nB : cB + (size_t)(t + 2) * kstep;
;             const char* a3 = a2 + kstep; const char* b3 = b2 + kstep;
;             if (last) E.pre(cur, wr, fr, epre);
;             PG8_LDB(B0, 0, 0); PG8_SCHED; PG8_LDA(At, 0, 0); PG8_STAGE(PG8_SA(1, 1), a1 + hstepA, voffA);
;             PG8_WAIT_L(8); PG8_BAR; PG8_WAIT_L(0); PG8_MMA(0, 0, At, B0); PG8_BAR; PG8_SCHED;
;             PG8_LDB(B1, 0, 1); PG8_STAGE(PG8_SB(0, 0), b2, voffB);
;             PG8_BAR; PG8_WAIT_L(0); PG8_MMA(0, 1, At, B1); PG8_BAR;
;             PG8_LDA(At, 0, 1); PG8_STAGE(PG8_SA(0, 0), a2, voffA);
;             PG8_BAR; PG8_WAIT_L(0); PG8_MMA(1, 0, At, B0); PG8_BAR; PG8_SCHED;
.LBB0_922:
	ds_read_b128 v[146:149], v173
	ds_read_b128 v[154:157], v173 offset:1024
	ds_read_b128 v[158:161], v173 offset:2048
	ds_read_b128 v[162:165], v173 offset:3072
	s_add_u32 s22, s20, 0xfffc0080
	s_addc_u32 s23, s21, -1
	s_cmp_eq_u32 s47, 12
	s_cselect_b32 s25, s13, s23
	s_cselect_b32 s24, s43, s22
	s_cselect_b32 s23, s11, s46
	s_cselect_b32 s22, s44, s45
	v_lshl_add_u64 v[150:151], s[20:21], 0, v[138:139]
	s_add_i32 m0, s19, 0xc000
	ds_read_b128 v[166:169], v174
	ds_read_b128 v[178:181], v174 offset:1024
	ds_read_b128 v[182:185], v174 offset:2048
	ds_read_b128 v[186:189], v174 offset:3072
	ds_read_b128 v[190:193], v174 offset:4096
	ds_read_b128 v[194:197], v174 offset:5120
	ds_read_b128 v[198:201], v174 offset:6144
	ds_read_b128 v[202:205], v174 offset:7168
	global_load_lds_dwordx4 v[150:151], off
	v_lshl_add_u64 v[150:151], s[20:21], 0, v[140:141]
	s_add_i32 m0, s19, 0xe000
	s_nop 0
	global_load_lds_dwordx4 v[150:151], off
	s_waitcnt lgkmcnt(8)
	s_barrier
	s_waitcnt lgkmcnt(0)
	v_mfma_f32_16x16x32_bf16 v[124:127], v[146:149], v[166:169], v[124:127]
	v_mfma_f32_16x16x32_bf16 v[120:123], v[158:161], v[166:169], v[120:123]
	v_mfma_f32_16x16x32_bf16 v[112:115], v[146:149], v[182:185], v[112:115]
	v_mfma_f32_16x16x32_bf16 v[104:107], v[158:161], v[182:185], v[104:107]
	v_mfma_f32_16x16x32_bf16 v[92:95], v[146:149], v[190:193], v[92:95]
	v_mfma_f32_16x16x32_bf16 v[88:91], v[158:161], v[190:193], v[88:91]
	v_mfma_f32_16x16x32_bf16 v[80:83], v[146:149], v[198:201], v[80:83]
	v_mfma_f32_16x16x32_bf16 v[72:75], v[158:161], v[198:201], v[72:75]
	v_mfma_f32_16x16x32_bf16 v[124:127], v[154:157], v[178:181], v[124:127]
	v_mfma_f32_16x16x32_bf16 v[120:123], v[162:165], v[178:181], v[120:123]
	v_mfma_f32_16x16x32_bf16 v[112:115], v[154:157], v[186:189], v[112:115]
	v_mfma_f32_16x16x32_bf16 v[104:107], v[162:165], v[186:189], v[104:107]
	v_mfma_f32_16x16x32_bf16 v[92:95], v[154:157], v[194:197], v[92:95]
	v_mfma_f32_16x16x32_bf16 v[88:91], v[162:165], v[194:197], v[88:91]
	v_mfma_f32_16x16x32_bf16 v[80:83], v[154:157], v[202:205], v[80:83]
	v_mfma_f32_16x16x32_bf16 v[72:75], v[162:165], v[202:205], v[72:75]
	s_barrier
	s_add_i32 s48, s38, s27
	v_lshl_add_u64 v[150:151], s[22:23], 0, v[132:133]
	s_mov_b32 m0, s48
	ds_read_b128 v[206:209], v175
	ds_read_b128 v[210:213], v175 offset:1024
	ds_read_b128 v[214:217], v175 offset:2048
	ds_read_b128 v[218:221], v175 offset:3072
	global_load_lds_dwordx4 v[150:151], off
	v_lshl_add_u64 v[222:223], s[22:23], 0, v[128:129]
	s_add_i32 m0, s48, 0x2000
	s_nop 0
	global_load_lds_dwordx4 v[222:223], off
	s_barrier
	s_waitcnt lgkmcnt(0)
	v_mfma_f32_16x16x32_bf16 v[116:119], v[206:209], v[166:169], v[116:119]
	v_mfma_f32_16x16x32_bf16 v[108:111], v[214:217], v[166:169], v[108:111]
	v_mfma_f32_16x16x32_bf16 v[100:103], v[206:209], v[182:185], v[100:103]
	v_mfma_f32_16x16x32_bf16 v[96:99], v[214:217], v[182:185], v[96:99]
	v_mfma_f32_16x16x32_bf16 v[84:87], v[206:209], v[190:193], v[84:87]
	v_mfma_f32_16x16x32_bf16 v[76:79], v[214:217], v[190:193], v[76:79]
	v_mfma_f32_16x16x32_bf16 v[68:71], v[206:209], v[198:201], v[68:71]
	v_mfma_f32_16x16x32_bf16 v[64:67], v[214:217], v[198:201], v[64:67]
	v_mfma_f32_16x16x32_bf16 v[116:119], v[210:213], v[178:181], v[116:119]
	v_mfma_f32_16x16x32_bf16 v[108:111], v[218:221], v[178:181], v[108:111]
	v_mfma_f32_16x16x32_bf16 v[100:103], v[210:213], v[186:189], v[100:103]
	v_mfma_f32_16x16x32_bf16 v[96:99], v[218:221], v[186:189], v[96:99]
	v_mfma_f32_16x16x32_bf16 v[84:87], v[210:213], v[194:197], v[84:87]
	v_mfma_f32_16x16x32_bf16 v[76:79], v[218:221], v[194:197], v[76:79]
	v_mfma_f32_16x16x32_bf16 v[68:71], v[210:213], v[202:205], v[68:71]
	v_mfma_f32_16x16x32_bf16 v[64:67], v[218:221], v[202:205], v[64:67]
	s_mov_b32 m0, s19
	v_lshl_add_u64 v[224:225], s[24:25], 0, v[134:135]
	s_barrier
	ds_read_b128 v[166:169], v174 offset:16384
	ds_read_b128 v[178:181], v174 offset:17408
	ds_read_b128 v[182:185], v174 offset:18432
	ds_read_b128 v[186:189], v174 offset:19456
	ds_read_b128 v[190:193], v174 offset:20480
	ds_read_b128 v[194:197], v174 offset:21504
	ds_read_b128 v[198:201], v174 offset:22528
	ds_read_b128 v[202:205], v174 offset:23552
	global_load_lds_dwordx4 v[224:225], off
	v_lshl_add_u64 v[226:227], s[24:25], 0, v[130:131]
	s_mov_b32 m0, s30
	s_nop 0
	global_load_lds_dwordx4 v[226:227], off
	s_barrier
	s_waitcnt lgkmcnt(0)
	v_mfma_f32_16x16x32_bf16 v[60:63], v[146:149], v[166:169], v[60:63]
	v_mfma_f32_16x16x32_bf16 v[56:59], v[158:161], v[166:169], v[56:59]
	v_mfma_f32_16x16x32_bf16 v[48:51], v[146:149], v[182:185], v[48:51]
	v_mfma_f32_16x16x32_bf16 v[40:43], v[158:161], v[182:185], v[40:43]
	v_mfma_f32_16x16x32_bf16 v[32:35], v[146:149], v[190:193], v[32:35]
	v_mfma_f32_16x16x32_bf16 v[24:27], v[158:161], v[190:193], v[24:27]
	v_mfma_f32_16x16x32_bf16 v[16:19], v[146:149], v[198:201], v[16:19]
	v_mfma_f32_16x16x32_bf16 v[8:11], v[158:161], v[198:201], v[8:11]
	v_mfma_f32_16x16x32_bf16 v[60:63], v[154:157], v[178:181], v[60:63]
	v_mfma_f32_16x16x32_bf16 v[56:59], v[162:165], v[178:181], v[56:59]
	v_mfma_f32_16x16x32_bf16 v[48:51], v[154:157], v[186:189], v[48:51]
	v_mfma_f32_16x16x32_bf16 v[40:43], v[162:165], v[186:189], v[40:43]
	v_mfma_f32_16x16x32_bf16 v[32:35], v[154:157], v[194:197], v[32:35]
	v_mfma_f32_16x16x32_bf16 v[24:27], v[162:165], v[194:197], v[24:27]
	v_mfma_f32_16x16x32_bf16 v[16:19], v[154:157], v[202:205], v[16:19]
	v_mfma_f32_16x16x32_bf16 v[8:11], v[162:165], v[202:205], v[8:11]
	s_barrier
; #define PG8_STAGE(bufoff, gbase, voff) do { _Pragma("unroll") for (int _i = 0; _i < 2; ++_i) \
;         __builtin_amdgcn_global_load_lds((const unsigned*)((const char*)(gbase) + (voff)[_i]), (LAS unsigned*)(lds + (bufoff) + ldsw + _i * 8192), 16, 0, 0); } while (0)
; #define PG8_LDA(dst, b, h) do { _Pragma("unroll") for (int m = 0; m < 4; ++m) _Pragma("unroll") for (int k = 0; k < 2; ++k) dst[m][k] = *(const LAS bf16x8*)(lds + PG8_SA(b, h) + aoff + m * 2048 + k * 1024); } while (0)
; #define PG8_LDB(dst, b, h) do { _Pragma("unroll") for (int n = 0; n < 2; ++n) _Pragma("unroll") for (int k = 0; k < 2; ++k) dst[n][k] = *(const LAS bf16x8*)(lds + PG8_SB(b, h) + boff + n * 2048 + k * 1024); } while (0)
; #define PG8_MMA(ai, bj, At, Bt) do { __builtin_amdgcn_s_setprio(1); _Pragma("unroll") for (int m = 0; m < 4; ++m) _Pragma("unroll") for (int n = 0; n < 2; ++n) _Pragma("unroll") for (int k = 0; k < 2; ++k) \
;         acc[ai][bj][m][n] = __builtin_amdgcn_mfma_f32_16x16x32_bf16(Bt[n][k], At[m][k], acc[ai][bj][m][n], 0, 0, 0); __builtin_amdgcn_s_setprio(0); } while (0)
; #define PG8_WAIT_V(n) asm volatile("s_waitcnt vmcnt(" #n ")" ::: "memory")
; #define PG8_WAIT_L(n) asm volatile("s_waitcnt lgkmcnt(" #n ")" ::: "memory")
; #define PG8_BAR __builtin_amdgcn_s_barrier()
; #define PG8_SCHED __builtin_amdgcn_sched_barrier(0)
; template <class Epi>
; __device__ __forceinline__ void gemm_phase(LAS unsigned char* lds, const Gemm g, const StaticOrder& S, const Epi& E) {
;     ...
;             PG8_STAGE(PG8_SB(0, 1), b2 + hstepB, voffB);
;             PG8_WAIT_V(6); PG8_BAR; PG8_MMA(1, 1, At, B1); PG8_BAR;
;             PG8_LDB(B0, 1, 0); PG8_SCHED; PG8_LDA(At, 1, 0); PG8_STAGE(PG8_SA(0, 1), a2 + hstepA, voffA);
;             PG8_WAIT_L(8); PG8_BAR; PG8_WAIT_L(0); PG8_MMA(0, 0, At, B0); PG8_BAR; PG8_SCHED;
;             PG8_LDB(B1, 1, 1); PG8_STAGE(PG8_SB(1, 0), b3, voffB);
;             PG8_BAR; PG8_WAIT_L(0); PG8_MMA(0, 1, At, B1); PG8_BAR;
;             PG8_LDA(At, 1, 1); PG8_STAGE(PG8_SA(1, 0), a3, voffA);
	s_add_u32 s48, s22, 0x40000
	s_addc_u32 s49, s23, 0
	s_add_i32 s50, s39, s27
	v_lshl_add_u64 v[146:147], s[48:49], 0, v[132:133]
	s_mov_b32 m0, s50
	s_nop 0
	global_load_lds_dwordx4 v[146:147], off
	v_lshl_add_u64 v[146:147], s[48:49], 0, v[128:129]
	s_add_i32 m0, s50, 0x2000
	s_nop 0
	global_load_lds_dwordx4 v[146:147], off
	s_waitcnt vmcnt(6)
	s_barrier
	v_mfma_f32_16x16x32_bf16 v[52:55], v[206:209], v[166:169], v[52:55]
	v_mfma_f32_16x16x32_bf16 v[44:47], v[214:217], v[166:169], v[44:47]
	v_mfma_f32_16x16x32_bf16 v[36:39], v[206:209], v[182:185], v[36:39]
	v_mfma_f32_16x16x32_bf16 v[28:31], v[214:217], v[182:185], v[28:31]
	v_mfma_f32_16x16x32_bf16 v[20:23], v[206:209], v[190:193], v[20:23]
	v_mfma_f32_16x16x32_bf16 v[12:15], v[214:217], v[190:193], v[12:15]
	v_mfma_f32_16x16x32_bf16 v[4:7], v[206:209], v[198:201], v[4:7]
	v_mfma_f32_16x16x32_bf16 v[0:3], v[214:217], v[198:201], v[0:3]
	v_mfma_f32_16x16x32_bf16 v[52:55], v[210:213], v[178:181], v[52:55]
	v_mfma_f32_16x16x32_bf16 v[44:47], v[218:221], v[178:181], v[44:47]
	v_mfma_f32_16x16x32_bf16 v[36:39], v[210:213], v[186:189], v[36:39]
	v_mfma_f32_16x16x32_bf16 v[28:31], v[218:221], v[186:189], v[28:31]
	v_mfma_f32_16x16x32_bf16 v[20:23], v[210:213], v[194:197], v[20:23]
	v_mfma_f32_16x16x32_bf16 v[12:15], v[218:221], v[194:197], v[12:15]
	v_mfma_f32_16x16x32_bf16 v[4:7], v[210:213], v[202:205], v[4:7]
	v_mfma_f32_16x16x32_bf16 v[0:3], v[218:221], v[202:205], v[0:3]
	s_add_i32 s48, 0, 0x18000
	v_add_u32_e32 v162, s48, v171
	s_barrier
	ds_read_b128 v[146:149], v162
	ds_read_b128 v[154:157], v162 offset:1024
	ds_read_b128 v[158:161], v162 offset:2048
	ds_read_b128 v[162:165], v162 offset:3072
	s_add_u32 s24, s24, 0x40000
	s_addc_u32 s25, s25, 0
	s_mov_b32 m0, s31
	v_lshl_add_u64 v[206:207], s[24:25], 0, v[134:135]
	ds_read_b128 v[166:169], v174 offset:32768
	ds_read_b128 v[178:181], v174 offset:33792
	ds_read_b128 v[182:185], v174 offset:34816
	ds_read_b128 v[186:189], v174 offset:35840
	ds_read_b128 v[190:193], v174 offset:36864
	ds_read_b128 v[194:197], v174 offset:37888
	ds_read_b128 v[198:201], v174 offset:38912
	ds_read_b128 v[202:205], v174 offset:39936
	global_load_lds_dwordx4 v[206:207], off
	v_lshl_add_u64 v[206:207], s[24:25], 0, v[130:131]
	s_mov_b32 m0, s33
	s_nop 0
	global_load_lds_dwordx4 v[206:207], off
	s_waitcnt lgkmcnt(8)
	s_barrier
	s_waitcnt lgkmcnt(0)
	v_mfma_f32_16x16x32_bf16 v[124:127], v[146:149], v[166:169], v[124:127]
	v_mfma_f32_16x16x32_bf16 v[120:123], v[158:161], v[166:169], v[120:123]
	v_mfma_f32_16x16x32_bf16 v[112:115], v[146:149], v[182:185], v[112:115]
	v_mfma_f32_16x16x32_bf16 v[104:107], v[158:161], v[182:185], v[104:107]
	v_mfma_f32_16x16x32_bf16 v[92:95], v[146:149], v[190:193], v[92:95]
	v_mfma_f32_16x16x32_bf16 v[88:91], v[158:161], v[190:193], v[88:91]
	v_mfma_f32_16x16x32_bf16 v[80:83], v[146:149], v[198:201], v[80:83]
	v_mfma_f32_16x16x32_bf16 v[72:75], v[158:161], v[198:201], v[72:75]
	v_mfma_f32_16x16x32_bf16 v[124:127], v[154:157], v[178:181], v[124:127]
	v_mfma_f32_16x16x32_bf16 v[120:123], v[162:165], v[178:181], v[120:123]
	v_mfma_f32_16x16x32_bf16 v[112:115], v[154:157], v[186:189], v[112:115]
	v_mfma_f32_16x16x32_bf16 v[104:107], v[162:165], v[186:189], v[104:107]
	v_mfma_f32_16x16x32_bf16 v[92:95], v[154:157], v[194:197], v[92:95]
	v_mfma_f32_16x16x32_bf16 v[88:91], v[162:165], v[194:197], v[88:91]
	v_mfma_f32_16x16x32_bf16 v[80:83], v[154:157], v[202:205], v[80:83]
	v_mfma_f32_16x16x32_bf16 v[72:75], v[162:165], v[202:205], v[72:75]
	s_barrier
	s_add_i32 s24, 0, 0x1c000
	s_add_i32 s25, s48, s27
	v_add_u32_e32 v177, s24, v171
	v_lshl_add_u64 v[150:151], v[150:151], 0, s[4:5]
	s_mov_b32 m0, s25
	ds_read_b128 v[206:209], v177
	ds_read_b128 v[210:213], v177 offset:1024
	ds_read_b128 v[214:217], v177 offset:2048
	ds_read_b128 v[218:221], v177 offset:3072
	global_load_lds_dwordx4 v[150:151], off
	v_lshl_add_u64 v[150:151], v[222:223], 0, s[4:5]
	s_add_i32 m0, s25, 0x2000
	s_nop 0
	global_load_lds_dwordx4 v[150:151], off
	s_barrier
	s_waitcnt lgkmcnt(0)
	v_mfma_f32_16x16x32_bf16 v[116:119], v[206:209], v[166:169], v[116:119]
	v_mfma_f32_16x16x32_bf16 v[108:111], v[214:217], v[166:169], v[108:111]
	v_mfma_f32_16x16x32_bf16 v[100:103], v[206:209], v[182:185], v[100:103]
	v_mfma_f32_16x16x32_bf16 v[96:99], v[214:217], v[182:185], v[96:99]
	v_mfma_f32_16x16x32_bf16 v[84:87], v[206:209], v[190:193], v[84:87]
	v_mfma_f32_16x16x32_bf16 v[76:79], v[214:217], v[190:193], v[76:79]
	v_mfma_f32_16x16x32_bf16 v[68:71], v[206:209], v[198:201], v[68:71]
	v_mfma_f32_16x16x32_bf16 v[64:67], v[214:217], v[198:201], v[64:67]
	v_mfma_f32_16x16x32_bf16 v[116:119], v[210:213], v[178:181], v[116:119]
	v_mfma_f32_16x16x32_bf16 v[108:111], v[218:221], v[178:181], v[108:111]
	v_mfma_f32_16x16x32_bf16 v[100:103], v[210:213], v[186:189], v[100:103]
	v_mfma_f32_16x16x32_bf16 v[96:99], v[218:221], v[186:189], v[96:99]
	v_mfma_f32_16x16x32_bf16 v[84:87], v[210:213], v[194:197], v[84:87]
	v_mfma_f32_16x16x32_bf16 v[76:79], v[218:221], v[194:197], v[76:79]
	v_mfma_f32_16x16x32_bf16 v[68:71], v[210:213], v[202:205], v[68:71]
	v_mfma_f32_16x16x32_bf16 v[64:67], v[218:221], v[202:205], v[64:67]
	s_mov_b32 m0, s35
	v_lshl_add_u64 v[150:151], v[224:225], 0, s[4:5]
	s_barrier
	ds_read_b128 v[166:169], v174 offset:49152
	ds_read_b128 v[178:181], v174 offset:50176
	ds_read_b128 v[182:185], v174 offset:51200
	ds_read_b128 v[186:189], v174 offset:52224
	ds_read_b128 v[190:193], v174 offset:53248
	ds_read_b128 v[194:197], v174 offset:54272
	ds_read_b128 v[198:201], v174 offset:55296
	ds_read_b128 v[202:205], v174 offset:56320
	global_load_lds_dwordx4 v[150:151], off
	v_lshl_add_u64 v[150:151], v[226:227], 0, s[4:5]
	s_mov_b32 m0, s36
	s_nop 0
	global_load_lds_dwordx4 v[150:151], off
	s_barrier
; __device__ __forceinline__ unsigned pk2(float lo, float hi) { const f32x2 v = (f32x2){lo, hi}; const bf16x2_t b = __builtin_convertvector(v, bf16x2_t); return __builtin_bit_cast(unsigned, b); }
; #define PG8_STAGE(bufoff, gbase, voff) do { _Pragma("unroll") for (int _i = 0; _i < 2; ++_i) \
;         __builtin_amdgcn_global_load_lds((const unsigned*)((const char*)(gbase) + (voff)[_i]), (LAS unsigned*)(lds + (bufoff) + ldsw + _i * 8192), 16, 0, 0); } while (0)
; #define PG8_MMA(ai, bj, At, Bt) do { __builtin_amdgcn_s_setprio(1); _Pragma("unroll") for (int m = 0; m < 4; ++m) _Pragma("unroll") for (int n = 0; n < 2; ++n) _Pragma("unroll") for (int k = 0; k < 2; ++k) \
;         acc[ai][bj][m][n] = __builtin_amdgcn_mfma_f32_16x16x32_bf16(Bt[n][k], At[m][k], acc[ai][bj][m][n], 0, 0, 0); __builtin_amdgcn_s_setprio(0); } while (0)
; #define PG8_WAIT_V(n) asm volatile("s_waitcnt vmcnt(" #n ")" ::: "memory")
; #define PG8_WAIT_L(n) asm volatile("s_waitcnt lgkmcnt(" #n ")" ::: "memory")
;     __device__ __forceinline__ void operator()(const f32x4 (&acc)[2][2][4][2], const Unit& u, int wr, int wc, int fr, int fq, const float (&)[8]) const {
;     ...
;         const int col0 = u.pn * BM + wc * 32 + 8 * fq;
; #pragma unroll
;         for (int ai = 0; ai < 2; ++ai)
; #pragma unroll
;             for (int m = 0; m < 4; ++m) { const int row = row0 + ai * HALF + m * 16; const float rs = rsqrtf(ep[ai * 4 + m] * (1.0f / 1024.0f) + EPS);
;                 u16* rowp = O + (size_t)row * ldc + col0;
; #pragma unroll
;                 for (int bj = 0; bj < 2; ++bj) { f32x4 v0 = acc[ai][bj][m][0] * rs, v1 = acc[ai][bj][m][1] * rs;
;                     if (ACT == 1) {
; #pragma unroll
;                         for (int j = 0; j < 4; ++j) { const float a0 = fmaxf(v0[j], 0.f), a1 = fmaxf(v1[j], 0.f); v0[j] = a0 * a0; v1[j] = a1 * a1; } }
;                     u32x4 w; w.x = pk2(v0[0], v0[1]); w.y = pk2(v0[2], v0[3]); w.z = pk2(v1[0], v1[1]); w.w = pk2(v1[2], v1[3]);
;                     *(u32x4*)(rowp + bj * HALF) = w; } }
; template <class Epi>
; __device__ __forceinline__ void gemm_phase(LAS unsigned char* lds, const Gemm g, const StaticOrder& S, const Epi& E) {
;     ...
;             PG8_BAR; PG8_WAIT_L(0); PG8_MMA(1, 0, At, B0); PG8_BAR; PG8_SCHED;
;             PG8_STAGE(PG8_SB(1, 1), b3 + hstepB, voffB);
;             PG8_WAIT_V(6); PG8_BAR; PG8_MMA(1, 1, At, B1); PG8_BAR;
	s_waitcnt lgkmcnt(0)
	v_mfma_f32_16x16x32_bf16 v[60:63], v[146:149], v[166:169], v[60:63]
	v_mfma_f32_16x16x32_bf16 v[56:59], v[158:161], v[166:169], v[56:59]
	v_mfma_f32_16x16x32_bf16 v[48:51], v[146:149], v[182:185], v[48:51]
	v_mfma_f32_16x16x32_bf16 v[40:43], v[158:161], v[182:185], v[40:43]
	v_mfma_f32_16x16x32_bf16 v[32:35], v[146:149], v[190:193], v[32:35]
	v_mfma_f32_16x16x32_bf16 v[24:27], v[158:161], v[190:193], v[24:27]
	v_mfma_f32_16x16x32_bf16 v[16:19], v[146:149], v[198:201], v[16:19]
	v_mfma_f32_16x16x32_bf16 v[8:11], v[158:161], v[198:201], v[8:11]
	v_mfma_f32_16x16x32_bf16 v[60:63], v[154:157], v[178:181], v[60:63]
	v_mfma_f32_16x16x32_bf16 v[56:59], v[162:165], v[178:181], v[56:59]
	v_mfma_f32_16x16x32_bf16 v[48:51], v[154:157], v[186:189], v[48:51]
	v_mfma_f32_16x16x32_bf16 v[40:43], v[162:165], v[186:189], v[40:43]
	v_mfma_f32_16x16x32_bf16 v[32:35], v[154:157], v[194:197], v[32:35]
	v_mfma_f32_16x16x32_bf16 v[24:27], v[162:165], v[194:197], v[24:27]
	v_mfma_f32_16x16x32_bf16 v[16:19], v[154:157], v[202:205], v[16:19]
	v_mfma_f32_16x16x32_bf16 v[8:11], v[162:165], v[202:205], v[8:11]
	s_barrier
	s_add_u32 s22, s22, 0x40080
	s_addc_u32 s23, s23, 0
	s_add_i32 s24, s24, s27
	v_lshl_add_u64 v[146:147], s[22:23], 0, v[132:133]
	s_mov_b32 m0, s24
	s_nop 0
	global_load_lds_dwordx4 v[146:147], off
	v_lshl_add_u64 v[146:147], s[22:23], 0, v[128:129]
	s_add_i32 m0, s24, 0x2000
	s_nop 0
	global_load_lds_dwordx4 v[146:147], off
	s_waitcnt vmcnt(6)
	s_barrier
	v_mfma_f32_16x16x32_bf16 v[52:55], v[206:209], v[166:169], v[52:55]
	v_mfma_f32_16x16x32_bf16 v[44:47], v[214:217], v[166:169], v[44:47]
	v_mfma_f32_16x16x32_bf16 v[36:39], v[206:209], v[182:185], v[36:39]
	v_mfma_f32_16x16x32_bf16 v[28:31], v[214:217], v[182:185], v[28:31]
	v_mfma_f32_16x16x32_bf16 v[20:23], v[206:209], v[190:193], v[20:23]
	v_mfma_f32_16x16x32_bf16 v[12:15], v[214:217], v[190:193], v[12:15]
	v_mfma_f32_16x16x32_bf16 v[4:7], v[206:209], v[198:201], v[4:7]
	v_mfma_f32_16x16x32_bf16 v[0:3], v[214:217], v[198:201], v[0:3]
	v_mfma_f32_16x16x32_bf16 v[52:55], v[210:213], v[178:181], v[52:55]
	v_mfma_f32_16x16x32_bf16 v[44:47], v[218:221], v[178:181], v[44:47]
	v_mfma_f32_16x16x32_bf16 v[36:39], v[210:213], v[186:189], v[36:39]
	v_mfma_f32_16x16x32_bf16 v[28:31], v[218:221], v[186:189], v[28:31]
	v_mfma_f32_16x16x32_bf16 v[20:23], v[210:213], v[194:197], v[20:23]
	v_mfma_f32_16x16x32_bf16 v[12:15], v[218:221], v[194:197], v[12:15]
	v_mfma_f32_16x16x32_bf16 v[4:7], v[210:213], v[202:205], v[4:7]
	v_mfma_f32_16x16x32_bf16 v[0:3], v[218:221], v[202:205], v[0:3]
	s_add_i32 s47, s47, 2
	s_add_u32 s20, s20, 0x100
	s_addc_u32 s21, s21, 0
	s_add_u32 s45, s45, 0x100
	s_addc_u32 s46, s46, 0
	s_cmp_gt_u32 s47, 13
	s_barrier
	s_cbranch_scc0 .LBB0_922
	s_setprio 0
	s_bfe_u32 vcc_lo, s18, 0x20003
	s_lshl_b32 vcc_lo, vcc_lo, 10
	s_add_i32 vcc_lo, vcc_lo, 0x20010
	v_lshl_add_u32 v236, v170, 2, vcc_lo
	ds_read_b32 v228, v236
	ds_read_b32 v229, v236 offset:64
	ds_read_b32 v230, v236 offset:128
	ds_read_b32 v231, v236 offset:192
	ds_read_b32 v232, v236 offset:512
	ds_read_b32 v233, v236 offset:576
	ds_read_b32 v234, v236 offset:640
	ds_read_b32 v235, v236 offset:704
	s_waitcnt lgkmcnt(0)
	v_lshl_add_u32 v154, s18, 8, v170
	v_or_b32_e32 v206, 16, v154
	v_or_b32_e32 v168, 32, v154
	v_or_b32_e32 v162, 48, v154
	v_add_u32_e32 v160, 0x80, v154
	v_add_u32_e32 v156, 0x90, v154
	v_add_u32_e32 v150, 0xa0, v154
	v_add_u32_e32 v146, 0xb0, v154
	v_lshl_or_b32 v208, s42, 8, v172
	v_mov_b64_e32 v[148:149], s[96:97]
	v_ashrrev_i32_e32 v209, 31, v208
	v_mad_i64_i32 v[210:211], s[20:21], v154, s40, v[148:149]
	s_nop 0
	v_lshlrev_b64 v[154:155], 1, v[208:209]
	v_lshl_add_u64 v[208:209], v[210:211], 0, v[154:155]
	s_mov_b32 s42, s10
	s_mov_b32 s18, s12
	s_mov_b64 s[22:23], s[16:17]
	s_waitcnt vmcnt(8)
	s_waitcnt lgkmcnt(0)
	s_waitcnt lgkmcnt(0)
	v_mov_b32_e32 v178, v228
	v_pk_mul_f32 v[126:127], v[126:127], v[178:179] op_sel_hi:[1,0]
	v_pk_mul_f32 v[124:125], v[124:125], v[178:179] op_sel_hi:[1,0]
	v_pk_mul_f32 v[190:191], v[122:123], v[178:179] op_sel_hi:[1,0]
	v_pk_mul_f32 v[122:123], v[120:121], v[178:179] op_sel_hi:[1,0]
	v_cvt_pk_bf16_f32 v120, v124, v125
	v_cvt_pk_bf16_f32 v121, v126, v127
	v_cvt_pk_bf16_f32 v122, v122, v123
	v_cvt_pk_bf16_f32 v123, v190, v191
	v_pk_mul_f32 v[116:117], v[116:117], v[178:179] op_sel_hi:[1,0]
	global_store_dwordx4 v[208:209], v[120:123], off
	s_nop 0
	v_pk_mul_f32 v[118:119], v[118:119], v[178:179] op_sel_hi:[1,0]
	v_pk_mul_f32 v[120:121], v[110:111], v[178:179] op_sel_hi:[1,0]
	v_pk_mul_f32 v[110:111], v[108:109], v[178:179] op_sel_hi:[1,0]
	v_cvt_pk_bf16_f32 v108, v116, v117
	v_cvt_pk_bf16_f32 v109, v118, v119
	v_cvt_pk_bf16_f32 v110, v110, v111
	v_cvt_pk_bf16_f32 v111, v120, v121
	global_store_dwordx4 v[208:209], v[108:111], off offset:256
	s_nop 1
	v_mov_b32_e32 v108, v229
	v_mad_i64_i32 v[110:111], s[20:21], v206, s40, v[148:149]
	v_pk_mul_f32 v[114:115], v[114:115], v[108:109] op_sel_hi:[1,0]
	v_pk_mul_f32 v[112:113], v[112:113], v[108:109] op_sel_hi:[1,0]
	v_pk_mul_f32 v[116:117], v[106:107], v[108:109] op_sel_hi:[1,0]
	v_pk_mul_f32 v[106:107], v[104:105], v[108:109] op_sel_hi:[1,0]
	v_lshl_add_u64 v[110:111], v[110:111], 0, v[154:155]
	v_cvt_pk_bf16_f32 v104, v112, v113
	v_cvt_pk_bf16_f32 v105, v114, v115
	v_cvt_pk_bf16_f32 v106, v106, v107
	v_cvt_pk_bf16_f32 v107, v116, v117
	global_store_dwordx4 v[110:111], v[104:107], off
	v_pk_mul_f32 v[100:101], v[100:101], v[108:109] op_sel_hi:[1,0]
	v_pk_mul_f32 v[112:113], v[98:99], v[108:109] op_sel_hi:[1,0]
	v_pk_mul_f32 v[98:99], v[96:97], v[108:109] op_sel_hi:[1,0]
	v_cvt_pk_bf16_f32 v96, v100, v101
	v_pk_mul_f32 v[102:103], v[102:103], v[108:109] op_sel_hi:[1,0]
	v_cvt_pk_bf16_f32 v98, v98, v99
	s_waitcnt lgkmcnt(0)
; __device__ __forceinline__ unsigned pk2(float lo, float hi) { const f32x2 v = (f32x2){lo, hi}; const bf16x2_t b = __builtin_convertvector(v, bf16x2_t); return __builtin_bit_cast(unsigned, b); }
; #define PG8_WAIT_V(n) asm volatile("s_waitcnt vmcnt(" #n ")" ::: "memory")
; #define PG8_BAR __builtin_amdgcn_s_barrier()
;     __device__ __forceinline__ void operator()(const f32x4 (&acc)[2][2][4][2], const Unit& u, int wr, int wc, int fr, int fq, const float (&)[8]) const {
;     ...
;             for (int m = 0; m < 4; ++m) { const int row = row0 + ai * HALF + m * 16; const float rs = rsqrtf(ep[ai * 4 + m] * (1.0f / 1024.0f) + EPS);
;                 u16* rowp = O + (size_t)row * ldc + col0;
; #pragma unroll
;                 for (int bj = 0; bj < 2; ++bj) { f32x4 v0 = acc[ai][bj][m][0] * rs, v1 = acc[ai][bj][m][1] * rs;
;                     if (ACT == 1) {
; #pragma unroll
;                         for (int j = 0; j < 4; ++j) { const float a0 = fmaxf(v0[j], 0.f), a1 = fmaxf(v1[j], 0.f); v0[j] = a0 * a0; v1[j] = a1 * a1; } }
;                     u32x4 w; w.x = pk2(v0[0], v0[1]); w.y = pk2(v0[2], v0[3]); w.z = pk2(v1[0], v1[1]); w.w = pk2(v1[2], v1[3]);
;                     *(u32x4*)(rowp + bj * HALF) = w; } }
; template <class Epi>
; __device__ __forceinline__ void gemm_phase(LAS unsigned char* lds, const Gemm g, const StaticOrder& S, const Epi& E) {
;     ...
;         E(acc, cur, wr, wc, fr, fq, epre);
;         if (!has_next) break;
; #pragma unroll
;         for (int a = 0; a < 2; ++a)
; #pragma unroll
;             for (int b = 0; b < 2; ++b)
; #pragma unroll
;                 for (int m = 0; m < 4; ++m)
; #pragma unroll
;                     for (int n = 0; n < 2; ++n) acc[a][b][m][n] = (f32x4){0.f, 0.f, 0.f, 0.f};
;         cur = nxt; cA = nA; cB = nB; ++ui;
;     }
;     PG8_WAIT_V(0);
;     if (wr == 0) PG8_BAR;
	v_cvt_pk_bf16_f32 v97, v102, v103
	v_cvt_pk_bf16_f32 v99, v112, v113
	global_store_dwordx4 v[110:111], v[96:99], off offset:256
	s_nop 0
	s_waitcnt lgkmcnt(0)
	v_mad_i64_i32 v[98:99], s[20:21], v168, s40, v[148:149]
	v_lshl_add_u64 v[98:99], v[98:99], 0, v[154:155]
	v_mov_b32_e32 v100, v230
	v_pk_mul_f32 v[94:95], v[94:95], v[100:101] op_sel_hi:[1,0]
	v_pk_mul_f32 v[92:93], v[92:93], v[100:101] op_sel_hi:[1,0]
	v_pk_mul_f32 v[102:103], v[90:91], v[100:101] op_sel_hi:[1,0]
	v_pk_mul_f32 v[90:91], v[88:89], v[100:101] op_sel_hi:[1,0]
	v_cvt_pk_bf16_f32 v88, v92, v93
	v_cvt_pk_bf16_f32 v89, v94, v95
	v_cvt_pk_bf16_f32 v90, v90, v91
	v_cvt_pk_bf16_f32 v91, v102, v103
	v_pk_mul_f32 v[84:85], v[84:85], v[100:101] op_sel_hi:[1,0]
	global_store_dwordx4 v[98:99], v[88:91], off
	s_nop 0
	v_pk_mul_f32 v[86:87], v[86:87], v[100:101] op_sel_hi:[1,0]
	v_pk_mul_f32 v[88:89], v[78:79], v[100:101] op_sel_hi:[1,0]
	v_pk_mul_f32 v[78:79], v[76:77], v[100:101] op_sel_hi:[1,0]
	v_cvt_pk_bf16_f32 v76, v84, v85
	v_cvt_pk_bf16_f32 v77, v86, v87
	v_cvt_pk_bf16_f32 v78, v78, v79
	v_cvt_pk_bf16_f32 v79, v88, v89
	global_store_dwordx4 v[98:99], v[76:79], off offset:256
	s_nop 1
	v_mov_b32_e32 v76, v231
	v_mad_i64_i32 v[78:79], s[20:21], v162, s40, v[148:149]
	v_pk_mul_f32 v[82:83], v[82:83], v[76:77] op_sel_hi:[1,0]
	v_pk_mul_f32 v[80:81], v[80:81], v[76:77] op_sel_hi:[1,0]
	v_pk_mul_f32 v[84:85], v[74:75], v[76:77] op_sel_hi:[1,0]
	v_pk_mul_f32 v[74:75], v[72:73], v[76:77] op_sel_hi:[1,0]
	v_lshl_add_u64 v[78:79], v[78:79], 0, v[154:155]
	v_cvt_pk_bf16_f32 v72, v80, v81
	v_cvt_pk_bf16_f32 v73, v82, v83
	v_cvt_pk_bf16_f32 v74, v74, v75
	v_cvt_pk_bf16_f32 v75, v84, v85
	global_store_dwordx4 v[78:79], v[72:75], off
	v_pk_mul_f32 v[68:69], v[68:69], v[76:77] op_sel_hi:[1,0]
	v_pk_mul_f32 v[80:81], v[66:67], v[76:77] op_sel_hi:[1,0]
	v_pk_mul_f32 v[66:67], v[64:65], v[76:77] op_sel_hi:[1,0]
	v_cvt_pk_bf16_f32 v64, v68, v69
	v_pk_mul_f32 v[70:71], v[70:71], v[76:77] op_sel_hi:[1,0]
	v_cvt_pk_bf16_f32 v66, v66, v67
	s_waitcnt lgkmcnt(0)
	v_cvt_pk_bf16_f32 v65, v70, v71
	v_cvt_pk_bf16_f32 v67, v80, v81
	global_store_dwordx4 v[78:79], v[64:67], off offset:256
	s_waitcnt lgkmcnt(0)
	s_nop 0
	s_nop 0
	s_nop 0
	s_nop 1
	v_mad_i64_i32 v[66:67], s[20:21], v160, s40, v[148:149]
	v_lshl_add_u64 v[66:67], v[66:67], 0, v[154:155]
	v_mov_b32_e32 v68, v232
	v_pk_mul_f32 v[62:63], v[62:63], v[68:69] op_sel_hi:[1,0]
	v_pk_mul_f32 v[60:61], v[60:61], v[68:69] op_sel_hi:[1,0]
	v_pk_mul_f32 v[70:71], v[58:59], v[68:69] op_sel_hi:[1,0]
	v_pk_mul_f32 v[58:59], v[56:57], v[68:69] op_sel_hi:[1,0]
	v_cvt_pk_bf16_f32 v56, v60, v61
	v_cvt_pk_bf16_f32 v57, v62, v63
	v_cvt_pk_bf16_f32 v58, v58, v59
	v_cvt_pk_bf16_f32 v59, v70, v71
	v_pk_mul_f32 v[52:53], v[52:53], v[68:69] op_sel_hi:[1,0]
	global_store_dwordx4 v[66:67], v[56:59], off
	s_nop 0
	v_pk_mul_f32 v[54:55], v[54:55], v[68:69] op_sel_hi:[1,0]
	v_pk_mul_f32 v[56:57], v[46:47], v[68:69] op_sel_hi:[1,0]
	v_pk_mul_f32 v[46:47], v[44:45], v[68:69] op_sel_hi:[1,0]
	v_cvt_pk_bf16_f32 v44, v52, v53
	v_cvt_pk_bf16_f32 v45, v54, v55
	v_cvt_pk_bf16_f32 v46, v46, v47
	v_cvt_pk_bf16_f32 v47, v56, v57
	global_store_dwordx4 v[66:67], v[44:47], off offset:256
	s_nop 1
	v_mov_b32_e32 v44, v233
	v_mad_i64_i32 v[46:47], s[20:21], v156, s40, v[148:149]
	v_pk_mul_f32 v[50:51], v[50:51], v[44:45] op_sel_hi:[1,0]
	v_pk_mul_f32 v[48:49], v[48:49], v[44:45] op_sel_hi:[1,0]
	v_pk_mul_f32 v[52:53], v[42:43], v[44:45] op_sel_hi:[1,0]
	v_pk_mul_f32 v[42:43], v[40:41], v[44:45] op_sel_hi:[1,0]
	v_lshl_add_u64 v[46:47], v[46:47], 0, v[154:155]
	v_cvt_pk_bf16_f32 v40, v48, v49
	v_cvt_pk_bf16_f32 v41, v50, v51
	v_cvt_pk_bf16_f32 v42, v42, v43
	v_cvt_pk_bf16_f32 v43, v52, v53
	global_store_dwordx4 v[46:47], v[40:43], off
	v_pk_mul_f32 v[36:37], v[36:37], v[44:45] op_sel_hi:[1,0]
	v_pk_mul_f32 v[48:49], v[30:31], v[44:45] op_sel_hi:[1,0]
	v_pk_mul_f32 v[30:31], v[28:29], v[44:45] op_sel_hi:[1,0]
	v_cvt_pk_bf16_f32 v28, v36, v37
	v_pk_mul_f32 v[38:39], v[38:39], v[44:45] op_sel_hi:[1,0]
	v_cvt_pk_bf16_f32 v30, v30, v31
	s_waitcnt lgkmcnt(0)
	v_cvt_pk_bf16_f32 v29, v38, v39
	v_cvt_pk_bf16_f32 v31, v48, v49
	global_store_dwordx4 v[46:47], v[28:31], off offset:256
	s_waitcnt lgkmcnt(0)
	s_nop 0
	s_nop 0
	s_nop 0
	s_nop 1
	v_mad_i64_i32 v[30:31], s[20:21], v150, s40, v[148:149]
	v_lshl_add_u64 v[30:31], v[30:31], 0, v[154:155]
	v_mov_b32_e32 v36, v234
	v_pk_mul_f32 v[34:35], v[34:35], v[36:37] op_sel_hi:[1,0]
	v_pk_mul_f32 v[32:33], v[32:33], v[36:37] op_sel_hi:[1,0]
	v_pk_mul_f32 v[38:39], v[26:27], v[36:37] op_sel_hi:[1,0]
	v_pk_mul_f32 v[26:27], v[24:25], v[36:37] op_sel_hi:[1,0]
	v_cvt_pk_bf16_f32 v24, v32, v33
	v_cvt_pk_bf16_f32 v25, v34, v35
	v_cvt_pk_bf16_f32 v26, v26, v27
	v_cvt_pk_bf16_f32 v27, v38, v39
	v_pk_mul_f32 v[20:21], v[20:21], v[36:37] op_sel_hi:[1,0]
	global_store_dwordx4 v[30:31], v[24:27], off
	s_nop 0
	v_pk_mul_f32 v[22:23], v[22:23], v[36:37] op_sel_hi:[1,0]
	v_pk_mul_f32 v[24:25], v[14:15], v[36:37] op_sel_hi:[1,0]
	v_pk_mul_f32 v[14:15], v[12:13], v[36:37] op_sel_hi:[1,0]
	v_cvt_pk_bf16_f32 v12, v20, v21
	v_cvt_pk_bf16_f32 v13, v22, v23
	v_cvt_pk_bf16_f32 v14, v14, v15
	v_cvt_pk_bf16_f32 v15, v24, v25
	global_store_dwordx4 v[30:31], v[12:15], off offset:256
	s_nop 1
	v_mov_b32_e32 v12, v235
	v_mad_i64_i32 v[14:15], s[20:21], v146, s40, v[148:149]
	v_pk_mul_f32 v[18:19], v[18:19], v[12:13] op_sel_hi:[1,0]
	v_pk_mul_f32 v[16:17], v[16:17], v[12:13] op_sel_hi:[1,0]
	v_pk_mul_f32 v[20:21], v[10:11], v[12:13] op_sel_hi:[1,0]
	v_pk_mul_f32 v[10:11], v[8:9], v[12:13] op_sel_hi:[1,0]
	v_lshl_add_u64 v[14:15], v[14:15], 0, v[154:155]
	v_cvt_pk_bf16_f32 v8, v16, v17
	v_cvt_pk_bf16_f32 v9, v18, v19
	v_cvt_pk_bf16_f32 v10, v10, v11
	v_cvt_pk_bf16_f32 v11, v20, v21
	global_store_dwordx4 v[14:15], v[8:11], off
	v_pk_mul_f32 v[6:7], v[6:7], v[12:13] op_sel_hi:[1,0]
	v_pk_mul_f32 v[4:5], v[4:5], v[12:13] op_sel_hi:[1,0]
	v_pk_mul_f32 v[8:9], v[2:3], v[12:13] op_sel_hi:[1,0]
	v_pk_mul_f32 v[2:3], v[0:1], v[12:13] op_sel_hi:[1,0]
	v_cvt_pk_bf16_f32 v0, v4, v5
	v_cvt_pk_bf16_f32 v1, v6, v7
	v_cvt_pk_bf16_f32 v2, v2, v3
	v_cvt_pk_bf16_f32 v3, v8, v9
	s_and_b64 vcc, exec, s[0:1]
	s_mov_b64 s[20:21], s[14:15]
	global_store_dwordx4 v[14:15], v[0:3], off offset:256
	s_cbranch_vccz .LBB0_919
	s_waitcnt vmcnt(0)
	v_readlane_b32 s40, v251, 54
	s_cmpk_gt_u32 s7, 0xff
	v_readlane_b32 s41, v251, 55
	s_cbranch_scc1 .LBB0_926
	s_barrier

; #define PG8_STAGE(bufoff, gbase, voff) do { _Pragma("unroll") for (int _i = 0; _i < 2; ++_i) \
;         __builtin_amdgcn_global_load_lds((const unsigned*)((const char*)(gbase) + (voff)[_i]), (LAS unsigned*)(lds + (bufoff) + ldsw + _i * 8192), 16, 0, 0); } while (0)
; #define PG8_LDA(dst, b, h) do { _Pragma("unroll") for (int m = 0; m < 4; ++m) _Pragma("unroll") for (int k = 0; k < 2; ++k) dst[m][k] = *(const LAS bf16x8*)(lds + PG8_SA(b, h) + aoff + m * 2048 + k * 1024); } while (0)
; #define PG8_LDB(dst, b, h) do { _Pragma("unroll") for (int n = 0; n < 2; ++n) _Pragma("unroll") for (int k = 0; k < 2; ++k) dst[n][k] = *(const LAS bf16x8*)(lds + PG8_SB(b, h) + boff + n * 2048 + k * 1024); } while (0)
; #define PG8_MMA(ai, bj, At, Bt) do { __builtin_amdgcn_s_setprio(1); _Pragma("unroll") for (int m = 0; m < 4; ++m) _Pragma("unroll") for (int n = 0; n < 2; ++n) _Pragma("unroll") for (int k = 0; k < 2; ++k) \
;         acc[ai][bj][m][n] = __builtin_amdgcn_mfma_f32_16x16x32_bf16(Bt[n][k], At[m][k], acc[ai][bj][m][n], 0, 0, 0); __builtin_amdgcn_s_setprio(0); } while (0)
; #define PG8_WAIT_L(n) asm volatile("s_waitcnt lgkmcnt(" #n ")" ::: "memory")
; #define PG8_BAR __builtin_amdgcn_s_barrier()
; #define PG8_SCHED __builtin_amdgcn_sched_barrier(0)
; template <class Epi>
; __device__ __forceinline__ void gemm_phase(LAS unsigned char* lds, const Gemm g, const StaticOrder& S, const Epi& E) {
;     ...
;         for (int t = 0; t < nt; t += 2) {
;             const bool last = (t == nt - 2);
;             const char* a1 = cA + (size_t)(t + 1) * kstep;
;             const char* a2 = last ? nA : cA + (size_t)(t + 2) * kstep; const char* b2 = last ? nB : cB + (size_t)(t + 2) * kstep;
;             const char* a3 = a2 + kstep; const char* b3 = b2 + kstep;
;             if (last) E.pre(cur, wr, fr, epre);
;             PG8_LDB(B0, 0, 0); PG8_SCHED; PG8_LDA(At, 0, 0); PG8_STAGE(PG8_SA(1, 1), a1 + hstepA, voffA);
;             PG8_WAIT_L(8); PG8_BAR; PG8_WAIT_L(0); PG8_MMA(0, 0, At, B0); PG8_BAR; PG8_SCHED;
;             PG8_LDB(B1, 0, 1); PG8_STAGE(PG8_SB(0, 0), b2, voffB);
;             PG8_BAR; PG8_WAIT_L(0); PG8_MMA(0, 1, At, B1); PG8_BAR;
;             PG8_LDA(At, 0, 1); PG8_STAGE(PG8_SA(0, 0), a2, voffA);
;             PG8_BAR; PG8_WAIT_L(0); PG8_MMA(1, 0, At, B0); PG8_BAR; PG8_SCHED;
.LBB0_1118:
	ds_read_b128 v[128:131], v190
	ds_read_b128 v[132:135], v190 offset:1024
	ds_read_b128 v[136:139], v190 offset:2048
	ds_read_b128 v[140:143], v190 offset:3072
	s_add_u32 s22, s4, 0xffec0080
	s_addc_u32 s23, s5, -1
	s_cmp_eq_u32 s46, 12
	s_cselect_b32 s25, s19, s23
	s_cselect_b32 s24, s18, s22
	s_cselect_b32 s23, s17, s45
	s_cselect_b32 s22, s43, s44
	v_lshl_add_u64 v[186:187], s[4:5], 0, v[162:163]
	s_add_i32 m0, s9, 0xc000
	ds_read_b128 v[144:147], v191
	ds_read_b128 v[148:151], v191 offset:1024
	ds_read_b128 v[170:173], v191 offset:2048
	ds_read_b128 v[174:177], v191 offset:3072
	ds_read_b128 v[178:181], v191 offset:4096
	ds_read_b128 v[182:185], v191 offset:5120
	ds_read_b128 v[194:197], v191 offset:6144
	ds_read_b128 v[198:201], v191 offset:7168
	global_load_lds_dwordx4 v[186:187], off
	v_lshl_add_u64 v[186:187], s[4:5], 0, v[164:165]
	s_add_i32 m0, s9, 0xe000
	s_nop 0
	global_load_lds_dwordx4 v[186:187], off
	s_waitcnt lgkmcnt(8)
	s_barrier
	s_waitcnt lgkmcnt(0)
	v_mfma_f32_16x16x32_bf16 v[124:127], v[128:131], v[144:147], v[124:127]
	v_mfma_f32_16x16x32_bf16 v[120:123], v[136:139], v[144:147], v[120:123]
	v_mfma_f32_16x16x32_bf16 v[108:111], v[128:131], v[170:173], v[108:111]
	v_mfma_f32_16x16x32_bf16 v[104:107], v[136:139], v[170:173], v[104:107]
	v_mfma_f32_16x16x32_bf16 v[92:95], v[128:131], v[178:181], v[92:95]
	v_mfma_f32_16x16x32_bf16 v[88:91], v[136:139], v[178:181], v[88:91]
	v_mfma_f32_16x16x32_bf16 v[76:79], v[128:131], v[194:197], v[76:79]
	v_mfma_f32_16x16x32_bf16 v[72:75], v[136:139], v[194:197], v[72:75]
	v_mfma_f32_16x16x32_bf16 v[124:127], v[132:135], v[148:151], v[124:127]
	v_mfma_f32_16x16x32_bf16 v[120:123], v[140:143], v[148:151], v[120:123]
	v_mfma_f32_16x16x32_bf16 v[108:111], v[132:135], v[174:177], v[108:111]
	v_mfma_f32_16x16x32_bf16 v[104:107], v[140:143], v[174:177], v[104:107]
	v_mfma_f32_16x16x32_bf16 v[92:95], v[132:135], v[182:185], v[92:95]
	v_mfma_f32_16x16x32_bf16 v[88:91], v[140:143], v[182:185], v[88:91]
	v_mfma_f32_16x16x32_bf16 v[76:79], v[132:135], v[198:201], v[76:79]
	v_mfma_f32_16x16x32_bf16 v[72:75], v[140:143], v[198:201], v[72:75]
	s_barrier
	s_add_i32 s47, s40, s29
	v_lshl_add_u64 v[186:187], s[22:23], 0, v[156:157]
	s_mov_b32 m0, s47
	ds_read_b128 v[202:205], v192
	ds_read_b128 v[206:209], v192 offset:1024
	ds_read_b128 v[210:213], v192 offset:2048
	ds_read_b128 v[214:217], v192 offset:3072
	global_load_lds_dwordx4 v[186:187], off
	v_lshl_add_u64 v[218:219], s[22:23], 0, v[160:161]
	s_add_i32 m0, s47, 0x2000
	s_nop 0
	global_load_lds_dwordx4 v[218:219], off
	s_barrier
	s_waitcnt lgkmcnt(0)
	v_mfma_f32_16x16x32_bf16 v[116:119], v[202:205], v[144:147], v[116:119]
	v_mfma_f32_16x16x32_bf16 v[112:115], v[210:213], v[144:147], v[112:115]
	v_mfma_f32_16x16x32_bf16 v[100:103], v[202:205], v[170:173], v[100:103]
	v_mfma_f32_16x16x32_bf16 v[96:99], v[210:213], v[170:173], v[96:99]
	v_mfma_f32_16x16x32_bf16 v[84:87], v[202:205], v[178:181], v[84:87]
	v_mfma_f32_16x16x32_bf16 v[80:83], v[210:213], v[178:181], v[80:83]
	v_mfma_f32_16x16x32_bf16 v[68:71], v[202:205], v[194:197], v[68:71]
	v_mfma_f32_16x16x32_bf16 v[64:67], v[210:213], v[194:197], v[64:67]
	v_mfma_f32_16x16x32_bf16 v[116:119], v[206:209], v[148:151], v[116:119]
	v_mfma_f32_16x16x32_bf16 v[112:115], v[214:217], v[148:151], v[112:115]
	v_mfma_f32_16x16x32_bf16 v[100:103], v[206:209], v[174:177], v[100:103]
	v_mfma_f32_16x16x32_bf16 v[96:99], v[214:217], v[174:177], v[96:99]
	v_mfma_f32_16x16x32_bf16 v[84:87], v[206:209], v[182:185], v[84:87]
	v_mfma_f32_16x16x32_bf16 v[80:83], v[214:217], v[182:185], v[80:83]
	v_mfma_f32_16x16x32_bf16 v[68:71], v[206:209], v[198:201], v[68:71]
	v_mfma_f32_16x16x32_bf16 v[64:67], v[214:217], v[198:201], v[64:67]
	s_mov_b32 m0, s9
	v_lshl_add_u64 v[220:221], s[24:25], 0, v[154:155]
	s_barrier
	ds_read_b128 v[144:147], v191 offset:16384
	ds_read_b128 v[148:151], v191 offset:17408
	ds_read_b128 v[170:173], v191 offset:18432
	ds_read_b128 v[174:177], v191 offset:19456
	ds_read_b128 v[178:181], v191 offset:20480
	ds_read_b128 v[182:185], v191 offset:21504
	ds_read_b128 v[194:197], v191 offset:22528
	ds_read_b128 v[198:201], v191 offset:23552
	global_load_lds_dwordx4 v[220:221], off
	v_lshl_add_u64 v[222:223], s[24:25], 0, v[158:159]
	s_mov_b32 m0, s30
	s_nop 0
	global_load_lds_dwordx4 v[222:223], off
	s_barrier
	s_waitcnt lgkmcnt(0)
	v_mfma_f32_16x16x32_bf16 v[60:63], v[128:131], v[144:147], v[60:63]
	v_mfma_f32_16x16x32_bf16 v[56:59], v[136:139], v[144:147], v[56:59]
	v_mfma_f32_16x16x32_bf16 v[44:47], v[128:131], v[170:173], v[44:47]
	v_mfma_f32_16x16x32_bf16 v[40:43], v[136:139], v[170:173], v[40:43]
	v_mfma_f32_16x16x32_bf16 v[28:31], v[128:131], v[178:181], v[28:31]
	v_mfma_f32_16x16x32_bf16 v[24:27], v[136:139], v[178:181], v[24:27]
	v_mfma_f32_16x16x32_bf16 v[12:15], v[128:131], v[194:197], v[12:15]
	v_mfma_f32_16x16x32_bf16 v[8:11], v[136:139], v[194:197], v[8:11]
	v_mfma_f32_16x16x32_bf16 v[60:63], v[132:135], v[148:151], v[60:63]
	v_mfma_f32_16x16x32_bf16 v[56:59], v[140:143], v[148:151], v[56:59]
	v_mfma_f32_16x16x32_bf16 v[44:47], v[132:135], v[174:177], v[44:47]
	v_mfma_f32_16x16x32_bf16 v[40:43], v[140:143], v[174:177], v[40:43]
	v_mfma_f32_16x16x32_bf16 v[28:31], v[132:135], v[182:185], v[28:31]
	v_mfma_f32_16x16x32_bf16 v[24:27], v[140:143], v[182:185], v[24:27]
	v_mfma_f32_16x16x32_bf16 v[12:15], v[132:135], v[198:201], v[12:15]
	v_mfma_f32_16x16x32_bf16 v[8:11], v[140:143], v[198:201], v[8:11]
	s_barrier
; #define PG8_STAGE(bufoff, gbase, voff) do { _Pragma("unroll") for (int _i = 0; _i < 2; ++_i) \
;         __builtin_amdgcn_global_load_lds((const unsigned*)((const char*)(gbase) + (voff)[_i]), (LAS unsigned*)(lds + (bufoff) + ldsw + _i * 8192), 16, 0, 0); } while (0)
; #define PG8_LDA(dst, b, h) do { _Pragma("unroll") for (int m = 0; m < 4; ++m) _Pragma("unroll") for (int k = 0; k < 2; ++k) dst[m][k] = *(const LAS bf16x8*)(lds + PG8_SA(b, h) + aoff + m * 2048 + k * 1024); } while (0)
; #define PG8_LDB(dst, b, h) do { _Pragma("unroll") for (int n = 0; n < 2; ++n) _Pragma("unroll") for (int k = 0; k < 2; ++k) dst[n][k] = *(const LAS bf16x8*)(lds + PG8_SB(b, h) + boff + n * 2048 + k * 1024); } while (0)
; #define PG8_MMA(ai, bj, At, Bt) do { __builtin_amdgcn_s_setprio(1); _Pragma("unroll") for (int m = 0; m < 4; ++m) _Pragma("unroll") for (int n = 0; n < 2; ++n) _Pragma("unroll") for (int k = 0; k < 2; ++k) \
;         acc[ai][bj][m][n] = __builtin_amdgcn_mfma_f32_16x16x32_bf16(Bt[n][k], At[m][k], acc[ai][bj][m][n], 0, 0, 0); __builtin_amdgcn_s_setprio(0); } while (0)
; #define PG8_WAIT_V(n) asm volatile("s_waitcnt vmcnt(" #n ")" ::: "memory")
; #define PG8_WAIT_L(n) asm volatile("s_waitcnt lgkmcnt(" #n ")" ::: "memory")
; #define PG8_BAR __builtin_amdgcn_s_barrier()
; #define PG8_SCHED __builtin_amdgcn_sched_barrier(0)
; template <class Epi>
; __device__ __forceinline__ void gemm_phase(LAS unsigned char* lds, const Gemm g, const StaticOrder& S, const Epi& E) {
;     ...
;             PG8_STAGE(PG8_SB(0, 1), b2 + hstepB, voffB);
;             PG8_WAIT_V(6); PG8_BAR; PG8_MMA(1, 1, At, B1); PG8_BAR;
;             PG8_LDB(B0, 1, 0); PG8_SCHED; PG8_LDA(At, 1, 0); PG8_STAGE(PG8_SA(0, 1), a2 + hstepA, voffA);
;             PG8_WAIT_L(8); PG8_BAR; PG8_WAIT_L(0); PG8_MMA(0, 0, At, B0); PG8_BAR; PG8_SCHED;
;             PG8_LDB(B1, 1, 1); PG8_STAGE(PG8_SB(1, 0), b3, voffB);
;             PG8_BAR; PG8_WAIT_L(0); PG8_MMA(0, 1, At, B1); PG8_BAR;
;             PG8_LDA(At, 1, 1); PG8_STAGE(PG8_SA(1, 0), a3, voffA);
	s_add_u32 s48, s22, 0x40000
	s_addc_u32 s49, s23, 0
	s_add_i32 s47, s41, s29
	v_lshl_add_u64 v[128:129], s[48:49], 0, v[156:157]
	s_mov_b32 m0, s47
	s_nop 0
	global_load_lds_dwordx4 v[128:129], off
	v_lshl_add_u64 v[128:129], s[48:49], 0, v[160:161]
	s_add_i32 m0, s47, 0x2000
	s_nop 0
	global_load_lds_dwordx4 v[128:129], off
	s_waitcnt vmcnt(6)
	s_barrier
	v_mfma_f32_16x16x32_bf16 v[52:55], v[202:205], v[144:147], v[52:55]
	v_mfma_f32_16x16x32_bf16 v[48:51], v[210:213], v[144:147], v[48:51]
	v_mfma_f32_16x16x32_bf16 v[36:39], v[202:205], v[170:173], v[36:39]
	v_mfma_f32_16x16x32_bf16 v[32:35], v[210:213], v[170:173], v[32:35]
	v_mfma_f32_16x16x32_bf16 v[20:23], v[202:205], v[178:181], v[20:23]
	v_mfma_f32_16x16x32_bf16 v[16:19], v[210:213], v[178:181], v[16:19]
	v_mfma_f32_16x16x32_bf16 v[4:7], v[202:205], v[194:197], v[4:7]
	v_mfma_f32_16x16x32_bf16 v[0:3], v[210:213], v[194:197], v[0:3]
	v_mfma_f32_16x16x32_bf16 v[52:55], v[206:209], v[148:151], v[52:55]
	v_mfma_f32_16x16x32_bf16 v[48:51], v[214:217], v[148:151], v[48:51]
	v_mfma_f32_16x16x32_bf16 v[36:39], v[206:209], v[174:177], v[36:39]
	v_mfma_f32_16x16x32_bf16 v[32:35], v[214:217], v[174:177], v[32:35]
	v_mfma_f32_16x16x32_bf16 v[20:23], v[206:209], v[182:185], v[20:23]
	v_mfma_f32_16x16x32_bf16 v[16:19], v[214:217], v[182:185], v[16:19]
	v_mfma_f32_16x16x32_bf16 v[4:7], v[206:209], v[198:201], v[4:7]
	v_mfma_f32_16x16x32_bf16 v[0:3], v[214:217], v[198:201], v[0:3]
	s_add_i32 s47, 0, 0x18000
	v_add_u32_e32 v140, s47, v188
	s_barrier
	ds_read_b128 v[128:131], v140
	ds_read_b128 v[132:135], v140 offset:1024
	ds_read_b128 v[136:139], v140 offset:2048
	ds_read_b128 v[140:143], v140 offset:3072
	s_add_u32 s24, s24, 0x140000
	s_addc_u32 s25, s25, 0
	s_mov_b32 m0, s31
	v_lshl_add_u64 v[202:203], s[24:25], 0, v[154:155]
	ds_read_b128 v[144:147], v191 offset:32768
	ds_read_b128 v[148:151], v191 offset:33792
	ds_read_b128 v[170:173], v191 offset:34816
	ds_read_b128 v[174:177], v191 offset:35840
	ds_read_b128 v[178:181], v191 offset:36864
	ds_read_b128 v[182:185], v191 offset:37888
	ds_read_b128 v[194:197], v191 offset:38912
	ds_read_b128 v[198:201], v191 offset:39936
	global_load_lds_dwordx4 v[202:203], off
	v_lshl_add_u64 v[202:203], s[24:25], 0, v[158:159]
	s_mov_b32 m0, s34
	s_nop 0
	global_load_lds_dwordx4 v[202:203], off
	s_waitcnt lgkmcnt(8)
	s_barrier
	s_waitcnt lgkmcnt(0)
	v_mfma_f32_16x16x32_bf16 v[124:127], v[128:131], v[144:147], v[124:127]
	v_mfma_f32_16x16x32_bf16 v[120:123], v[136:139], v[144:147], v[120:123]
	v_mfma_f32_16x16x32_bf16 v[108:111], v[128:131], v[170:173], v[108:111]
	v_mfma_f32_16x16x32_bf16 v[104:107], v[136:139], v[170:173], v[104:107]
	v_mfma_f32_16x16x32_bf16 v[92:95], v[128:131], v[178:181], v[92:95]
	v_mfma_f32_16x16x32_bf16 v[88:91], v[136:139], v[178:181], v[88:91]
	v_mfma_f32_16x16x32_bf16 v[76:79], v[128:131], v[194:197], v[76:79]
	v_mfma_f32_16x16x32_bf16 v[72:75], v[136:139], v[194:197], v[72:75]
	v_mfma_f32_16x16x32_bf16 v[124:127], v[132:135], v[148:151], v[124:127]
	v_mfma_f32_16x16x32_bf16 v[120:123], v[140:143], v[148:151], v[120:123]
	v_mfma_f32_16x16x32_bf16 v[108:111], v[132:135], v[174:177], v[108:111]
	v_mfma_f32_16x16x32_bf16 v[104:107], v[140:143], v[174:177], v[104:107]
	v_mfma_f32_16x16x32_bf16 v[92:95], v[132:135], v[182:185], v[92:95]
	v_mfma_f32_16x16x32_bf16 v[88:91], v[140:143], v[182:185], v[88:91]
	v_mfma_f32_16x16x32_bf16 v[76:79], v[132:135], v[198:201], v[76:79]
	v_mfma_f32_16x16x32_bf16 v[72:75], v[140:143], v[198:201], v[72:75]
	s_barrier
	s_add_i32 s24, 0, 0x1c000
	s_add_i32 s25, s47, s29
	v_add_u32_e32 v214, s24, v188
	v_lshl_add_u64 v[186:187], v[186:187], 0, s[14:15]
	s_mov_b32 m0, s25
	ds_read_b128 v[202:205], v214
	ds_read_b128 v[206:209], v214 offset:1024
	ds_read_b128 v[210:213], v214 offset:2048
	ds_read_b128 v[214:217], v214 offset:3072
	global_load_lds_dwordx4 v[186:187], off
	v_lshl_add_u64 v[186:187], v[218:219], 0, s[14:15]
	s_add_i32 m0, s25, 0x2000
	s_nop 0
	global_load_lds_dwordx4 v[186:187], off
	s_barrier
	s_waitcnt lgkmcnt(0)
	v_mfma_f32_16x16x32_bf16 v[116:119], v[202:205], v[144:147], v[116:119]
	v_mfma_f32_16x16x32_bf16 v[112:115], v[210:213], v[144:147], v[112:115]
	v_mfma_f32_16x16x32_bf16 v[100:103], v[202:205], v[170:173], v[100:103]
	v_mfma_f32_16x16x32_bf16 v[96:99], v[210:213], v[170:173], v[96:99]
	v_mfma_f32_16x16x32_bf16 v[84:87], v[202:205], v[178:181], v[84:87]
	v_mfma_f32_16x16x32_bf16 v[80:83], v[210:213], v[178:181], v[80:83]
	v_mfma_f32_16x16x32_bf16 v[68:71], v[202:205], v[194:197], v[68:71]
	v_mfma_f32_16x16x32_bf16 v[64:67], v[210:213], v[194:197], v[64:67]
	v_mfma_f32_16x16x32_bf16 v[116:119], v[206:209], v[148:151], v[116:119]
	v_mfma_f32_16x16x32_bf16 v[112:115], v[214:217], v[148:151], v[112:115]
	v_mfma_f32_16x16x32_bf16 v[100:103], v[206:209], v[174:177], v[100:103]
	v_mfma_f32_16x16x32_bf16 v[96:99], v[214:217], v[174:177], v[96:99]
	v_mfma_f32_16x16x32_bf16 v[84:87], v[206:209], v[182:185], v[84:87]
	v_mfma_f32_16x16x32_bf16 v[80:83], v[214:217], v[182:185], v[80:83]
	v_mfma_f32_16x16x32_bf16 v[68:71], v[206:209], v[198:201], v[68:71]
	v_mfma_f32_16x16x32_bf16 v[64:67], v[214:217], v[198:201], v[64:67]
	s_mov_b32 m0, s36
	v_lshl_add_u64 v[186:187], v[220:221], 0, s[14:15]
	s_barrier
	ds_read_b128 v[144:147], v191 offset:49152
	ds_read_b128 v[148:151], v191 offset:50176
	ds_read_b128 v[170:173], v191 offset:51200
	ds_read_b128 v[174:177], v191 offset:52224
	ds_read_b128 v[178:181], v191 offset:53248
	ds_read_b128 v[182:185], v191 offset:54272
	ds_read_b128 v[194:197], v191 offset:55296
	ds_read_b128 v[198:201], v191 offset:56320
	global_load_lds_dwordx4 v[186:187], off
	v_lshl_add_u64 v[186:187], v[222:223], 0, s[14:15]
	s_mov_b32 m0, s37
	s_nop 0
	global_load_lds_dwordx4 v[186:187], off
	s_barrier
; #define PG8_STAGE(bufoff, gbase, voff) do { _Pragma("unroll") for (int _i = 0; _i < 2; ++_i) \
;         __builtin_amdgcn_global_load_lds((const unsigned*)((const char*)(gbase) + (voff)[_i]), (LAS unsigned*)(lds + (bufoff) + ldsw + _i * 8192), 16, 0, 0); } while (0)
; #define PG8_MMA(ai, bj, At, Bt) do { __builtin_amdgcn_s_setprio(1); _Pragma("unroll") for (int m = 0; m < 4; ++m) _Pragma("unroll") for (int n = 0; n < 2; ++n) _Pragma("unroll") for (int k = 0; k < 2; ++k) \
;         acc[ai][bj][m][n] = __builtin_amdgcn_mfma_f32_16x16x32_bf16(Bt[n][k], At[m][k], acc[ai][bj][m][n], 0, 0, 0); __builtin_amdgcn_s_setprio(0); } while (0)
; #define PG8_WAIT_V(n) asm volatile("s_waitcnt vmcnt(" #n ")" ::: "memory")
; #define PG8_WAIT_L(n) asm volatile("s_waitcnt lgkmcnt(" #n ")" ::: "memory")
; #define PG8_BAR __builtin_amdgcn_s_barrier()
; #define PG8_SCHED __builtin_amdgcn_sched_barrier(0)
; template <class Epi>
; __device__ __forceinline__ void gemm_phase(LAS unsigned char* lds, const Gemm g, const StaticOrder& S, const Epi& E) {
;     ...
;             PG8_BAR; PG8_WAIT_L(0); PG8_MMA(1, 0, At, B0); PG8_BAR; PG8_SCHED;
;             PG8_STAGE(PG8_SB(1, 1), b3 + hstepB, voffB);
;             PG8_WAIT_V(6); PG8_BAR; PG8_MMA(1, 1, At, B1); PG8_BAR;
;         }
	s_waitcnt lgkmcnt(0)
	v_mfma_f32_16x16x32_bf16 v[60:63], v[128:131], v[144:147], v[60:63]
	v_mfma_f32_16x16x32_bf16 v[56:59], v[136:139], v[144:147], v[56:59]
	v_mfma_f32_16x16x32_bf16 v[44:47], v[128:131], v[170:173], v[44:47]
	v_mfma_f32_16x16x32_bf16 v[40:43], v[136:139], v[170:173], v[40:43]
	v_mfma_f32_16x16x32_bf16 v[28:31], v[128:131], v[178:181], v[28:31]
	v_mfma_f32_16x16x32_bf16 v[24:27], v[136:139], v[178:181], v[24:27]
	v_mfma_f32_16x16x32_bf16 v[12:15], v[128:131], v[194:197], v[12:15]
	v_mfma_f32_16x16x32_bf16 v[8:11], v[136:139], v[194:197], v[8:11]
	v_mfma_f32_16x16x32_bf16 v[60:63], v[132:135], v[148:151], v[60:63]
	v_mfma_f32_16x16x32_bf16 v[56:59], v[140:143], v[148:151], v[56:59]
	v_mfma_f32_16x16x32_bf16 v[44:47], v[132:135], v[174:177], v[44:47]
	v_mfma_f32_16x16x32_bf16 v[40:43], v[140:143], v[174:177], v[40:43]
	v_mfma_f32_16x16x32_bf16 v[28:31], v[132:135], v[182:185], v[28:31]
	v_mfma_f32_16x16x32_bf16 v[24:27], v[140:143], v[182:185], v[24:27]
	v_mfma_f32_16x16x32_bf16 v[12:15], v[132:135], v[198:201], v[12:15]
	v_mfma_f32_16x16x32_bf16 v[8:11], v[140:143], v[198:201], v[8:11]
	s_barrier
	s_add_u32 s22, s22, 0x40080
	s_addc_u32 s23, s23, 0
	s_add_i32 s24, s24, s29
	v_lshl_add_u64 v[128:129], s[22:23], 0, v[156:157]
	s_mov_b32 m0, s24
	s_nop 0
	global_load_lds_dwordx4 v[128:129], off
	v_lshl_add_u64 v[128:129], s[22:23], 0, v[160:161]
	s_add_i32 m0, s24, 0x2000
	s_nop 0
	global_load_lds_dwordx4 v[128:129], off
	s_waitcnt vmcnt(6)
	s_barrier
	v_mfma_f32_16x16x32_bf16 v[52:55], v[202:205], v[144:147], v[52:55]
	v_mfma_f32_16x16x32_bf16 v[48:51], v[210:213], v[144:147], v[48:51]
	v_mfma_f32_16x16x32_bf16 v[36:39], v[202:205], v[170:173], v[36:39]
	v_mfma_f32_16x16x32_bf16 v[32:35], v[210:213], v[170:173], v[32:35]
	v_mfma_f32_16x16x32_bf16 v[20:23], v[202:205], v[178:181], v[20:23]
	v_mfma_f32_16x16x32_bf16 v[16:19], v[210:213], v[178:181], v[16:19]
	v_mfma_f32_16x16x32_bf16 v[4:7], v[202:205], v[194:197], v[4:7]
	v_mfma_f32_16x16x32_bf16 v[0:3], v[210:213], v[194:197], v[0:3]
	v_mfma_f32_16x16x32_bf16 v[52:55], v[206:209], v[148:151], v[52:55]
	v_mfma_f32_16x16x32_bf16 v[48:51], v[214:217], v[148:151], v[48:51]
	v_mfma_f32_16x16x32_bf16 v[36:39], v[206:209], v[174:177], v[36:39]
	v_mfma_f32_16x16x32_bf16 v[32:35], v[214:217], v[174:177], v[32:35]
	v_mfma_f32_16x16x32_bf16 v[20:23], v[206:209], v[182:185], v[20:23]
	v_mfma_f32_16x16x32_bf16 v[16:19], v[214:217], v[182:185], v[16:19]
	v_mfma_f32_16x16x32_bf16 v[4:7], v[206:209], v[198:201], v[4:7]
	v_mfma_f32_16x16x32_bf16 v[0:3], v[214:217], v[198:201], v[0:3]
	s_add_i32 s46, s46, 2
	s_add_u32 s4, s4, 0x100
	s_addc_u32 s5, s5, 0
	s_add_u32 s44, s44, 0x100
	s_addc_u32 s45, s45, 0
	s_cmp_gt_u32 s46, 13
	s_barrier
	s_cbranch_scc0 .LBB0_1118
; __device__ __forceinline__ unsigned pk2(float lo, float hi) { const f32x2 v = (f32x2){lo, hi}; const bf16x2_t b = __builtin_convertvector(v, bf16x2_t); return __builtin_bit_cast(unsigned, b); }
; __device__ __forceinline__ void unpack8(const u32x4 v, float* f) { f[0] = bf_lo(v.x); f[1] = bf_hi(v.x); f[2] = bf_lo(v.y); f[3] = bf_hi(v.y); f[4] = bf_lo(v.z); f[5] = bf_hi(v.z); f[6] = bf_lo(v.w); f[7] = bf_hi(v.w); }
;     __device__ __forceinline__ void operator()(const f32x4 (&acc)[2][2][4][2], const Unit& u, int wr, int wc, int fr, int fq, const float (&)[8]) const {
;         const int row0 = u.pm * BM + wr * 64 + fr, col0 = u.pn * BM + wc * 32 + 8 * fq;
; #pragma unroll
;         for (int ai = 0; ai < 2; ++ai) {
;             u32x4 bv[4][2];
; #pragma unroll
;             for (int m = 0; m < 4; ++m)
; #pragma unroll
;                 for (int bj = 0; bj < 2; ++bj) bv[m][bj] = *(const u32x4*)(xb + (size_t)(row0 + ai * HALF + m * 16) * DM + col0 + bj * HALF);
; #pragma unroll
;             for (int m = 0; m < 4; ++m) { const int row = row0 + ai * HALF + m * 16; const size_t ro = (size_t)row * DM + col0; float s = 0.f;
; #pragma unroll
;                 for (int bj = 0; bj < 2; ++bj) { float b8[8]; unpack8(bv[m][bj], b8);
;                     const f32x4 v0 = (f32x4){b8[0], b8[1], b8[2], b8[3]} + acc[ai][bj][m][0], v1 = (f32x4){b8[4], b8[5], b8[6], b8[7]} + acc[ai][bj][m][1];
;                     s += v0[0] * v0[0] + v0[1] * v0[1] + v0[2] * v0[2] + v0[3] * v0[3] + v1[0] * v1[0] + v1[1] * v1[1] + v1[2] * v1[2] + v1[3] * v1[3];
;                     if (LAST) { *(f32x4*)(out + ro + bj * HALF) = v0; *(f32x4*)(out + ro + bj * HALF + 4) = v1; }
;                     else { u32x4 w; w.x = pk2(v0[0], v0[1]); w.y = pk2(v0[2], v0[3]); w.z = pk2(v1[0], v1[1]); w.w = pk2(v1[2], v1[3]); *(u32x4*)(xb + ro + bj * HALF) = w; } }
;                 s += __shfl_xor(s, 16); s += __shfl_xor(s, 32);
;                 if (fq == 0) ss[(size_t)row * 16 + u.pn * 4 + wc] = s; }
	s_setprio 0
	v_lshl_or_b32 v170, s8, 8, v189
	v_lshl_add_u32 v172, s10, 8, v153
	v_ashrrev_i32_e32 v171, 31, v170
	v_lshlrev_b64 v[204:205], 1, v[170:171]
	v_ashrrev_i32_e32 v173, 31, v172
	v_lshl_add_u64 v[174:175], s[76:77], 0, v[204:205]
	v_lshlrev_b64 v[206:207], 11, v[172:173]
	v_lshl_add_u64 v[128:129], v[174:175], 0, v[206:207]
	global_load_dwordx4 v[196:199], v[128:129], off
	global_load_dwordx4 v[200:203], v[128:129], off offset:256
	v_or_b32_e32 v184, 16, v172
	v_or_b32_e32 v180, 32, v172
	v_or_b32_e32 v176, 48, v172
	v_ashrrev_i32_e32 v185, 31, v184
	v_ashrrev_i32_e32 v181, 31, v180
	v_ashrrev_i32_e32 v177, 31, v176
	v_lshlrev_b64 v[186:187], 11, v[184:185]
	v_lshlrev_b64 v[182:183], 11, v[180:181]
	v_lshlrev_b64 v[178:179], 11, v[176:177]
	v_lshl_add_u64 v[128:129], v[174:175], 0, v[186:187]
	v_lshl_add_u64 v[130:131], v[174:175], 0, v[182:183]
	v_lshl_add_u64 v[194:195], v[174:175], 0, v[178:179]
	global_load_dwordx4 v[148:151], v[128:129], off
	global_load_dwordx4 v[144:147], v[128:129], off offset:256
	global_load_dwordx4 v[140:143], v[130:131], off
	global_load_dwordx4 v[136:139], v[130:131], off offset:256
	global_load_dwordx4 v[132:135], v[194:195], off
	s_nop 0
	global_load_dwordx4 v[128:131], v[194:195], off offset:256
	v_add_u32_e32 v226, 0x80, v172
	v_ashrrev_i32_e32 v227, 31, v226
	v_lshlrev_b64 v[226:227], 11, v[226:227]
	v_lshl_add_u64 v[226:227], v[174:175], 0, v[226:227]
	global_load_dwordx4 v[216:219], v[226:227], off
	global_load_dwordx4 v[220:223], v[226:227], off offset:256
	v_add_u32_e32 v226, 0x90, v172
	v_ashrrev_i32_e32 v227, 31, v226
	v_lshlrev_b64 v[226:227], 11, v[226:227]
	v_lshl_add_u64 v[226:227], v[174:175], 0, v[226:227]
	global_load_dwordx4 v[228:231], v[226:227], off
	global_load_dwordx4 v[232:235], v[226:227], off offset:256
	v_add_u32_e32 v226, 0xa0, v172
	v_ashrrev_i32_e32 v227, 31, v226
	v_lshlrev_b64 v[226:227], 11, v[226:227]
	v_lshl_add_u64 v[226:227], v[174:175], 0, v[226:227]
	global_load_dwordx4 v[236:239], v[226:227], off
	global_load_dwordx4 v[240:243], v[226:227], off offset:256
	v_add_u32_e32 v226, 0xb0, v172
	v_ashrrev_i32_e32 v227, 31, v226
	v_lshlrev_b64 v[226:227], 11, v[226:227]
	v_lshl_add_u64 v[226:227], v[174:175], 0, v[226:227]
	global_load_dwordx4 v[244:247], v[226:227], off
	global_load_dwordx4 v[252:255], v[226:227], off offset:256
	v_and_b32_e32 v195, 64, v193
	v_xor_b32_e32 v194, 16, v193
	v_add_u32_e32 v195, 64, v195
	v_xor_b32_e32 v208, 32, v193
	v_cmp_lt_i32_e32 vcc, v194, v195
	s_waitcnt vmcnt(15)
	v_and_b32_e32 v209, 0xffff0000, v196
	v_cndmask_b32_e32 v194, v193, v194, vcc
	v_cmp_lt_i32_e32 vcc, v208, v195
	v_lshlrev_b32_e32 v195, 2, v194
	s_waitcnt vmcnt(14)
	v_lshlrev_b32_e32 v212, 16, v200
	v_cndmask_b32_e32 v208, v193, v208, vcc
	v_lshlrev_b32_e32 v194, 2, v208
	v_lshlrev_b32_e32 v208, 16, v196
	v_and_b32_e32 v213, 0xffff0000, v200
	v_lshlrev_b32_e32 v210, 16, v198
	v_and_b32_e32 v211, 0xffff0000, v198
	v_lshlrev_b32_e32 v198, 16, v199
	v_and_b32_e32 v199, 0xffff0000, v199
	v_lshlrev_b32_e32 v200, 16, v201
	v_and_b32_e32 v201, 0xffff0000, v201
	v_lshlrev_b32_e32 v214, 16, v202
	v_and_b32_e32 v215, 0xffff0000, v202
	v_pk_add_f32 v[124:125], v[124:125], v[208:209]
	v_pk_add_f32 v[116:117], v[116:117], v[212:213]
	v_lshlrev_b32_e32 v196, 16, v197
	v_and_b32_e32 v197, 0xffff0000, v197
	v_pk_add_f32 v[122:123], v[122:123], v[198:199]
	v_pk_add_f32 v[118:119], v[118:119], v[200:201]
	v_pk_add_f32 v[198:199], v[112:113], v[214:215]
	v_mul_f32_e32 v200, v125, v125
	v_cvt_pk_bf16_f32 v112, v124, v125
	v_mul_f32_e32 v125, v117, v117
	v_pk_add_f32 v[126:127], v[126:127], v[196:197]
	v_fmac_f32_e32 v200, v124, v124
	v_fmac_f32_e32 v125, v116, v116
	v_fmac_f32_e32 v200, v126, v126
	v_fmac_f32_e32 v125, v118, v118
	v_pk_add_f32 v[120:121], v[120:121], v[210:211]
	v_fmac_f32_e32 v200, v127, v127
	v_fmac_f32_e32 v125, v119, v119
	v_lshlrev_b32_e32 v202, 16, v203
	v_and_b32_e32 v203, 0xffff0000, v203
	v_fmac_f32_e32 v200, v120, v120
	v_fmac_f32_e32 v125, v198, v198
	v_pk_add_f32 v[196:197], v[114:115], v[202:203]
	v_fmac_f32_e32 v200, v121, v121
	v_fmac_f32_e32 v125, v199, v199
	v_fmac_f32_e32 v200, v122, v122
	v_fmac_f32_e32 v125, v196, v196
	v_fmac_f32_e32 v200, v123, v123
	v_fmac_f32_e32 v125, v197, v197
	v_cvt_pk_bf16_f32 v115, v122, v123
	v_add_f32_e32 v122, v200, v125
	ds_bpermute_b32 v123, v195, v122
	v_cvt_pk_bf16_f32 v114, v120, v121
	v_lshl_add_u64 v[120:121], s[76:77], 0, v[206:207]
	v_cvt_pk_bf16_f32 v113, v126, v127
	v_lshl_add_u64 v[120:121], v[120:121], 0, v[204:205]
	global_store_dwordx4 v[120:121], v[112:115], off
	s_waitcnt lgkmcnt(0)
	s_nop 0
	v_add_f32_e32 v112, v122, v123
	ds_bpermute_b32 v113, v194, v112
	v_cvt_pk_bf16_f32 v114, v116, v117
	v_cvt_pk_bf16_f32 v115, v118, v119
	v_cvt_pk_bf16_f32 v116, v198, v199
	v_cvt_pk_bf16_f32 v117, v196, v197
	global_store_dwordx4 v[120:121], v[114:117], off offset:256
	s_and_saveexec_b64 s[4:5], s[0:1]
	s_cbranch_execz .LBB0_1121
	s_waitcnt lgkmcnt(0)
	v_add_f32_e32 v114, v112, v113
	s_lshl_b32 s22, s8, 2
	v_lshlrev_b64 v[112:113], 6, v[172:173]
	s_ashr_i32 s23, s22, 31
	v_lshl_add_u64 v[112:113], s[12:13], 0, v[112:113]
	v_lshl_add_u64 v[112:113], s[22:23], 2, v[112:113]
	s_lshl_b32 s10, s35, 2
	v_lshl_add_u64 v[112:113], v[112:113], 0, s[10:11]
	global_store_dword v[112:113], v114, off

; #define PG8_STAGE(bufoff, gbase, voff) do { _Pragma("unroll") for (int _i = 0; _i < 2; ++_i) \
;         __builtin_amdgcn_global_load_lds((const unsigned*)((const char*)(gbase) + (voff)[_i]), (LAS unsigned*)(lds + (bufoff) + ldsw + _i * 8192), 16, 0, 0); } while (0)
; #define PG8_LDA(dst, b, h) do { _Pragma("unroll") for (int m = 0; m < 4; ++m) _Pragma("unroll") for (int k = 0; k < 2; ++k) dst[m][k] = *(const LAS bf16x8*)(lds + PG8_SA(b, h) + aoff + m * 2048 + k * 1024); } while (0)
; #define PG8_LDB(dst, b, h) do { _Pragma("unroll") for (int n = 0; n < 2; ++n) _Pragma("unroll") for (int k = 0; k < 2; ++k) dst[n][k] = *(const LAS bf16x8*)(lds + PG8_SB(b, h) + boff + n * 2048 + k * 1024); } while (0)
; #define PG8_MMA(ai, bj, At, Bt) do { __builtin_amdgcn_s_setprio(1); _Pragma("unroll") for (int m = 0; m < 4; ++m) _Pragma("unroll") for (int n = 0; n < 2; ++n) _Pragma("unroll") for (int k = 0; k < 2; ++k) \
;         acc[ai][bj][m][n] = __builtin_amdgcn_mfma_f32_16x16x32_bf16(Bt[n][k], At[m][k], acc[ai][bj][m][n], 0, 0, 0); __builtin_amdgcn_s_setprio(0); } while (0)
; #define PG8_WAIT_L(n) asm volatile("s_waitcnt lgkmcnt(" #n ")" ::: "memory")
; #define PG8_BAR __builtin_amdgcn_s_barrier()
; #define PG8_SCHED __builtin_amdgcn_sched_barrier(0)
; template <class Epi>
; __device__ __forceinline__ void gemm_phase(LAS unsigned char* lds, const Gemm g, const StaticOrder& S, const Epi& E) {
;     ...
;         for (int t = 0; t < nt; t += 2) {
;             const bool last = (t == nt - 2);
;             const char* a1 = cA + (size_t)(t + 1) * kstep;
;             const char* a2 = last ? nA : cA + (size_t)(t + 2) * kstep; const char* b2 = last ? nB : cB + (size_t)(t + 2) * kstep;
;             const char* a3 = a2 + kstep; const char* b3 = b2 + kstep;
;             if (last) E.pre(cur, wr, fr, epre);
;             PG8_LDB(B0, 0, 0); PG8_SCHED; PG8_LDA(At, 0, 0); PG8_STAGE(PG8_SA(1, 1), a1 + hstepA, voffA);
;             PG8_WAIT_L(8); PG8_BAR; PG8_WAIT_L(0); PG8_MMA(0, 0, At, B0); PG8_BAR; PG8_SCHED;
;             PG8_LDB(B1, 0, 1); PG8_STAGE(PG8_SB(0, 0), b2, voffB);
;             PG8_BAR; PG8_WAIT_L(0); PG8_MMA(0, 1, At, B1); PG8_BAR;
;             PG8_LDA(At, 0, 1); PG8_STAGE(PG8_SA(0, 0), a2, voffA);
;             PG8_BAR; PG8_WAIT_L(0); PG8_MMA(1, 0, At, B0); PG8_BAR; PG8_SCHED;
.LBB0_1204:
	ds_read_b128 v[146:149], v176
	ds_read_b128 v[154:157], v176 offset:1024
	ds_read_b128 v[158:161], v176 offset:2048
	ds_read_b128 v[162:165], v176 offset:3072
	s_add_u32 s22, s20, 0xfffc0080
	s_addc_u32 s23, s21, -1
	s_cmp_eq_u32 s45, 12
	s_cselect_b32 s25, s13, s23
	s_cselect_b32 s24, s41, s22
	s_cselect_b32 s23, s11, s44
	s_cselect_b32 s22, s42, s43
	v_lshl_add_u64 v[150:151], s[20:21], 0, v[138:139]
	s_add_i32 m0, s19, 0xc000
	ds_read_b128 v[166:169], v177
	ds_read_b128 v[170:173], v177 offset:1024
	ds_read_b128 v[180:183], v177 offset:2048
	ds_read_b128 v[184:187], v177 offset:3072
	ds_read_b128 v[188:191], v177 offset:4096
	ds_read_b128 v[192:195], v177 offset:5120
	ds_read_b128 v[196:199], v177 offset:6144
	ds_read_b128 v[200:203], v177 offset:7168
	global_load_lds_dwordx4 v[150:151], off
	v_lshl_add_u64 v[150:151], s[20:21], 0, v[140:141]
	s_add_i32 m0, s19, 0xe000
	s_nop 0
	global_load_lds_dwordx4 v[150:151], off
	s_waitcnt lgkmcnt(8)
	s_barrier
	s_waitcnt lgkmcnt(0)
	v_mfma_f32_16x16x32_bf16 v[124:127], v[146:149], v[166:169], v[124:127]
	v_mfma_f32_16x16x32_bf16 v[120:123], v[158:161], v[166:169], v[120:123]
	v_mfma_f32_16x16x32_bf16 v[108:111], v[146:149], v[180:183], v[108:111]
	v_mfma_f32_16x16x32_bf16 v[104:107], v[158:161], v[180:183], v[104:107]
	v_mfma_f32_16x16x32_bf16 v[92:95], v[146:149], v[188:191], v[92:95]
	v_mfma_f32_16x16x32_bf16 v[88:91], v[158:161], v[188:191], v[88:91]
	v_mfma_f32_16x16x32_bf16 v[76:79], v[146:149], v[196:199], v[76:79]
	v_mfma_f32_16x16x32_bf16 v[72:75], v[158:161], v[196:199], v[72:75]
	v_mfma_f32_16x16x32_bf16 v[124:127], v[154:157], v[170:173], v[124:127]
	v_mfma_f32_16x16x32_bf16 v[120:123], v[162:165], v[170:173], v[120:123]
	v_mfma_f32_16x16x32_bf16 v[108:111], v[154:157], v[184:187], v[108:111]
	v_mfma_f32_16x16x32_bf16 v[104:107], v[162:165], v[184:187], v[104:107]
	v_mfma_f32_16x16x32_bf16 v[92:95], v[154:157], v[192:195], v[92:95]
	v_mfma_f32_16x16x32_bf16 v[88:91], v[162:165], v[192:195], v[88:91]
	v_mfma_f32_16x16x32_bf16 v[76:79], v[154:157], v[200:203], v[76:79]
	v_mfma_f32_16x16x32_bf16 v[72:75], v[162:165], v[200:203], v[72:75]
	s_barrier
	s_add_i32 s46, s37, s28
	v_lshl_add_u64 v[150:151], s[22:23], 0, v[130:131]
	s_mov_b32 m0, s46
	ds_read_b128 v[204:207], v178
	ds_read_b128 v[208:211], v178 offset:1024
	ds_read_b128 v[212:215], v178 offset:2048
	ds_read_b128 v[216:219], v178 offset:3072
	global_load_lds_dwordx4 v[150:151], off
	v_lshl_add_u64 v[220:221], s[22:23], 0, v[134:135]
	s_add_i32 m0, s46, 0x2000
	s_nop 0
	global_load_lds_dwordx4 v[220:221], off
	s_barrier
	s_waitcnt lgkmcnt(0)
	v_mfma_f32_16x16x32_bf16 v[116:119], v[204:207], v[166:169], v[116:119]
	v_mfma_f32_16x16x32_bf16 v[112:115], v[212:215], v[166:169], v[112:115]
	v_mfma_f32_16x16x32_bf16 v[100:103], v[204:207], v[180:183], v[100:103]
	v_mfma_f32_16x16x32_bf16 v[96:99], v[212:215], v[180:183], v[96:99]
	v_mfma_f32_16x16x32_bf16 v[84:87], v[204:207], v[188:191], v[84:87]
	v_mfma_f32_16x16x32_bf16 v[80:83], v[212:215], v[188:191], v[80:83]
	v_mfma_f32_16x16x32_bf16 v[68:71], v[204:207], v[196:199], v[68:71]
	v_mfma_f32_16x16x32_bf16 v[64:67], v[212:215], v[196:199], v[64:67]
	v_mfma_f32_16x16x32_bf16 v[116:119], v[208:211], v[170:173], v[116:119]
	v_mfma_f32_16x16x32_bf16 v[112:115], v[216:219], v[170:173], v[112:115]
	v_mfma_f32_16x16x32_bf16 v[100:103], v[208:211], v[184:187], v[100:103]
	v_mfma_f32_16x16x32_bf16 v[96:99], v[216:219], v[184:187], v[96:99]
	v_mfma_f32_16x16x32_bf16 v[84:87], v[208:211], v[192:195], v[84:87]
	v_mfma_f32_16x16x32_bf16 v[80:83], v[216:219], v[192:195], v[80:83]
	v_mfma_f32_16x16x32_bf16 v[68:71], v[208:211], v[200:203], v[68:71]
	v_mfma_f32_16x16x32_bf16 v[64:67], v[216:219], v[200:203], v[64:67]
	s_mov_b32 m0, s19
	v_lshl_add_u64 v[222:223], s[24:25], 0, v[128:129]
	s_barrier
	ds_read_b128 v[166:169], v177 offset:16384
	ds_read_b128 v[170:173], v177 offset:17408
	ds_read_b128 v[180:183], v177 offset:18432
	ds_read_b128 v[184:187], v177 offset:19456
	ds_read_b128 v[188:191], v177 offset:20480
	ds_read_b128 v[192:195], v177 offset:21504
	ds_read_b128 v[196:199], v177 offset:22528
	ds_read_b128 v[200:203], v177 offset:23552
	global_load_lds_dwordx4 v[222:223], off
	v_lshl_add_u64 v[224:225], s[24:25], 0, v[132:133]
	s_mov_b32 m0, s29
	s_nop 0
	global_load_lds_dwordx4 v[224:225], off
	s_barrier
	s_waitcnt lgkmcnt(0)
	v_mfma_f32_16x16x32_bf16 v[60:63], v[146:149], v[166:169], v[60:63]
	v_mfma_f32_16x16x32_bf16 v[56:59], v[158:161], v[166:169], v[56:59]
	v_mfma_f32_16x16x32_bf16 v[44:47], v[146:149], v[180:183], v[44:47]
	v_mfma_f32_16x16x32_bf16 v[40:43], v[158:161], v[180:183], v[40:43]
	v_mfma_f32_16x16x32_bf16 v[28:31], v[146:149], v[188:191], v[28:31]
	v_mfma_f32_16x16x32_bf16 v[24:27], v[158:161], v[188:191], v[24:27]
	v_mfma_f32_16x16x32_bf16 v[12:15], v[146:149], v[196:199], v[12:15]
	v_mfma_f32_16x16x32_bf16 v[8:11], v[158:161], v[196:199], v[8:11]
	v_mfma_f32_16x16x32_bf16 v[60:63], v[154:157], v[170:173], v[60:63]
	v_mfma_f32_16x16x32_bf16 v[56:59], v[162:165], v[170:173], v[56:59]
	v_mfma_f32_16x16x32_bf16 v[44:47], v[154:157], v[184:187], v[44:47]
	v_mfma_f32_16x16x32_bf16 v[40:43], v[162:165], v[184:187], v[40:43]
	v_mfma_f32_16x16x32_bf16 v[28:31], v[154:157], v[192:195], v[28:31]
	v_mfma_f32_16x16x32_bf16 v[24:27], v[162:165], v[192:195], v[24:27]
	v_mfma_f32_16x16x32_bf16 v[12:15], v[154:157], v[200:203], v[12:15]
	v_mfma_f32_16x16x32_bf16 v[8:11], v[162:165], v[200:203], v[8:11]
	s_barrier
; #define PG8_STAGE(bufoff, gbase, voff) do { _Pragma("unroll") for (int _i = 0; _i < 2; ++_i) \
;         __builtin_amdgcn_global_load_lds((const unsigned*)((const char*)(gbase) + (voff)[_i]), (LAS unsigned*)(lds + (bufoff) + ldsw + _i * 8192), 16, 0, 0); } while (0)
; #define PG8_LDA(dst, b, h) do { _Pragma("unroll") for (int m = 0; m < 4; ++m) _Pragma("unroll") for (int k = 0; k < 2; ++k) dst[m][k] = *(const LAS bf16x8*)(lds + PG8_SA(b, h) + aoff + m * 2048 + k * 1024); } while (0)
; #define PG8_LDB(dst, b, h) do { _Pragma("unroll") for (int n = 0; n < 2; ++n) _Pragma("unroll") for (int k = 0; k < 2; ++k) dst[n][k] = *(const LAS bf16x8*)(lds + PG8_SB(b, h) + boff + n * 2048 + k * 1024); } while (0)
; #define PG8_MMA(ai, bj, At, Bt) do { __builtin_amdgcn_s_setprio(1); _Pragma("unroll") for (int m = 0; m < 4; ++m) _Pragma("unroll") for (int n = 0; n < 2; ++n) _Pragma("unroll") for (int k = 0; k < 2; ++k) \
;         acc[ai][bj][m][n] = __builtin_amdgcn_mfma_f32_16x16x32_bf16(Bt[n][k], At[m][k], acc[ai][bj][m][n], 0, 0, 0); __builtin_amdgcn_s_setprio(0); } while (0)
; #define PG8_WAIT_V(n) asm volatile("s_waitcnt vmcnt(" #n ")" ::: "memory")
; #define PG8_WAIT_L(n) asm volatile("s_waitcnt lgkmcnt(" #n ")" ::: "memory")
; #define PG8_BAR __builtin_amdgcn_s_barrier()
; #define PG8_SCHED __builtin_amdgcn_sched_barrier(0)
; template <class Epi>
; __device__ __forceinline__ void gemm_phase(LAS unsigned char* lds, const Gemm g, const StaticOrder& S, const Epi& E) {
;     ...
;             PG8_STAGE(PG8_SB(0, 1), b2 + hstepB, voffB);
;             PG8_WAIT_V(6); PG8_BAR; PG8_MMA(1, 1, At, B1); PG8_BAR;
;             PG8_LDB(B0, 1, 0); PG8_SCHED; PG8_LDA(At, 1, 0); PG8_STAGE(PG8_SA(0, 1), a2 + hstepA, voffA);
;             PG8_WAIT_L(8); PG8_BAR; PG8_WAIT_L(0); PG8_MMA(0, 0, At, B0); PG8_BAR; PG8_SCHED;
;             PG8_LDB(B1, 1, 1); PG8_STAGE(PG8_SB(1, 0), b3, voffB);
;             PG8_BAR; PG8_WAIT_L(0); PG8_MMA(0, 1, At, B1); PG8_BAR;
;             PG8_LDA(At, 1, 1); PG8_STAGE(PG8_SA(1, 0), a3, voffA);
	s_add_u32 s46, s22, 0x40000
	s_addc_u32 s47, s23, 0
	s_add_i32 s48, s38, s28
	v_lshl_add_u64 v[146:147], s[46:47], 0, v[130:131]
	s_mov_b32 m0, s48
	s_nop 0
	global_load_lds_dwordx4 v[146:147], off
	v_lshl_add_u64 v[146:147], s[46:47], 0, v[134:135]
	s_add_i32 m0, s48, 0x2000
	s_nop 0
	global_load_lds_dwordx4 v[146:147], off
	s_waitcnt vmcnt(6)
	s_barrier
	v_mfma_f32_16x16x32_bf16 v[52:55], v[204:207], v[166:169], v[52:55]
	v_mfma_f32_16x16x32_bf16 v[48:51], v[212:215], v[166:169], v[48:51]
	v_mfma_f32_16x16x32_bf16 v[36:39], v[204:207], v[180:183], v[36:39]
	v_mfma_f32_16x16x32_bf16 v[32:35], v[212:215], v[180:183], v[32:35]
	v_mfma_f32_16x16x32_bf16 v[20:23], v[204:207], v[188:191], v[20:23]
	v_mfma_f32_16x16x32_bf16 v[16:19], v[212:215], v[188:191], v[16:19]
	v_mfma_f32_16x16x32_bf16 v[4:7], v[204:207], v[196:199], v[4:7]
	v_mfma_f32_16x16x32_bf16 v[0:3], v[212:215], v[196:199], v[0:3]
	v_mfma_f32_16x16x32_bf16 v[52:55], v[208:211], v[170:173], v[52:55]
	v_mfma_f32_16x16x32_bf16 v[48:51], v[216:219], v[170:173], v[48:51]
	v_mfma_f32_16x16x32_bf16 v[36:39], v[208:211], v[184:187], v[36:39]
	v_mfma_f32_16x16x32_bf16 v[32:35], v[216:219], v[184:187], v[32:35]
	v_mfma_f32_16x16x32_bf16 v[20:23], v[208:211], v[192:195], v[20:23]
	v_mfma_f32_16x16x32_bf16 v[16:19], v[216:219], v[192:195], v[16:19]
	v_mfma_f32_16x16x32_bf16 v[4:7], v[208:211], v[200:203], v[4:7]
	v_mfma_f32_16x16x32_bf16 v[0:3], v[216:219], v[200:203], v[0:3]
	s_add_i32 s46, 0, 0x18000
	v_add_u32_e32 v162, s46, v174
	s_barrier
	ds_read_b128 v[146:149], v162
	ds_read_b128 v[154:157], v162 offset:1024
	ds_read_b128 v[158:161], v162 offset:2048
	ds_read_b128 v[162:165], v162 offset:3072
	s_add_u32 s24, s24, 0x40000
	s_addc_u32 s25, s25, 0
	s_mov_b32 m0, s30
	v_lshl_add_u64 v[204:205], s[24:25], 0, v[128:129]
	ds_read_b128 v[166:169], v177 offset:32768
	ds_read_b128 v[170:173], v177 offset:33792
	ds_read_b128 v[180:183], v177 offset:34816
	ds_read_b128 v[184:187], v177 offset:35840
	ds_read_b128 v[188:191], v177 offset:36864
	ds_read_b128 v[192:195], v177 offset:37888
	ds_read_b128 v[196:199], v177 offset:38912
	ds_read_b128 v[200:203], v177 offset:39936
	global_load_lds_dwordx4 v[204:205], off
	v_lshl_add_u64 v[204:205], s[24:25], 0, v[132:133]
	s_mov_b32 m0, s31
	s_nop 0
	global_load_lds_dwordx4 v[204:205], off
	s_waitcnt lgkmcnt(8)
	s_barrier
	s_waitcnt lgkmcnt(0)
	v_mfma_f32_16x16x32_bf16 v[124:127], v[146:149], v[166:169], v[124:127]
	v_mfma_f32_16x16x32_bf16 v[120:123], v[158:161], v[166:169], v[120:123]
	v_mfma_f32_16x16x32_bf16 v[108:111], v[146:149], v[180:183], v[108:111]
	v_mfma_f32_16x16x32_bf16 v[104:107], v[158:161], v[180:183], v[104:107]
	v_mfma_f32_16x16x32_bf16 v[92:95], v[146:149], v[188:191], v[92:95]
	v_mfma_f32_16x16x32_bf16 v[88:91], v[158:161], v[188:191], v[88:91]
	v_mfma_f32_16x16x32_bf16 v[76:79], v[146:149], v[196:199], v[76:79]
	v_mfma_f32_16x16x32_bf16 v[72:75], v[158:161], v[196:199], v[72:75]
	v_mfma_f32_16x16x32_bf16 v[124:127], v[154:157], v[170:173], v[124:127]
	v_mfma_f32_16x16x32_bf16 v[120:123], v[162:165], v[170:173], v[120:123]
	v_mfma_f32_16x16x32_bf16 v[108:111], v[154:157], v[184:187], v[108:111]
	v_mfma_f32_16x16x32_bf16 v[104:107], v[162:165], v[184:187], v[104:107]
	v_mfma_f32_16x16x32_bf16 v[92:95], v[154:157], v[192:195], v[92:95]
	v_mfma_f32_16x16x32_bf16 v[88:91], v[162:165], v[192:195], v[88:91]
	v_mfma_f32_16x16x32_bf16 v[76:79], v[154:157], v[200:203], v[76:79]
	v_mfma_f32_16x16x32_bf16 v[72:75], v[162:165], v[200:203], v[72:75]
	s_barrier
	s_add_i32 s24, 0, 0x1c000
	s_add_i32 s25, s46, s28
	v_add_u32_e32 v216, s24, v174
	v_lshl_add_u64 v[150:151], v[150:151], 0, s[4:5]
	s_mov_b32 m0, s25
	ds_read_b128 v[204:207], v216
	ds_read_b128 v[208:211], v216 offset:1024
	ds_read_b128 v[212:215], v216 offset:2048
	ds_read_b128 v[216:219], v216 offset:3072
	global_load_lds_dwordx4 v[150:151], off
	v_lshl_add_u64 v[150:151], v[220:221], 0, s[4:5]
	s_add_i32 m0, s25, 0x2000
	s_nop 0
	global_load_lds_dwordx4 v[150:151], off
	s_barrier
	s_waitcnt lgkmcnt(0)
	v_mfma_f32_16x16x32_bf16 v[116:119], v[204:207], v[166:169], v[116:119]
	v_mfma_f32_16x16x32_bf16 v[112:115], v[212:215], v[166:169], v[112:115]
	v_mfma_f32_16x16x32_bf16 v[100:103], v[204:207], v[180:183], v[100:103]
	v_mfma_f32_16x16x32_bf16 v[96:99], v[212:215], v[180:183], v[96:99]
	v_mfma_f32_16x16x32_bf16 v[84:87], v[204:207], v[188:191], v[84:87]
	v_mfma_f32_16x16x32_bf16 v[80:83], v[212:215], v[188:191], v[80:83]
	v_mfma_f32_16x16x32_bf16 v[68:71], v[204:207], v[196:199], v[68:71]
	v_mfma_f32_16x16x32_bf16 v[64:67], v[212:215], v[196:199], v[64:67]
	v_mfma_f32_16x16x32_bf16 v[116:119], v[208:211], v[170:173], v[116:119]
	v_mfma_f32_16x16x32_bf16 v[112:115], v[216:219], v[170:173], v[112:115]
	v_mfma_f32_16x16x32_bf16 v[100:103], v[208:211], v[184:187], v[100:103]
	v_mfma_f32_16x16x32_bf16 v[96:99], v[216:219], v[184:187], v[96:99]
	v_mfma_f32_16x16x32_bf16 v[84:87], v[208:211], v[192:195], v[84:87]
	v_mfma_f32_16x16x32_bf16 v[80:83], v[216:219], v[192:195], v[80:83]
	v_mfma_f32_16x16x32_bf16 v[68:71], v[208:211], v[200:203], v[68:71]
	v_mfma_f32_16x16x32_bf16 v[64:67], v[216:219], v[200:203], v[64:67]
	s_mov_b32 m0, s34
	v_lshl_add_u64 v[150:151], v[222:223], 0, s[4:5]
	s_barrier
	ds_read_b128 v[166:169], v177 offset:49152
	ds_read_b128 v[170:173], v177 offset:50176
	ds_read_b128 v[180:183], v177 offset:51200
	ds_read_b128 v[184:187], v177 offset:52224
	ds_read_b128 v[188:191], v177 offset:53248
	ds_read_b128 v[192:195], v177 offset:54272
	ds_read_b128 v[196:199], v177 offset:55296
	ds_read_b128 v[200:203], v177 offset:56320
	global_load_lds_dwordx4 v[150:151], off
	v_lshl_add_u64 v[150:151], v[224:225], 0, s[4:5]
	s_mov_b32 m0, s35
	s_nop 0
	global_load_lds_dwordx4 v[150:151], off
	s_barrier
; __device__ __forceinline__ unsigned pk2(float lo, float hi) { const f32x2 v = (f32x2){lo, hi}; const bf16x2_t b = __builtin_convertvector(v, bf16x2_t); return __builtin_bit_cast(unsigned, b); }
; #define PG8_STAGE(bufoff, gbase, voff) do { _Pragma("unroll") for (int _i = 0; _i < 2; ++_i) \
;         __builtin_amdgcn_global_load_lds((const unsigned*)((const char*)(gbase) + (voff)[_i]), (LAS unsigned*)(lds + (bufoff) + ldsw + _i * 8192), 16, 0, 0); } while (0)
; #define PG8_MMA(ai, bj, At, Bt) do { __builtin_amdgcn_s_setprio(1); _Pragma("unroll") for (int m = 0; m < 4; ++m) _Pragma("unroll") for (int n = 0; n < 2; ++n) _Pragma("unroll") for (int k = 0; k < 2; ++k) \
;         acc[ai][bj][m][n] = __builtin_amdgcn_mfma_f32_16x16x32_bf16(Bt[n][k], At[m][k], acc[ai][bj][m][n], 0, 0, 0); __builtin_amdgcn_s_setprio(0); } while (0)
; #define PG8_WAIT_V(n) asm volatile("s_waitcnt vmcnt(" #n ")" ::: "memory")
; #define PG8_WAIT_L(n) asm volatile("s_waitcnt lgkmcnt(" #n ")" ::: "memory")
;     __device__ __forceinline__ void operator()(const f32x4 (&acc)[2][2][4][2], const Unit& u, int wr, int wc, int fr, int fq, const float (&)[8]) const {
;     ...
;         const int col0 = u.pn * BM + wc * 32 + 8 * fq;
; #pragma unroll
;         for (int ai = 0; ai < 2; ++ai)
; #pragma unroll
;             for (int m = 0; m < 4; ++m) { const int row = row0 + ai * HALF + m * 16; const float rs = rsqrtf(ep[ai * 4 + m] * (1.0f / 1024.0f) + EPS);
;                 u16* rowp = O + (size_t)row * ldc + col0;
; #pragma unroll
;                 for (int bj = 0; bj < 2; ++bj) { f32x4 v0 = acc[ai][bj][m][0] * rs, v1 = acc[ai][bj][m][1] * rs;
;                     if (ACT == 1) {
; #pragma unroll
;                         for (int j = 0; j < 4; ++j) { const float a0 = fmaxf(v0[j], 0.f), a1 = fmaxf(v1[j], 0.f); v0[j] = a0 * a0; v1[j] = a1 * a1; } }
;                     u32x4 w; w.x = pk2(v0[0], v0[1]); w.y = pk2(v0[2], v0[3]); w.z = pk2(v1[0], v1[1]); w.w = pk2(v1[2], v1[3]);
;                     *(u32x4*)(rowp + bj * HALF) = w; } }
; template <class Epi>
; __device__ __forceinline__ void gemm_phase(LAS unsigned char* lds, const Gemm g, const StaticOrder& S, const Epi& E) {
;     ...
;             PG8_BAR; PG8_WAIT_L(0); PG8_MMA(1, 0, At, B0); PG8_BAR; PG8_SCHED;
;             PG8_STAGE(PG8_SB(1, 1), b3 + hstepB, voffB);
;             PG8_WAIT_V(6); PG8_BAR; PG8_MMA(1, 1, At, B1); PG8_BAR;
	s_waitcnt lgkmcnt(0)
	v_mfma_f32_16x16x32_bf16 v[60:63], v[146:149], v[166:169], v[60:63]
	v_mfma_f32_16x16x32_bf16 v[56:59], v[158:161], v[166:169], v[56:59]
	v_mfma_f32_16x16x32_bf16 v[44:47], v[146:149], v[180:183], v[44:47]
	v_mfma_f32_16x16x32_bf16 v[40:43], v[158:161], v[180:183], v[40:43]
	v_mfma_f32_16x16x32_bf16 v[28:31], v[146:149], v[188:191], v[28:31]
	v_mfma_f32_16x16x32_bf16 v[24:27], v[158:161], v[188:191], v[24:27]
	v_mfma_f32_16x16x32_bf16 v[12:15], v[146:149], v[196:199], v[12:15]
	v_mfma_f32_16x16x32_bf16 v[8:11], v[158:161], v[196:199], v[8:11]
	v_mfma_f32_16x16x32_bf16 v[60:63], v[154:157], v[170:173], v[60:63]
	v_mfma_f32_16x16x32_bf16 v[56:59], v[162:165], v[170:173], v[56:59]
	v_mfma_f32_16x16x32_bf16 v[44:47], v[154:157], v[184:187], v[44:47]
	v_mfma_f32_16x16x32_bf16 v[40:43], v[162:165], v[184:187], v[40:43]
	v_mfma_f32_16x16x32_bf16 v[28:31], v[154:157], v[192:195], v[28:31]
	v_mfma_f32_16x16x32_bf16 v[24:27], v[162:165], v[192:195], v[24:27]
	v_mfma_f32_16x16x32_bf16 v[12:15], v[154:157], v[200:203], v[12:15]
	v_mfma_f32_16x16x32_bf16 v[8:11], v[162:165], v[200:203], v[8:11]
	s_barrier
	s_add_u32 s22, s22, 0x40080
	s_addc_u32 s23, s23, 0
	s_add_i32 s24, s24, s28
	v_lshl_add_u64 v[146:147], s[22:23], 0, v[130:131]
	s_mov_b32 m0, s24
	s_nop 0
	global_load_lds_dwordx4 v[146:147], off
	v_lshl_add_u64 v[146:147], s[22:23], 0, v[134:135]
	s_add_i32 m0, s24, 0x2000
	s_nop 0
	global_load_lds_dwordx4 v[146:147], off
	s_waitcnt vmcnt(6)
	s_barrier
	v_mfma_f32_16x16x32_bf16 v[52:55], v[204:207], v[166:169], v[52:55]
	v_mfma_f32_16x16x32_bf16 v[48:51], v[212:215], v[166:169], v[48:51]
	v_mfma_f32_16x16x32_bf16 v[36:39], v[204:207], v[180:183], v[36:39]
	v_mfma_f32_16x16x32_bf16 v[32:35], v[212:215], v[180:183], v[32:35]
	v_mfma_f32_16x16x32_bf16 v[20:23], v[204:207], v[188:191], v[20:23]
	v_mfma_f32_16x16x32_bf16 v[16:19], v[212:215], v[188:191], v[16:19]
	v_mfma_f32_16x16x32_bf16 v[4:7], v[204:207], v[196:199], v[4:7]
	v_mfma_f32_16x16x32_bf16 v[0:3], v[212:215], v[196:199], v[0:3]
	v_mfma_f32_16x16x32_bf16 v[52:55], v[208:211], v[170:173], v[52:55]
	v_mfma_f32_16x16x32_bf16 v[48:51], v[216:219], v[170:173], v[48:51]
	v_mfma_f32_16x16x32_bf16 v[36:39], v[208:211], v[184:187], v[36:39]
	v_mfma_f32_16x16x32_bf16 v[32:35], v[216:219], v[184:187], v[32:35]
	v_mfma_f32_16x16x32_bf16 v[20:23], v[208:211], v[192:195], v[20:23]
	v_mfma_f32_16x16x32_bf16 v[16:19], v[216:219], v[192:195], v[16:19]
	v_mfma_f32_16x16x32_bf16 v[4:7], v[208:211], v[200:203], v[4:7]
	v_mfma_f32_16x16x32_bf16 v[0:3], v[216:219], v[200:203], v[0:3]
	s_add_i32 s45, s45, 2
	s_add_u32 s20, s20, 0x100
	s_addc_u32 s21, s21, 0
	s_add_u32 s43, s43, 0x100
	s_addc_u32 s44, s44, 0
	s_cmp_gt_u32 s45, 13
	s_barrier
	s_cbranch_scc0 .LBB0_1204
	s_setprio 0
	s_bfe_u32 vcc_lo, s18, 0x20003
	s_lshl_b32 vcc_lo, vcc_lo, 10
	s_add_i32 vcc_lo, vcc_lo, 0x20010
	v_lshl_add_u32 v236, v153, 2, vcc_lo
	ds_read_b32 v228, v236
	ds_read_b32 v229, v236 offset:64
	ds_read_b32 v230, v236 offset:128
	ds_read_b32 v231, v236 offset:192
	ds_read_b32 v232, v236 offset:512
	ds_read_b32 v233, v236 offset:576
	ds_read_b32 v234, v236 offset:640
	ds_read_b32 v235, v236 offset:704
	s_waitcnt lgkmcnt(0)
	v_lshl_add_u32 v148, s18, 8, v153
	v_ashrrev_i32_e32 v149, 31, v148
	v_or_b32_e32 v172, 16, v148
	v_ashrrev_i32_e32 v173, 31, v172
	v_or_b32_e32 v168, 32, v148
	v_or_b32_e32 v164, 48, v148
	v_ashrrev_i32_e32 v169, 31, v168
	v_ashrrev_i32_e32 v165, 31, v164
	v_add_u32_e32 v162, 0x80, v148
	v_add_u32_e32 v156, 0x90, v148
	v_ashrrev_i32_e32 v163, 31, v162
	v_ashrrev_i32_e32 v157, 31, v156
	v_add_u32_e32 v150, 0xa0, v148
	v_ashrrev_i32_e32 v151, 31, v150
	v_add_u32_e32 v146, 0xb0, v148
	v_ashrrev_i32_e32 v147, 31, v146
	v_lshl_or_b32 v166, s40, 8, v175
	v_ashrrev_i32_e32 v167, 31, v166
	v_lshlrev_b64 v[170:171], 13, v[148:149]
	v_lshlrev_b64 v[148:149], 1, v[166:167]
	v_lshl_add_u64 v[166:167], s[96:97], 0, v[170:171]
	v_lshl_add_u64 v[210:211], v[166:167], 0, v[148:149]
	s_mov_b32 s40, s10
	s_mov_b32 s18, s12
	s_mov_b64 s[22:23], s[16:17]
	s_mov_b64 s[20:21], s[14:15]
	s_waitcnt vmcnt(8)
	s_waitcnt lgkmcnt(0)
	s_waitcnt lgkmcnt(0)
	v_mov_b32_e32 v182, v228
	v_pk_mul_f32 v[120:121], v[120:121], v[182:183] op_sel_hi:[1,0]
	v_pk_mul_f32 v[126:127], v[126:127], v[182:183] op_sel_hi:[1,0]
	v_pk_mul_f32 v[124:125], v[124:125], v[182:183] op_sel_hi:[1,0]
	v_pk_mul_f32 v[122:123], v[122:123], v[182:183] op_sel_hi:[1,0]
	v_max_f32_e32 v120, 0, v120
	v_max_f32_e32 v121, 0, v121
	v_max_f32_e32 v124, 0, v124
	v_max_f32_e32 v125, 0, v125
	v_pk_mul_f32 v[188:189], v[120:121], v[120:121]
	v_max_f32_e32 v120, 0, v126
	v_max_f32_e32 v122, 0, v122
	v_max_f32_e32 v121, 0, v127
	v_max_f32_e32 v123, 0, v123
	v_pk_mul_f32 v[124:125], v[124:125], v[124:125]
	v_pk_mul_f32 v[126:127], v[120:121], v[120:121]
	v_pk_mul_f32 v[192:193], v[122:123], v[122:123]
	v_pk_mul_f32 v[114:115], v[114:115], v[182:183] op_sel_hi:[1,0]
	v_cvt_pk_bf16_f32 v120, v124, v125
	v_cvt_pk_bf16_f32 v121, v126, v127
	v_cvt_pk_bf16_f32 v122, v188, v189
	v_cvt_pk_bf16_f32 v123, v192, v193
	v_pk_mul_f32 v[116:117], v[116:117], v[182:183] op_sel_hi:[1,0]
	v_pk_mul_f32 v[112:113], v[112:113], v[182:183] op_sel_hi:[1,0]
	v_max_f32_e32 v114, 0, v114
	v_max_f32_e32 v115, 0, v115
	global_store_dwordx4 v[210:211], v[120:123], off
	v_pk_mul_f32 v[118:119], v[118:119], v[182:183] op_sel_hi:[1,0]
	v_max_f32_e32 v116, 0, v116
	v_max_f32_e32 v112, 0, v112
	v_max_f32_e32 v117, 0, v117
	v_max_f32_e32 v113, 0, v113
	v_pk_mul_f32 v[122:123], v[114:115], v[114:115]
	v_pk_mul_f32 v[116:117], v[116:117], v[116:117]
	v_pk_mul_f32 v[120:121], v[112:113], v[112:113]
; __device__ __forceinline__ unsigned pk2(float lo, float hi) { const f32x2 v = (f32x2){lo, hi}; const bf16x2_t b = __builtin_convertvector(v, bf16x2_t); return __builtin_bit_cast(unsigned, b); }
;     __device__ __forceinline__ void operator()(const f32x4 (&acc)[2][2][4][2], const Unit& u, int wr, int wc, int fr, int fq, const float (&)[8]) const {
;     ...
;             for (int m = 0; m < 4; ++m) { const int row = row0 + ai * HALF + m * 16; const float rs = rsqrtf(ep[ai * 4 + m] * (1.0f / 1024.0f) + EPS);
;                 u16* rowp = O + (size_t)row * ldc + col0;
; #pragma unroll
;                 for (int bj = 0; bj < 2; ++bj) { f32x4 v0 = acc[ai][bj][m][0] * rs, v1 = acc[ai][bj][m][1] * rs;
;                     if (ACT == 1) {
; #pragma unroll
;                         for (int j = 0; j < 4; ++j) { const float a0 = fmaxf(v0[j], 0.f), a1 = fmaxf(v1[j], 0.f); v0[j] = a0 * a0; v1[j] = a1 * a1; } }
;                     u32x4 w; w.x = pk2(v0[0], v0[1]); w.y = pk2(v0[2], v0[3]); w.z = pk2(v1[0], v1[1]); w.w = pk2(v1[2], v1[3]);
;                     *(u32x4*)(rowp + bj * HALF) = w; } }
	v_max_f32_e32 v112, 0, v118
	v_max_f32_e32 v113, 0, v119
	v_pk_mul_f32 v[118:119], v[112:113], v[112:113]
	v_cvt_pk_bf16_f32 v112, v116, v117
	v_cvt_pk_bf16_f32 v113, v118, v119
	v_cvt_pk_bf16_f32 v114, v120, v121
	v_cvt_pk_bf16_f32 v115, v122, v123
	global_store_dwordx4 v[210:211], v[112:115], off offset:256
	s_nop 1
	v_mov_b32_e32 v112, v229
	v_pk_mul_f32 v[104:105], v[104:105], v[112:113] op_sel_hi:[1,0]
	v_pk_mul_f32 v[110:111], v[110:111], v[112:113] op_sel_hi:[1,0]
	v_pk_mul_f32 v[108:109], v[108:109], v[112:113] op_sel_hi:[1,0]
	v_pk_mul_f32 v[106:107], v[106:107], v[112:113] op_sel_hi:[1,0]
	v_max_f32_e32 v104, 0, v104
	v_max_f32_e32 v105, 0, v105
	v_lshlrev_b64 v[114:115], 13, v[172:173]
	v_max_f32_e32 v108, 0, v108
	v_max_f32_e32 v109, 0, v109
	v_pk_mul_f32 v[116:117], v[104:105], v[104:105]
	v_max_f32_e32 v104, 0, v110
	v_max_f32_e32 v106, 0, v106
	v_max_f32_e32 v105, 0, v111
	v_max_f32_e32 v107, 0, v107
	v_lshl_add_u64 v[114:115], s[96:97], 0, v[114:115]
	v_pk_mul_f32 v[108:109], v[108:109], v[108:109]
	v_pk_mul_f32 v[110:111], v[104:105], v[104:105]
	v_pk_mul_f32 v[118:119], v[106:107], v[106:107]
	v_pk_mul_f32 v[96:97], v[96:97], v[112:113] op_sel_hi:[1,0]
	v_lshl_add_u64 v[114:115], v[114:115], 0, v[148:149]
	v_cvt_pk_bf16_f32 v104, v108, v109
	v_cvt_pk_bf16_f32 v105, v110, v111
	v_cvt_pk_bf16_f32 v106, v116, v117
	v_cvt_pk_bf16_f32 v107, v118, v119
	v_pk_mul_f32 v[102:103], v[102:103], v[112:113] op_sel_hi:[1,0]
	v_max_f32_e32 v96, 0, v96
	v_max_f32_e32 v97, 0, v97
	global_store_dwordx4 v[114:115], v[104:107], off
	v_pk_mul_f32 v[100:101], v[100:101], v[112:113] op_sel_hi:[1,0]
	v_pk_mul_f32 v[98:99], v[98:99], v[112:113] op_sel_hi:[1,0]
	v_pk_mul_f32 v[104:105], v[96:97], v[96:97]
	v_max_f32_e32 v96, 0, v102
	v_max_f32_e32 v97, 0, v103
	v_max_f32_e32 v100, 0, v100
	v_max_f32_e32 v101, 0, v101
	v_pk_mul_f32 v[100:101], v[100:101], v[100:101]
	v_pk_mul_f32 v[108:109], v[96:97], v[96:97]
	v_cvt_pk_bf16_f32 v96, v100, v101
	s_waitcnt lgkmcnt(0)
	v_max_f32_e32 v98, 0, v98
	v_max_f32_e32 v99, 0, v99
	v_pk_mul_f32 v[110:111], v[98:99], v[98:99]
	v_cvt_pk_bf16_f32 v97, v108, v109
	v_cvt_pk_bf16_f32 v98, v104, v105
	v_cvt_pk_bf16_f32 v99, v110, v111
	global_store_dwordx4 v[114:115], v[96:99], off offset:256
	s_waitcnt lgkmcnt(0)
	s_nop 0
	s_nop 0
	s_nop 0
	s_nop 1
	v_lshlrev_b64 v[98:99], 13, v[168:169]
	v_lshl_add_u64 v[98:99], s[96:97], 0, v[98:99]
	v_lshl_add_u64 v[98:99], v[98:99], 0, v[148:149]
	v_mov_b32_e32 v100, v230
	v_pk_mul_f32 v[88:89], v[88:89], v[100:101] op_sel_hi:[1,0]
	v_pk_mul_f32 v[94:95], v[94:95], v[100:101] op_sel_hi:[1,0]
	v_pk_mul_f32 v[92:93], v[92:93], v[100:101] op_sel_hi:[1,0]
	v_pk_mul_f32 v[90:91], v[90:91], v[100:101] op_sel_hi:[1,0]
	v_max_f32_e32 v88, 0, v88
	v_max_f32_e32 v89, 0, v89
	v_max_f32_e32 v92, 0, v92
	v_max_f32_e32 v93, 0, v93
	v_pk_mul_f32 v[102:103], v[88:89], v[88:89]
	v_max_f32_e32 v88, 0, v94
	v_max_f32_e32 v90, 0, v90
	v_max_f32_e32 v89, 0, v95
	v_max_f32_e32 v91, 0, v91
	v_pk_mul_f32 v[92:93], v[92:93], v[92:93]
	v_pk_mul_f32 v[94:95], v[88:89], v[88:89]
	v_pk_mul_f32 v[104:105], v[90:91], v[90:91]
	v_pk_mul_f32 v[82:83], v[82:83], v[100:101] op_sel_hi:[1,0]
	v_cvt_pk_bf16_f32 v88, v92, v93
	v_cvt_pk_bf16_f32 v89, v94, v95
	v_cvt_pk_bf16_f32 v90, v102, v103
	v_cvt_pk_bf16_f32 v91, v104, v105
	v_pk_mul_f32 v[84:85], v[84:85], v[100:101] op_sel_hi:[1,0]
	v_pk_mul_f32 v[80:81], v[80:81], v[100:101] op_sel_hi:[1,0]
	v_max_f32_e32 v82, 0, v82
	v_max_f32_e32 v83, 0, v83
	global_store_dwordx4 v[98:99], v[88:91], off
	v_pk_mul_f32 v[86:87], v[86:87], v[100:101] op_sel_hi:[1,0]
	v_max_f32_e32 v84, 0, v84
	v_max_f32_e32 v80, 0, v80
	v_max_f32_e32 v85, 0, v85
	v_max_f32_e32 v81, 0, v81
	v_pk_mul_f32 v[90:91], v[82:83], v[82:83]
	v_pk_mul_f32 v[84:85], v[84:85], v[84:85]
	v_pk_mul_f32 v[88:89], v[80:81], v[80:81]
	v_max_f32_e32 v80, 0, v86
	v_max_f32_e32 v81, 0, v87
	v_pk_mul_f32 v[86:87], v[80:81], v[80:81]
	v_cvt_pk_bf16_f32 v80, v84, v85
	v_cvt_pk_bf16_f32 v81, v86, v87
	v_cvt_pk_bf16_f32 v82, v88, v89
	v_cvt_pk_bf16_f32 v83, v90, v91
	global_store_dwordx4 v[98:99], v[80:83], off offset:256
	s_nop 1
	v_mov_b32_e32 v80, v231
	v_pk_mul_f32 v[72:73], v[72:73], v[80:81] op_sel_hi:[1,0]
	v_pk_mul_f32 v[78:79], v[78:79], v[80:81] op_sel_hi:[1,0]
	v_pk_mul_f32 v[76:77], v[76:77], v[80:81] op_sel_hi:[1,0]
	v_pk_mul_f32 v[74:75], v[74:75], v[80:81] op_sel_hi:[1,0]
	v_max_f32_e32 v72, 0, v72
	v_max_f32_e32 v73, 0, v73
	v_lshlrev_b64 v[82:83], 13, v[164:165]
	v_max_f32_e32 v76, 0, v76
	v_max_f32_e32 v77, 0, v77
	v_pk_mul_f32 v[84:85], v[72:73], v[72:73]
	v_max_f32_e32 v72, 0, v78
	v_max_f32_e32 v74, 0, v74
	v_max_f32_e32 v73, 0, v79
	v_max_f32_e32 v75, 0, v75
	v_lshl_add_u64 v[82:83], s[96:97], 0, v[82:83]
	v_pk_mul_f32 v[76:77], v[76:77], v[76:77]
	v_pk_mul_f32 v[78:79], v[72:73], v[72:73]
	v_pk_mul_f32 v[86:87], v[74:75], v[74:75]
	v_pk_mul_f32 v[64:65], v[64:65], v[80:81] op_sel_hi:[1,0]
	v_lshl_add_u64 v[82:83], v[82:83], 0, v[148:149]
	v_cvt_pk_bf16_f32 v72, v76, v77
	v_cvt_pk_bf16_f32 v73, v78, v79
	v_cvt_pk_bf16_f32 v74, v84, v85
	v_cvt_pk_bf16_f32 v75, v86, v87
	v_pk_mul_f32 v[70:71], v[70:71], v[80:81] op_sel_hi:[1,0]
	v_max_f32_e32 v64, 0, v64
	v_max_f32_e32 v65, 0, v65
	global_store_dwordx4 v[82:83], v[72:75], off
	v_pk_mul_f32 v[68:69], v[68:69], v[80:81] op_sel_hi:[1,0]
	v_pk_mul_f32 v[66:67], v[66:67], v[80:81] op_sel_hi:[1,0]
	v_pk_mul_f32 v[72:73], v[64:65], v[64:65]
	v_max_f32_e32 v64, 0, v70
	v_max_f32_e32 v65, 0, v71
	v_max_f32_e32 v68, 0, v68
	v_max_f32_e32 v69, 0, v69
	v_pk_mul_f32 v[68:69], v[68:69], v[68:69]
	v_pk_mul_f32 v[76:77], v[64:65], v[64:65]
	v_cvt_pk_bf16_f32 v64, v68, v69
	s_waitcnt lgkmcnt(0)
; __device__ __forceinline__ unsigned pk2(float lo, float hi) { const f32x2 v = (f32x2){lo, hi}; const bf16x2_t b = __builtin_convertvector(v, bf16x2_t); return __builtin_bit_cast(unsigned, b); }
;     __device__ __forceinline__ void operator()(const f32x4 (&acc)[2][2][4][2], const Unit& u, int wr, int wc, int fr, int fq, const float (&)[8]) const {
;     ...
;             for (int m = 0; m < 4; ++m) { const int row = row0 + ai * HALF + m * 16; const float rs = rsqrtf(ep[ai * 4 + m] * (1.0f / 1024.0f) + EPS);
;                 u16* rowp = O + (size_t)row * ldc + col0;
; #pragma unroll
;                 for (int bj = 0; bj < 2; ++bj) { f32x4 v0 = acc[ai][bj][m][0] * rs, v1 = acc[ai][bj][m][1] * rs;
;                     if (ACT == 1) {
; #pragma unroll
;                         for (int j = 0; j < 4; ++j) { const float a0 = fmaxf(v0[j], 0.f), a1 = fmaxf(v1[j], 0.f); v0[j] = a0 * a0; v1[j] = a1 * a1; } }
;                     u32x4 w; w.x = pk2(v0[0], v0[1]); w.y = pk2(v0[2], v0[3]); w.z = pk2(v1[0], v1[1]); w.w = pk2(v1[2], v1[3]);
;                     *(u32x4*)(rowp + bj * HALF) = w; } }
	v_max_f32_e32 v66, 0, v66
	v_max_f32_e32 v67, 0, v67
	v_pk_mul_f32 v[78:79], v[66:67], v[66:67]
	v_cvt_pk_bf16_f32 v65, v76, v77
	v_cvt_pk_bf16_f32 v66, v72, v73
	v_cvt_pk_bf16_f32 v67, v78, v79
	global_store_dwordx4 v[82:83], v[64:67], off offset:256
	s_waitcnt lgkmcnt(0)
	s_nop 0
	s_nop 0
	s_nop 0
	s_nop 1
	v_lshlrev_b64 v[66:67], 13, v[162:163]
	v_lshl_add_u64 v[66:67], s[96:97], 0, v[66:67]
	v_lshl_add_u64 v[66:67], v[66:67], 0, v[148:149]
	v_mov_b32_e32 v68, v232
	v_pk_mul_f32 v[56:57], v[56:57], v[68:69] op_sel_hi:[1,0]
	v_pk_mul_f32 v[62:63], v[62:63], v[68:69] op_sel_hi:[1,0]
	v_pk_mul_f32 v[60:61], v[60:61], v[68:69] op_sel_hi:[1,0]
	v_pk_mul_f32 v[58:59], v[58:59], v[68:69] op_sel_hi:[1,0]
	v_max_f32_e32 v56, 0, v56
	v_max_f32_e32 v57, 0, v57
	v_max_f32_e32 v60, 0, v60
	v_max_f32_e32 v61, 0, v61
	v_pk_mul_f32 v[70:71], v[56:57], v[56:57]
	v_max_f32_e32 v56, 0, v62
	v_max_f32_e32 v58, 0, v58
	v_max_f32_e32 v57, 0, v63
	v_max_f32_e32 v59, 0, v59
	v_pk_mul_f32 v[60:61], v[60:61], v[60:61]
	v_pk_mul_f32 v[62:63], v[56:57], v[56:57]
	v_pk_mul_f32 v[72:73], v[58:59], v[58:59]
	v_pk_mul_f32 v[50:51], v[50:51], v[68:69] op_sel_hi:[1,0]
	v_cvt_pk_bf16_f32 v56, v60, v61
	v_cvt_pk_bf16_f32 v57, v62, v63
	v_cvt_pk_bf16_f32 v58, v70, v71
	v_cvt_pk_bf16_f32 v59, v72, v73
	v_pk_mul_f32 v[52:53], v[52:53], v[68:69] op_sel_hi:[1,0]
	v_pk_mul_f32 v[48:49], v[48:49], v[68:69] op_sel_hi:[1,0]
	v_max_f32_e32 v50, 0, v50
	v_max_f32_e32 v51, 0, v51
	global_store_dwordx4 v[66:67], v[56:59], off
	v_pk_mul_f32 v[54:55], v[54:55], v[68:69] op_sel_hi:[1,0]
	v_max_f32_e32 v52, 0, v52
	v_max_f32_e32 v48, 0, v48
	v_max_f32_e32 v53, 0, v53
	v_max_f32_e32 v49, 0, v49
	v_pk_mul_f32 v[58:59], v[50:51], v[50:51]
	v_pk_mul_f32 v[52:53], v[52:53], v[52:53]
	v_pk_mul_f32 v[56:57], v[48:49], v[48:49]
	v_max_f32_e32 v48, 0, v54
	v_max_f32_e32 v49, 0, v55
	v_pk_mul_f32 v[54:55], v[48:49], v[48:49]
	v_cvt_pk_bf16_f32 v48, v52, v53
	v_cvt_pk_bf16_f32 v49, v54, v55
	v_cvt_pk_bf16_f32 v50, v56, v57
	v_cvt_pk_bf16_f32 v51, v58, v59
	global_store_dwordx4 v[66:67], v[48:51], off offset:256
	s_nop 1
	v_mov_b32_e32 v48, v233
	v_pk_mul_f32 v[40:41], v[40:41], v[48:49] op_sel_hi:[1,0]
	v_pk_mul_f32 v[46:47], v[46:47], v[48:49] op_sel_hi:[1,0]
	v_pk_mul_f32 v[44:45], v[44:45], v[48:49] op_sel_hi:[1,0]
	v_pk_mul_f32 v[42:43], v[42:43], v[48:49] op_sel_hi:[1,0]
	v_max_f32_e32 v40, 0, v40
	v_max_f32_e32 v41, 0, v41
	v_lshlrev_b64 v[50:51], 13, v[156:157]
	v_max_f32_e32 v44, 0, v44
	v_max_f32_e32 v45, 0, v45
	v_pk_mul_f32 v[52:53], v[40:41], v[40:41]
	v_max_f32_e32 v40, 0, v46
	v_max_f32_e32 v42, 0, v42
	v_max_f32_e32 v41, 0, v47
	v_max_f32_e32 v43, 0, v43
	v_lshl_add_u64 v[50:51], s[96:97], 0, v[50:51]
	v_pk_mul_f32 v[44:45], v[44:45], v[44:45]
	v_pk_mul_f32 v[46:47], v[40:41], v[40:41]
	v_pk_mul_f32 v[54:55], v[42:43], v[42:43]
	v_pk_mul_f32 v[32:33], v[32:33], v[48:49] op_sel_hi:[1,0]
	v_lshl_add_u64 v[50:51], v[50:51], 0, v[148:149]
	v_cvt_pk_bf16_f32 v40, v44, v45
	v_cvt_pk_bf16_f32 v41, v46, v47
	v_cvt_pk_bf16_f32 v42, v52, v53
	v_cvt_pk_bf16_f32 v43, v54, v55
	v_pk_mul_f32 v[38:39], v[38:39], v[48:49] op_sel_hi:[1,0]
	v_max_f32_e32 v32, 0, v32
	v_max_f32_e32 v33, 0, v33
	global_store_dwordx4 v[50:51], v[40:43], off
	v_pk_mul_f32 v[36:37], v[36:37], v[48:49] op_sel_hi:[1,0]
	v_pk_mul_f32 v[34:35], v[34:35], v[48:49] op_sel_hi:[1,0]
	v_pk_mul_f32 v[40:41], v[32:33], v[32:33]
	v_max_f32_e32 v32, 0, v38
	v_max_f32_e32 v33, 0, v39
	v_max_f32_e32 v36, 0, v36
	v_max_f32_e32 v37, 0, v37
	v_pk_mul_f32 v[36:37], v[36:37], v[36:37]
	v_pk_mul_f32 v[44:45], v[32:33], v[32:33]
	v_cvt_pk_bf16_f32 v32, v36, v37
	s_waitcnt lgkmcnt(0)
	v_max_f32_e32 v34, 0, v34
	v_max_f32_e32 v35, 0, v35
	v_pk_mul_f32 v[46:47], v[34:35], v[34:35]
	v_cvt_pk_bf16_f32 v33, v44, v45
	v_cvt_pk_bf16_f32 v34, v40, v41
	v_cvt_pk_bf16_f32 v35, v46, v47
	global_store_dwordx4 v[50:51], v[32:35], off offset:256
	s_waitcnt lgkmcnt(0)
; __device__ __forceinline__ unsigned pk2(float lo, float hi) { const f32x2 v = (f32x2){lo, hi}; const bf16x2_t b = __builtin_convertvector(v, bf16x2_t); return __builtin_bit_cast(unsigned, b); }
; #define PG8_WAIT_V(n) asm volatile("s_waitcnt vmcnt(" #n ")" ::: "memory")
; #define PG8_BAR __builtin_amdgcn_s_barrier()
;     __device__ __forceinline__ void operator()(const f32x4 (&acc)[2][2][4][2], const Unit& u, int wr, int wc, int fr, int fq, const float (&)[8]) const {
;     ...
;             for (int m = 0; m < 4; ++m) { const int row = row0 + ai * HALF + m * 16; const float rs = rsqrtf(ep[ai * 4 + m] * (1.0f / 1024.0f) + EPS);
;                 u16* rowp = O + (size_t)row * ldc + col0;
; #pragma unroll
;                 for (int bj = 0; bj < 2; ++bj) { f32x4 v0 = acc[ai][bj][m][0] * rs, v1 = acc[ai][bj][m][1] * rs;
;                     if (ACT == 1) {
; #pragma unroll
;                         for (int j = 0; j < 4; ++j) { const float a0 = fmaxf(v0[j], 0.f), a1 = fmaxf(v1[j], 0.f); v0[j] = a0 * a0; v1[j] = a1 * a1; } }
;                     u32x4 w; w.x = pk2(v0[0], v0[1]); w.y = pk2(v0[2], v0[3]); w.z = pk2(v1[0], v1[1]); w.w = pk2(v1[2], v1[3]);
;                     *(u32x4*)(rowp + bj * HALF) = w; } }
; template <class Epi>
; __device__ __forceinline__ void gemm_phase(LAS unsigned char* lds, const Gemm g, const StaticOrder& S, const Epi& E) {
;     ...
;         E(acc, cur, wr, wc, fr, fq, epre);
;         if (!has_next) break;
; #pragma unroll
;         for (int a = 0; a < 2; ++a)
; #pragma unroll
;             for (int b = 0; b < 2; ++b)
; #pragma unroll
;                 for (int m = 0; m < 4; ++m)
; #pragma unroll
;                     for (int n = 0; n < 2; ++n) acc[a][b][m][n] = (f32x4){0.f, 0.f, 0.f, 0.f};
;         cur = nxt; cA = nA; cB = nB; ++ui;
;     }
;     PG8_WAIT_V(0);
;     if (wr == 0) PG8_BAR;
	s_nop 0
	s_nop 0
	s_nop 0
	s_nop 1
	v_lshlrev_b64 v[34:35], 13, v[150:151]
	v_lshl_add_u64 v[34:35], s[96:97], 0, v[34:35]
	v_lshl_add_u64 v[34:35], v[34:35], 0, v[148:149]
	v_mov_b32_e32 v36, v234
	v_pk_mul_f32 v[24:25], v[24:25], v[36:37] op_sel_hi:[1,0]
	v_pk_mul_f32 v[30:31], v[30:31], v[36:37] op_sel_hi:[1,0]
	v_pk_mul_f32 v[28:29], v[28:29], v[36:37] op_sel_hi:[1,0]
	v_pk_mul_f32 v[26:27], v[26:27], v[36:37] op_sel_hi:[1,0]
	v_max_f32_e32 v24, 0, v24
	v_max_f32_e32 v25, 0, v25
	v_max_f32_e32 v28, 0, v28
	v_max_f32_e32 v29, 0, v29
	v_pk_mul_f32 v[38:39], v[24:25], v[24:25]
	v_max_f32_e32 v24, 0, v30
	v_max_f32_e32 v26, 0, v26
	v_max_f32_e32 v25, 0, v31
	v_max_f32_e32 v27, 0, v27
	v_pk_mul_f32 v[28:29], v[28:29], v[28:29]
	v_pk_mul_f32 v[30:31], v[24:25], v[24:25]
	v_pk_mul_f32 v[40:41], v[26:27], v[26:27]
	v_pk_mul_f32 v[18:19], v[18:19], v[36:37] op_sel_hi:[1,0]
	v_cvt_pk_bf16_f32 v24, v28, v29
	v_cvt_pk_bf16_f32 v25, v30, v31
	v_cvt_pk_bf16_f32 v26, v38, v39
	v_cvt_pk_bf16_f32 v27, v40, v41
	v_pk_mul_f32 v[20:21], v[20:21], v[36:37] op_sel_hi:[1,0]
	v_pk_mul_f32 v[16:17], v[16:17], v[36:37] op_sel_hi:[1,0]
	v_max_f32_e32 v18, 0, v18
	v_max_f32_e32 v19, 0, v19
	global_store_dwordx4 v[34:35], v[24:27], off
	v_pk_mul_f32 v[22:23], v[22:23], v[36:37] op_sel_hi:[1,0]
	v_max_f32_e32 v20, 0, v20
	v_max_f32_e32 v16, 0, v16
	v_max_f32_e32 v21, 0, v21
	v_max_f32_e32 v17, 0, v17
	v_pk_mul_f32 v[26:27], v[18:19], v[18:19]
	v_pk_mul_f32 v[20:21], v[20:21], v[20:21]
	v_pk_mul_f32 v[24:25], v[16:17], v[16:17]
	v_max_f32_e32 v16, 0, v22
	v_max_f32_e32 v17, 0, v23
	v_pk_mul_f32 v[22:23], v[16:17], v[16:17]
	v_cvt_pk_bf16_f32 v16, v20, v21
	v_cvt_pk_bf16_f32 v17, v22, v23
	v_cvt_pk_bf16_f32 v18, v24, v25
	v_cvt_pk_bf16_f32 v19, v26, v27
	global_store_dwordx4 v[34:35], v[16:19], off offset:256
	s_nop 1
	v_mov_b32_e32 v16, v235
	v_pk_mul_f32 v[8:9], v[8:9], v[16:17] op_sel_hi:[1,0]
	v_pk_mul_f32 v[14:15], v[14:15], v[16:17] op_sel_hi:[1,0]
	v_pk_mul_f32 v[12:13], v[12:13], v[16:17] op_sel_hi:[1,0]
	v_pk_mul_f32 v[10:11], v[10:11], v[16:17] op_sel_hi:[1,0]
	v_max_f32_e32 v8, 0, v8
	v_max_f32_e32 v9, 0, v9
	v_lshlrev_b64 v[18:19], 13, v[146:147]
	v_max_f32_e32 v12, 0, v12
	v_max_f32_e32 v13, 0, v13
	v_pk_mul_f32 v[20:21], v[8:9], v[8:9]
	v_max_f32_e32 v8, 0, v14
	v_max_f32_e32 v10, 0, v10
	v_max_f32_e32 v9, 0, v15
	v_max_f32_e32 v11, 0, v11
	v_lshl_add_u64 v[18:19], s[96:97], 0, v[18:19]
	v_pk_mul_f32 v[12:13], v[12:13], v[12:13]
	v_pk_mul_f32 v[14:15], v[8:9], v[8:9]
	v_pk_mul_f32 v[22:23], v[10:11], v[10:11]
	v_pk_mul_f32 v[0:1], v[0:1], v[16:17] op_sel_hi:[1,0]
	v_lshl_add_u64 v[18:19], v[18:19], 0, v[148:149]
	v_cvt_pk_bf16_f32 v8, v12, v13
	v_cvt_pk_bf16_f32 v9, v14, v15
	v_cvt_pk_bf16_f32 v10, v20, v21
	v_cvt_pk_bf16_f32 v11, v22, v23
	v_pk_mul_f32 v[6:7], v[6:7], v[16:17] op_sel_hi:[1,0]
	v_pk_mul_f32 v[4:5], v[4:5], v[16:17] op_sel_hi:[1,0]
	v_pk_mul_f32 v[2:3], v[2:3], v[16:17] op_sel_hi:[1,0]
	v_max_f32_e32 v0, 0, v0
	v_max_f32_e32 v1, 0, v1
	global_store_dwordx4 v[18:19], v[8:11], off
	v_max_f32_e32 v4, 0, v4
	v_max_f32_e32 v5, 0, v5
	v_pk_mul_f32 v[8:9], v[0:1], v[0:1]
	v_max_f32_e32 v0, 0, v6
	v_max_f32_e32 v2, 0, v2
	v_max_f32_e32 v1, 0, v7
	v_max_f32_e32 v3, 0, v3
	v_pk_mul_f32 v[4:5], v[4:5], v[4:5]
	v_pk_mul_f32 v[6:7], v[0:1], v[0:1]
	v_pk_mul_f32 v[10:11], v[2:3], v[2:3]
	v_cvt_pk_bf16_f32 v0, v4, v5
	v_cvt_pk_bf16_f32 v1, v6, v7
	v_cvt_pk_bf16_f32 v2, v8, v9
	v_cvt_pk_bf16_f32 v3, v10, v11
	s_and_b64 vcc, exec, s[0:1]
	global_store_dwordx4 v[18:19], v[0:3], off offset:256
	s_cbranch_vccz .LBB0_1197
	s_waitcnt vmcnt(0)
	s_cmpk_gt_u32 s7, 0xff
	s_cbranch_scc1 .LBB0_1208
	s_barrier

; #define PG8_STAGE(bufoff, gbase, voff) do { _Pragma("unroll") for (int _i = 0; _i < 2; ++_i) \
;         __builtin_amdgcn_global_load_lds((const unsigned*)((const char*)(gbase) + (voff)[_i]), (LAS unsigned*)(lds + (bufoff) + ldsw + _i * 8192), 16, 0, 0); } while (0)
; #define PG8_LDA(dst, b, h) do { _Pragma("unroll") for (int m = 0; m < 4; ++m) _Pragma("unroll") for (int k = 0; k < 2; ++k) dst[m][k] = *(const LAS bf16x8*)(lds + PG8_SA(b, h) + aoff + m * 2048 + k * 1024); } while (0)
; #define PG8_LDB(dst, b, h) do { _Pragma("unroll") for (int n = 0; n < 2; ++n) _Pragma("unroll") for (int k = 0; k < 2; ++k) dst[n][k] = *(const LAS bf16x8*)(lds + PG8_SB(b, h) + boff + n * 2048 + k * 1024); } while (0)
; #define PG8_MMA(ai, bj, At, Bt) do { __builtin_amdgcn_s_setprio(1); _Pragma("unroll") for (int m = 0; m < 4; ++m) _Pragma("unroll") for (int n = 0; n < 2; ++n) _Pragma("unroll") for (int k = 0; k < 2; ++k) \
;         acc[ai][bj][m][n] = __builtin_amdgcn_mfma_f32_16x16x32_bf16(Bt[n][k], At[m][k], acc[ai][bj][m][n], 0, 0, 0); __builtin_amdgcn_s_setprio(0); } while (0)
; #define PG8_WAIT_L(n) asm volatile("s_waitcnt lgkmcnt(" #n ")" ::: "memory")
; #define PG8_BAR __builtin_amdgcn_s_barrier()
; #define PG8_SCHED __builtin_amdgcn_sched_barrier(0)
; template <class Epi>
; __device__ __forceinline__ void gemm_phase(LAS unsigned char* lds, const Gemm g, const StaticOrder& S, const Epi& E) {
;     ...
;         for (int t = 0; t < nt; t += 2) {
;             const bool last = (t == nt - 2);
;             const char* a1 = cA + (size_t)(t + 1) * kstep;
;             const char* a2 = last ? nA : cA + (size_t)(t + 2) * kstep; const char* b2 = last ? nB : cB + (size_t)(t + 2) * kstep;
;             const char* a3 = a2 + kstep; const char* b3 = b2 + kstep;
;             if (last) E.pre(cur, wr, fr, epre);
;             PG8_LDB(B0, 0, 0); PG8_SCHED; PG8_LDA(At, 0, 0); PG8_STAGE(PG8_SA(1, 1), a1 + hstepA, voffA);
;             PG8_WAIT_L(8); PG8_BAR; PG8_WAIT_L(0); PG8_MMA(0, 0, At, B0); PG8_BAR; PG8_SCHED;
;             PG8_LDB(B1, 0, 1); PG8_STAGE(PG8_SB(0, 0), b2, voffB);
;             PG8_BAR; PG8_WAIT_L(0); PG8_MMA(0, 1, At, B1); PG8_BAR;
;             PG8_LDA(At, 0, 1); PG8_STAGE(PG8_SA(0, 0), a2, voffA);
;             PG8_BAR; PG8_WAIT_L(0); PG8_MMA(1, 0, At, B0); PG8_BAR; PG8_SCHED;
.LBB0_1278:
	ds_read_b128 v[128:131], v190
	ds_read_b128 v[132:135], v190 offset:1024
	ds_read_b128 v[136:139], v190 offset:2048
	ds_read_b128 v[140:143], v190 offset:3072
	s_add_u32 s24, s22, 0xfff00080
	s_addc_u32 s25, s23, -1
	s_cmp_eq_u32 s48, 60
	s_cselect_b32 s27, s17, s25
	s_cselect_b32 s26, s44, s24
	s_cselect_b32 s25, s15, s47
	s_cselect_b32 s24, s45, s46
	v_lshl_add_u64 v[186:187], s[22:23], 0, v[162:163]
	s_add_i32 m0, s7, 0xc000
	ds_read_b128 v[144:147], v191
	ds_read_b128 v[148:151], v191 offset:1024
	ds_read_b128 v[170:173], v191 offset:2048
	ds_read_b128 v[174:177], v191 offset:3072
	ds_read_b128 v[178:181], v191 offset:4096
	ds_read_b128 v[182:185], v191 offset:5120
	ds_read_b128 v[194:197], v191 offset:6144
	ds_read_b128 v[198:201], v191 offset:7168
	global_load_lds_dwordx4 v[186:187], off
	v_lshl_add_u64 v[186:187], s[22:23], 0, v[164:165]
	s_add_i32 m0, s7, 0xe000
	s_nop 0
	global_load_lds_dwordx4 v[186:187], off
	s_waitcnt lgkmcnt(8)
	s_barrier
	s_waitcnt lgkmcnt(0)
	v_mfma_f32_16x16x32_bf16 v[124:127], v[128:131], v[144:147], v[124:127]
	v_mfma_f32_16x16x32_bf16 v[120:123], v[136:139], v[144:147], v[120:123]
	v_mfma_f32_16x16x32_bf16 v[108:111], v[128:131], v[170:173], v[108:111]
	v_mfma_f32_16x16x32_bf16 v[104:107], v[136:139], v[170:173], v[104:107]
	v_mfma_f32_16x16x32_bf16 v[92:95], v[128:131], v[178:181], v[92:95]
	v_mfma_f32_16x16x32_bf16 v[88:91], v[136:139], v[178:181], v[88:91]
	v_mfma_f32_16x16x32_bf16 v[76:79], v[128:131], v[194:197], v[76:79]
	v_mfma_f32_16x16x32_bf16 v[72:75], v[136:139], v[194:197], v[72:75]
	v_mfma_f32_16x16x32_bf16 v[124:127], v[132:135], v[148:151], v[124:127]
	v_mfma_f32_16x16x32_bf16 v[120:123], v[140:143], v[148:151], v[120:123]
	v_mfma_f32_16x16x32_bf16 v[108:111], v[132:135], v[174:177], v[108:111]
	v_mfma_f32_16x16x32_bf16 v[104:107], v[140:143], v[174:177], v[104:107]
	v_mfma_f32_16x16x32_bf16 v[92:95], v[132:135], v[182:185], v[92:95]
	v_mfma_f32_16x16x32_bf16 v[88:91], v[140:143], v[182:185], v[88:91]
	v_mfma_f32_16x16x32_bf16 v[76:79], v[132:135], v[198:201], v[76:79]
	v_mfma_f32_16x16x32_bf16 v[72:75], v[140:143], v[198:201], v[72:75]
	s_barrier
	s_add_i32 s49, s42, s31
	v_lshl_add_u64 v[186:187], s[24:25], 0, v[156:157]
	s_mov_b32 m0, s49
	ds_read_b128 v[202:205], v192
	ds_read_b128 v[206:209], v192 offset:1024
	ds_read_b128 v[210:213], v192 offset:2048
	ds_read_b128 v[214:217], v192 offset:3072
	global_load_lds_dwordx4 v[186:187], off
	v_lshl_add_u64 v[218:219], s[24:25], 0, v[160:161]
	s_add_i32 m0, s49, 0x2000
	s_nop 0
	global_load_lds_dwordx4 v[218:219], off
	s_barrier
	s_waitcnt lgkmcnt(0)
	v_mfma_f32_16x16x32_bf16 v[116:119], v[202:205], v[144:147], v[116:119]
	v_mfma_f32_16x16x32_bf16 v[112:115], v[210:213], v[144:147], v[112:115]
	v_mfma_f32_16x16x32_bf16 v[100:103], v[202:205], v[170:173], v[100:103]
	v_mfma_f32_16x16x32_bf16 v[96:99], v[210:213], v[170:173], v[96:99]
	v_mfma_f32_16x16x32_bf16 v[84:87], v[202:205], v[178:181], v[84:87]
	v_mfma_f32_16x16x32_bf16 v[80:83], v[210:213], v[178:181], v[80:83]
	v_mfma_f32_16x16x32_bf16 v[68:71], v[202:205], v[194:197], v[68:71]
	v_mfma_f32_16x16x32_bf16 v[64:67], v[210:213], v[194:197], v[64:67]
	v_mfma_f32_16x16x32_bf16 v[116:119], v[206:209], v[148:151], v[116:119]
	v_mfma_f32_16x16x32_bf16 v[112:115], v[214:217], v[148:151], v[112:115]
	v_mfma_f32_16x16x32_bf16 v[100:103], v[206:209], v[174:177], v[100:103]
	v_mfma_f32_16x16x32_bf16 v[96:99], v[214:217], v[174:177], v[96:99]
	v_mfma_f32_16x16x32_bf16 v[84:87], v[206:209], v[182:185], v[84:87]
	v_mfma_f32_16x16x32_bf16 v[80:83], v[214:217], v[182:185], v[80:83]
	v_mfma_f32_16x16x32_bf16 v[68:71], v[206:209], v[198:201], v[68:71]
	v_mfma_f32_16x16x32_bf16 v[64:67], v[214:217], v[198:201], v[64:67]
	s_mov_b32 m0, s7
	v_lshl_add_u64 v[220:221], s[26:27], 0, v[154:155]
	s_barrier
	ds_read_b128 v[144:147], v191 offset:16384
	ds_read_b128 v[148:151], v191 offset:17408
	ds_read_b128 v[170:173], v191 offset:18432
	ds_read_b128 v[174:177], v191 offset:19456
	ds_read_b128 v[178:181], v191 offset:20480
	ds_read_b128 v[182:185], v191 offset:21504
	ds_read_b128 v[194:197], v191 offset:22528
	ds_read_b128 v[198:201], v191 offset:23552
	global_load_lds_dwordx4 v[220:221], off
	v_lshl_add_u64 v[222:223], s[26:27], 0, v[158:159]
	s_mov_b32 m0, s34
	s_nop 0
	global_load_lds_dwordx4 v[222:223], off
	s_barrier
	s_waitcnt lgkmcnt(0)
	v_mfma_f32_16x16x32_bf16 v[60:63], v[128:131], v[144:147], v[60:63]
	v_mfma_f32_16x16x32_bf16 v[56:59], v[136:139], v[144:147], v[56:59]
	v_mfma_f32_16x16x32_bf16 v[44:47], v[128:131], v[170:173], v[44:47]
	v_mfma_f32_16x16x32_bf16 v[40:43], v[136:139], v[170:173], v[40:43]
	v_mfma_f32_16x16x32_bf16 v[28:31], v[128:131], v[178:181], v[28:31]
	v_mfma_f32_16x16x32_bf16 v[24:27], v[136:139], v[178:181], v[24:27]
	v_mfma_f32_16x16x32_bf16 v[12:15], v[128:131], v[194:197], v[12:15]
	v_mfma_f32_16x16x32_bf16 v[8:11], v[136:139], v[194:197], v[8:11]
	v_mfma_f32_16x16x32_bf16 v[60:63], v[132:135], v[148:151], v[60:63]
	v_mfma_f32_16x16x32_bf16 v[56:59], v[140:143], v[148:151], v[56:59]
	v_mfma_f32_16x16x32_bf16 v[44:47], v[132:135], v[174:177], v[44:47]
	v_mfma_f32_16x16x32_bf16 v[40:43], v[140:143], v[174:177], v[40:43]
	v_mfma_f32_16x16x32_bf16 v[28:31], v[132:135], v[182:185], v[28:31]
	v_mfma_f32_16x16x32_bf16 v[24:27], v[140:143], v[182:185], v[24:27]
	v_mfma_f32_16x16x32_bf16 v[12:15], v[132:135], v[198:201], v[12:15]
	v_mfma_f32_16x16x32_bf16 v[8:11], v[140:143], v[198:201], v[8:11]
	s_barrier
; #define PG8_STAGE(bufoff, gbase, voff) do { _Pragma("unroll") for (int _i = 0; _i < 2; ++_i) \
;         __builtin_amdgcn_global_load_lds((const unsigned*)((const char*)(gbase) + (voff)[_i]), (LAS unsigned*)(lds + (bufoff) + ldsw + _i * 8192), 16, 0, 0); } while (0)
; #define PG8_LDA(dst, b, h) do { _Pragma("unroll") for (int m = 0; m < 4; ++m) _Pragma("unroll") for (int k = 0; k < 2; ++k) dst[m][k] = *(const LAS bf16x8*)(lds + PG8_SA(b, h) + aoff + m * 2048 + k * 1024); } while (0)
; #define PG8_LDB(dst, b, h) do { _Pragma("unroll") for (int n = 0; n < 2; ++n) _Pragma("unroll") for (int k = 0; k < 2; ++k) dst[n][k] = *(const LAS bf16x8*)(lds + PG8_SB(b, h) + boff + n * 2048 + k * 1024); } while (0)
; #define PG8_MMA(ai, bj, At, Bt) do { __builtin_amdgcn_s_setprio(1); _Pragma("unroll") for (int m = 0; m < 4; ++m) _Pragma("unroll") for (int n = 0; n < 2; ++n) _Pragma("unroll") for (int k = 0; k < 2; ++k) \
;         acc[ai][bj][m][n] = __builtin_amdgcn_mfma_f32_16x16x32_bf16(Bt[n][k], At[m][k], acc[ai][bj][m][n], 0, 0, 0); __builtin_amdgcn_s_setprio(0); } while (0)
; #define PG8_WAIT_V(n) asm volatile("s_waitcnt vmcnt(" #n ")" ::: "memory")
; #define PG8_WAIT_L(n) asm volatile("s_waitcnt lgkmcnt(" #n ")" ::: "memory")
; #define PG8_BAR __builtin_amdgcn_s_barrier()
; #define PG8_SCHED __builtin_amdgcn_sched_barrier(0)
; template <class Epi>
; __device__ __forceinline__ void gemm_phase(LAS unsigned char* lds, const Gemm g, const StaticOrder& S, const Epi& E) {
;     ...
;             PG8_STAGE(PG8_SB(0, 1), b2 + hstepB, voffB);
;             PG8_WAIT_V(6); PG8_BAR; PG8_MMA(1, 1, At, B1); PG8_BAR;
;             PG8_LDB(B0, 1, 0); PG8_SCHED; PG8_LDA(At, 1, 0); PG8_STAGE(PG8_SA(0, 1), a2 + hstepA, voffA);
;             PG8_WAIT_L(8); PG8_BAR; PG8_WAIT_L(0); PG8_MMA(0, 0, At, B0); PG8_BAR; PG8_SCHED;
;             PG8_LDB(B1, 1, 1); PG8_STAGE(PG8_SB(1, 0), b3, voffB);
;             PG8_BAR; PG8_WAIT_L(0); PG8_MMA(0, 1, At, B1); PG8_BAR;
;             PG8_LDA(At, 1, 1); PG8_STAGE(PG8_SA(1, 0), a3, voffA);
	s_add_u32 s50, s24, 0x100000
	s_addc_u32 s51, s25, 0
	s_add_i32 s49, s43, s31
	v_lshl_add_u64 v[128:129], s[50:51], 0, v[156:157]
	s_mov_b32 m0, s49
	s_nop 0
	global_load_lds_dwordx4 v[128:129], off
	v_lshl_add_u64 v[128:129], s[50:51], 0, v[160:161]
	s_add_i32 m0, s49, 0x2000
	s_nop 0
	global_load_lds_dwordx4 v[128:129], off
	s_waitcnt vmcnt(6)
	s_barrier
	v_mfma_f32_16x16x32_bf16 v[52:55], v[202:205], v[144:147], v[52:55]
	v_mfma_f32_16x16x32_bf16 v[48:51], v[210:213], v[144:147], v[48:51]
	v_mfma_f32_16x16x32_bf16 v[36:39], v[202:205], v[170:173], v[36:39]
	v_mfma_f32_16x16x32_bf16 v[32:35], v[210:213], v[170:173], v[32:35]
	v_mfma_f32_16x16x32_bf16 v[20:23], v[202:205], v[178:181], v[20:23]
	v_mfma_f32_16x16x32_bf16 v[16:19], v[210:213], v[178:181], v[16:19]
	v_mfma_f32_16x16x32_bf16 v[4:7], v[202:205], v[194:197], v[4:7]
	v_mfma_f32_16x16x32_bf16 v[0:3], v[210:213], v[194:197], v[0:3]
	v_mfma_f32_16x16x32_bf16 v[52:55], v[206:209], v[148:151], v[52:55]
	v_mfma_f32_16x16x32_bf16 v[48:51], v[214:217], v[148:151], v[48:51]
	v_mfma_f32_16x16x32_bf16 v[36:39], v[206:209], v[174:177], v[36:39]
	v_mfma_f32_16x16x32_bf16 v[32:35], v[214:217], v[174:177], v[32:35]
	v_mfma_f32_16x16x32_bf16 v[20:23], v[206:209], v[182:185], v[20:23]
	v_mfma_f32_16x16x32_bf16 v[16:19], v[214:217], v[182:185], v[16:19]
	v_mfma_f32_16x16x32_bf16 v[4:7], v[206:209], v[198:201], v[4:7]
	v_mfma_f32_16x16x32_bf16 v[0:3], v[214:217], v[198:201], v[0:3]
	s_add_i32 s49, 0, 0x18000
	v_add_u32_e32 v140, s49, v188
	s_barrier
	ds_read_b128 v[128:131], v140
	ds_read_b128 v[132:135], v140 offset:1024
	ds_read_b128 v[136:139], v140 offset:2048
	ds_read_b128 v[140:143], v140 offset:3072
	s_add_u32 s26, s26, 0x100000
	s_addc_u32 s27, s27, 0
	s_mov_b32 m0, s35
	v_lshl_add_u64 v[202:203], s[26:27], 0, v[154:155]
	ds_read_b128 v[144:147], v191 offset:32768
	ds_read_b128 v[148:151], v191 offset:33792
	ds_read_b128 v[170:173], v191 offset:34816
	ds_read_b128 v[174:177], v191 offset:35840
	ds_read_b128 v[178:181], v191 offset:36864
	ds_read_b128 v[182:185], v191 offset:37888
	ds_read_b128 v[194:197], v191 offset:38912
	ds_read_b128 v[198:201], v191 offset:39936
	global_load_lds_dwordx4 v[202:203], off
	v_lshl_add_u64 v[202:203], s[26:27], 0, v[158:159]
	s_mov_b32 m0, s36
	s_nop 0
	global_load_lds_dwordx4 v[202:203], off
	s_waitcnt lgkmcnt(8)
	s_barrier
	s_waitcnt lgkmcnt(0)
	v_mfma_f32_16x16x32_bf16 v[124:127], v[128:131], v[144:147], v[124:127]
	v_mfma_f32_16x16x32_bf16 v[120:123], v[136:139], v[144:147], v[120:123]
	v_mfma_f32_16x16x32_bf16 v[108:111], v[128:131], v[170:173], v[108:111]
	v_mfma_f32_16x16x32_bf16 v[104:107], v[136:139], v[170:173], v[104:107]
	v_mfma_f32_16x16x32_bf16 v[92:95], v[128:131], v[178:181], v[92:95]
	v_mfma_f32_16x16x32_bf16 v[88:91], v[136:139], v[178:181], v[88:91]
	v_mfma_f32_16x16x32_bf16 v[76:79], v[128:131], v[194:197], v[76:79]
	v_mfma_f32_16x16x32_bf16 v[72:75], v[136:139], v[194:197], v[72:75]
	v_mfma_f32_16x16x32_bf16 v[124:127], v[132:135], v[148:151], v[124:127]
	v_mfma_f32_16x16x32_bf16 v[120:123], v[140:143], v[148:151], v[120:123]
	v_mfma_f32_16x16x32_bf16 v[108:111], v[132:135], v[174:177], v[108:111]
	v_mfma_f32_16x16x32_bf16 v[104:107], v[140:143], v[174:177], v[104:107]
	v_mfma_f32_16x16x32_bf16 v[92:95], v[132:135], v[182:185], v[92:95]
	v_mfma_f32_16x16x32_bf16 v[88:91], v[140:143], v[182:185], v[88:91]
	v_mfma_f32_16x16x32_bf16 v[76:79], v[132:135], v[198:201], v[76:79]
	v_mfma_f32_16x16x32_bf16 v[72:75], v[140:143], v[198:201], v[72:75]
	s_barrier
	s_add_i32 s26, 0, 0x1c000
	s_add_i32 s27, s49, s31
	v_add_u32_e32 v214, s26, v188
	v_lshl_add_u64 v[186:187], v[186:187], 0, s[12:13]
	s_mov_b32 m0, s27
	ds_read_b128 v[202:205], v214
	ds_read_b128 v[206:209], v214 offset:1024
	ds_read_b128 v[210:213], v214 offset:2048
	ds_read_b128 v[214:217], v214 offset:3072
	global_load_lds_dwordx4 v[186:187], off
	v_lshl_add_u64 v[186:187], v[218:219], 0, s[12:13]
	s_add_i32 m0, s27, 0x2000
	s_nop 0
	global_load_lds_dwordx4 v[186:187], off
	s_barrier
	s_waitcnt lgkmcnt(0)
	v_mfma_f32_16x16x32_bf16 v[116:119], v[202:205], v[144:147], v[116:119]
	v_mfma_f32_16x16x32_bf16 v[112:115], v[210:213], v[144:147], v[112:115]
	v_mfma_f32_16x16x32_bf16 v[100:103], v[202:205], v[170:173], v[100:103]
	v_mfma_f32_16x16x32_bf16 v[96:99], v[210:213], v[170:173], v[96:99]
	v_mfma_f32_16x16x32_bf16 v[84:87], v[202:205], v[178:181], v[84:87]
	v_mfma_f32_16x16x32_bf16 v[80:83], v[210:213], v[178:181], v[80:83]
	v_mfma_f32_16x16x32_bf16 v[68:71], v[202:205], v[194:197], v[68:71]
	v_mfma_f32_16x16x32_bf16 v[64:67], v[210:213], v[194:197], v[64:67]
	v_mfma_f32_16x16x32_bf16 v[116:119], v[206:209], v[148:151], v[116:119]
	v_mfma_f32_16x16x32_bf16 v[112:115], v[214:217], v[148:151], v[112:115]
	v_mfma_f32_16x16x32_bf16 v[100:103], v[206:209], v[174:177], v[100:103]
	v_mfma_f32_16x16x32_bf16 v[96:99], v[214:217], v[174:177], v[96:99]
	v_mfma_f32_16x16x32_bf16 v[84:87], v[206:209], v[182:185], v[84:87]
	v_mfma_f32_16x16x32_bf16 v[80:83], v[214:217], v[182:185], v[80:83]
	v_mfma_f32_16x16x32_bf16 v[68:71], v[206:209], v[198:201], v[68:71]
	v_mfma_f32_16x16x32_bf16 v[64:67], v[214:217], v[198:201], v[64:67]
	s_mov_b32 m0, s38
	v_lshl_add_u64 v[186:187], v[220:221], 0, s[12:13]
	s_barrier
	ds_read_b128 v[144:147], v191 offset:49152
	ds_read_b128 v[148:151], v191 offset:50176
	ds_read_b128 v[170:173], v191 offset:51200
	ds_read_b128 v[174:177], v191 offset:52224
	ds_read_b128 v[178:181], v191 offset:53248
	ds_read_b128 v[182:185], v191 offset:54272
	ds_read_b128 v[194:197], v191 offset:55296
	ds_read_b128 v[198:201], v191 offset:56320
	global_load_lds_dwordx4 v[186:187], off
	v_lshl_add_u64 v[186:187], v[222:223], 0, s[12:13]
	s_mov_b32 m0, s39
	s_nop 0
	global_load_lds_dwordx4 v[186:187], off
	s_barrier
; #define PG8_STAGE(bufoff, gbase, voff) do { _Pragma("unroll") for (int _i = 0; _i < 2; ++_i) \
;         __builtin_amdgcn_global_load_lds((const unsigned*)((const char*)(gbase) + (voff)[_i]), (LAS unsigned*)(lds + (bufoff) + ldsw + _i * 8192), 16, 0, 0); } while (0)
; #define PG8_MMA(ai, bj, At, Bt) do { __builtin_amdgcn_s_setprio(1); _Pragma("unroll") for (int m = 0; m < 4; ++m) _Pragma("unroll") for (int n = 0; n < 2; ++n) _Pragma("unroll") for (int k = 0; k < 2; ++k) \
;         acc[ai][bj][m][n] = __builtin_amdgcn_mfma_f32_16x16x32_bf16(Bt[n][k], At[m][k], acc[ai][bj][m][n], 0, 0, 0); __builtin_amdgcn_s_setprio(0); } while (0)
; #define PG8_WAIT_V(n) asm volatile("s_waitcnt vmcnt(" #n ")" ::: "memory")
; #define PG8_WAIT_L(n) asm volatile("s_waitcnt lgkmcnt(" #n ")" ::: "memory")
; #define PG8_BAR __builtin_amdgcn_s_barrier()
; #define PG8_SCHED __builtin_amdgcn_sched_barrier(0)
; template <class Epi>
; __device__ __forceinline__ void gemm_phase(LAS unsigned char* lds, const Gemm g, const StaticOrder& S, const Epi& E) {
;     ...
;             PG8_BAR; PG8_WAIT_L(0); PG8_MMA(1, 0, At, B0); PG8_BAR; PG8_SCHED;
;             PG8_STAGE(PG8_SB(1, 1), b3 + hstepB, voffB);
;             PG8_WAIT_V(6); PG8_BAR; PG8_MMA(1, 1, At, B1); PG8_BAR;
	s_waitcnt lgkmcnt(0)
	v_mfma_f32_16x16x32_bf16 v[60:63], v[128:131], v[144:147], v[60:63]
	v_mfma_f32_16x16x32_bf16 v[56:59], v[136:139], v[144:147], v[56:59]
	v_mfma_f32_16x16x32_bf16 v[44:47], v[128:131], v[170:173], v[44:47]
	v_mfma_f32_16x16x32_bf16 v[40:43], v[136:139], v[170:173], v[40:43]
	v_mfma_f32_16x16x32_bf16 v[28:31], v[128:131], v[178:181], v[28:31]
	v_mfma_f32_16x16x32_bf16 v[24:27], v[136:139], v[178:181], v[24:27]
	v_mfma_f32_16x16x32_bf16 v[12:15], v[128:131], v[194:197], v[12:15]
	v_mfma_f32_16x16x32_bf16 v[8:11], v[136:139], v[194:197], v[8:11]
	v_mfma_f32_16x16x32_bf16 v[60:63], v[132:135], v[148:151], v[60:63]
	v_mfma_f32_16x16x32_bf16 v[56:59], v[140:143], v[148:151], v[56:59]
	v_mfma_f32_16x16x32_bf16 v[44:47], v[132:135], v[174:177], v[44:47]
	v_mfma_f32_16x16x32_bf16 v[40:43], v[140:143], v[174:177], v[40:43]
	v_mfma_f32_16x16x32_bf16 v[28:31], v[132:135], v[182:185], v[28:31]
	v_mfma_f32_16x16x32_bf16 v[24:27], v[140:143], v[182:185], v[24:27]
	v_mfma_f32_16x16x32_bf16 v[12:15], v[132:135], v[198:201], v[12:15]
	v_mfma_f32_16x16x32_bf16 v[8:11], v[140:143], v[198:201], v[8:11]
	s_barrier
	s_add_u32 s24, s24, 0x100080
	s_addc_u32 s25, s25, 0
	s_add_i32 s26, s26, s31
	v_lshl_add_u64 v[128:129], s[24:25], 0, v[156:157]
	s_mov_b32 m0, s26
	s_nop 0
	global_load_lds_dwordx4 v[128:129], off
	v_lshl_add_u64 v[128:129], s[24:25], 0, v[160:161]
	s_add_i32 m0, s26, 0x2000
	s_nop 0
	global_load_lds_dwordx4 v[128:129], off
	s_waitcnt vmcnt(6)
	s_barrier
	v_mfma_f32_16x16x32_bf16 v[52:55], v[202:205], v[144:147], v[52:55]
	v_mfma_f32_16x16x32_bf16 v[48:51], v[210:213], v[144:147], v[48:51]
	v_mfma_f32_16x16x32_bf16 v[36:39], v[202:205], v[170:173], v[36:39]
	v_mfma_f32_16x16x32_bf16 v[32:35], v[210:213], v[170:173], v[32:35]
	v_mfma_f32_16x16x32_bf16 v[20:23], v[202:205], v[178:181], v[20:23]
	v_mfma_f32_16x16x32_bf16 v[16:19], v[210:213], v[178:181], v[16:19]
	v_mfma_f32_16x16x32_bf16 v[4:7], v[202:205], v[194:197], v[4:7]
	v_mfma_f32_16x16x32_bf16 v[0:3], v[210:213], v[194:197], v[0:3]
	v_mfma_f32_16x16x32_bf16 v[52:55], v[206:209], v[148:151], v[52:55]
	v_mfma_f32_16x16x32_bf16 v[48:51], v[214:217], v[148:151], v[48:51]
	v_mfma_f32_16x16x32_bf16 v[36:39], v[206:209], v[174:177], v[36:39]
	v_mfma_f32_16x16x32_bf16 v[32:35], v[214:217], v[174:177], v[32:35]
	v_mfma_f32_16x16x32_bf16 v[20:23], v[206:209], v[182:185], v[20:23]
	v_mfma_f32_16x16x32_bf16 v[16:19], v[214:217], v[182:185], v[16:19]
	v_mfma_f32_16x16x32_bf16 v[4:7], v[206:209], v[198:201], v[4:7]
	v_mfma_f32_16x16x32_bf16 v[0:3], v[214:217], v[198:201], v[0:3]
	s_add_i32 s48, s48, 2
	s_add_u32 s22, s22, 0x100
	s_addc_u32 s23, s23, 0
	s_add_u32 s46, s46, 0x100
	s_addc_u32 s47, s47, 0
	s_cmp_gt_u32 s48, 61
	s_barrier
	s_cbranch_scc0 .LBB0_1278
; __device__ __forceinline__ unsigned pk2(float lo, float hi) { const f32x2 v = (f32x2){lo, hi}; const bf16x2_t b = __builtin_convertvector(v, bf16x2_t); return __builtin_bit_cast(unsigned, b); }
; __device__ __forceinline__ void unpack8(const u32x4 v, float* f) { f[0] = bf_lo(v.x); f[1] = bf_hi(v.x); f[2] = bf_lo(v.y); f[3] = bf_hi(v.y); f[4] = bf_lo(v.z); f[5] = bf_hi(v.z); f[6] = bf_lo(v.w); f[7] = bf_hi(v.w); }
;     __device__ __forceinline__ void operator()(const f32x4 (&acc)[2][2][4][2], const Unit& u, int wr, int wc, int fr, int fq, const float (&)[8]) const {
;         const int row0 = u.pm * BM + wr * 64 + fr, col0 = u.pn * BM + wc * 32 + 8 * fq;
; #pragma unroll
;         for (int ai = 0; ai < 2; ++ai) {
;             u32x4 bv[4][2];
; #pragma unroll
;             for (int m = 0; m < 4; ++m)
; #pragma unroll
;                 for (int bj = 0; bj < 2; ++bj) bv[m][bj] = *(const u32x4*)(xb + (size_t)(row0 + ai * HALF + m * 16) * DM + col0 + bj * HALF);
; #pragma unroll
;             for (int m = 0; m < 4; ++m) { const int row = row0 + ai * HALF + m * 16; const size_t ro = (size_t)row * DM + col0; float s = 0.f;
; #pragma unroll
;                 for (int bj = 0; bj < 2; ++bj) { float b8[8]; unpack8(bv[m][bj], b8);
;                     const f32x4 v0 = (f32x4){b8[0], b8[1], b8[2], b8[3]} + acc[ai][bj][m][0], v1 = (f32x4){b8[4], b8[5], b8[6], b8[7]} + acc[ai][bj][m][1];
;                     s += v0[0] * v0[0] + v0[1] * v0[1] + v0[2] * v0[2] + v0[3] * v0[3] + v1[0] * v1[0] + v1[1] * v1[1] + v1[2] * v1[2] + v1[3] * v1[3];
;                     if (LAST) { *(f32x4*)(out + ro + bj * HALF) = v0; *(f32x4*)(out + ro + bj * HALF + 4) = v1; }
;                     else { u32x4 w; w.x = pk2(v0[0], v0[1]); w.y = pk2(v0[2], v0[3]); w.z = pk2(v1[0], v1[1]); w.w = pk2(v1[2], v1[3]); *(u32x4*)(xb + ro + bj * HALF) = w; } }
;                 s += __shfl_xor(s, 16); s += __shfl_xor(s, 32);
;                 if (fq == 0) ss[(size_t)row * 16 + u.pn * 4 + wc] = s; }
	s_setprio 0
	v_lshl_or_b32 v170, s6, 8, v189
	v_lshl_add_u32 v172, s8, 8, v153
	v_ashrrev_i32_e32 v171, 31, v170
	v_lshlrev_b64 v[204:205], 1, v[170:171]
	v_ashrrev_i32_e32 v173, 31, v172
	v_lshl_add_u64 v[174:175], s[76:77], 0, v[204:205]
	v_lshlrev_b64 v[206:207], 11, v[172:173]
	v_lshl_add_u64 v[128:129], v[174:175], 0, v[206:207]
	global_load_dwordx4 v[196:199], v[128:129], off
	global_load_dwordx4 v[200:203], v[128:129], off offset:256
	v_or_b32_e32 v184, 16, v172
	v_or_b32_e32 v180, 32, v172
	v_or_b32_e32 v176, 48, v172
	v_ashrrev_i32_e32 v185, 31, v184
	v_ashrrev_i32_e32 v181, 31, v180
	v_ashrrev_i32_e32 v177, 31, v176
	v_lshlrev_b64 v[186:187], 11, v[184:185]
	v_lshlrev_b64 v[182:183], 11, v[180:181]
	v_lshlrev_b64 v[178:179], 11, v[176:177]
	v_lshl_add_u64 v[128:129], v[174:175], 0, v[186:187]
	v_lshl_add_u64 v[130:131], v[174:175], 0, v[182:183]
	v_lshl_add_u64 v[194:195], v[174:175], 0, v[178:179]
	global_load_dwordx4 v[148:151], v[128:129], off
	global_load_dwordx4 v[144:147], v[128:129], off offset:256
	global_load_dwordx4 v[140:143], v[130:131], off
	global_load_dwordx4 v[136:139], v[130:131], off offset:256
	global_load_dwordx4 v[132:135], v[194:195], off
	s_nop 0
	global_load_dwordx4 v[128:131], v[194:195], off offset:256
	v_add_u32_e32 v226, 0x80, v172
	v_ashrrev_i32_e32 v227, 31, v226
	v_lshlrev_b64 v[226:227], 11, v[226:227]
	v_lshl_add_u64 v[226:227], v[174:175], 0, v[226:227]
	global_load_dwordx4 v[216:219], v[226:227], off
	global_load_dwordx4 v[220:223], v[226:227], off offset:256
	v_add_u32_e32 v226, 0x90, v172
	v_ashrrev_i32_e32 v227, 31, v226
	v_lshlrev_b64 v[226:227], 11, v[226:227]
	v_lshl_add_u64 v[226:227], v[174:175], 0, v[226:227]
	global_load_dwordx4 v[228:231], v[226:227], off
	global_load_dwordx4 v[232:235], v[226:227], off offset:256
	v_add_u32_e32 v226, 0xa0, v172
	v_ashrrev_i32_e32 v227, 31, v226
	v_lshlrev_b64 v[226:227], 11, v[226:227]
	v_lshl_add_u64 v[226:227], v[174:175], 0, v[226:227]
	global_load_dwordx4 v[236:239], v[226:227], off
	global_load_dwordx4 v[240:243], v[226:227], off offset:256
	v_add_u32_e32 v226, 0xb0, v172
	v_ashrrev_i32_e32 v227, 31, v226
	v_lshlrev_b64 v[226:227], 11, v[226:227]
	v_lshl_add_u64 v[226:227], v[174:175], 0, v[226:227]
	global_load_dwordx4 v[244:247], v[226:227], off
	global_load_dwordx4 v[252:255], v[226:227], off offset:256
	v_and_b32_e32 v195, 64, v193
	v_xor_b32_e32 v194, 16, v193
	v_add_u32_e32 v195, 64, v195
	v_xor_b32_e32 v208, 32, v193
	v_cmp_lt_i32_e32 vcc, v194, v195
	s_waitcnt vmcnt(15)
	v_and_b32_e32 v209, 0xffff0000, v196
	v_cndmask_b32_e32 v194, v193, v194, vcc
	v_cmp_lt_i32_e32 vcc, v208, v195
	v_lshlrev_b32_e32 v195, 2, v194
	s_waitcnt vmcnt(14)
	v_lshlrev_b32_e32 v212, 16, v200
	v_cndmask_b32_e32 v208, v193, v208, vcc
	v_lshlrev_b32_e32 v194, 2, v208
	v_lshlrev_b32_e32 v208, 16, v196
	v_and_b32_e32 v213, 0xffff0000, v200
	v_lshlrev_b32_e32 v210, 16, v198
	v_and_b32_e32 v211, 0xffff0000, v198
	v_lshlrev_b32_e32 v198, 16, v199
	v_and_b32_e32 v199, 0xffff0000, v199
	v_lshlrev_b32_e32 v200, 16, v201
	v_and_b32_e32 v201, 0xffff0000, v201
	v_lshlrev_b32_e32 v214, 16, v202
	v_and_b32_e32 v215, 0xffff0000, v202
	v_pk_add_f32 v[124:125], v[124:125], v[208:209]
	v_pk_add_f32 v[116:117], v[116:117], v[212:213]
	v_lshlrev_b32_e32 v196, 16, v197
	v_and_b32_e32 v197, 0xffff0000, v197
	v_pk_add_f32 v[122:123], v[122:123], v[198:199]
	v_pk_add_f32 v[118:119], v[118:119], v[200:201]
	v_pk_add_f32 v[198:199], v[112:113], v[214:215]
	v_mul_f32_e32 v200, v125, v125
	v_cvt_pk_bf16_f32 v112, v124, v125
	v_mul_f32_e32 v125, v117, v117
	v_pk_add_f32 v[126:127], v[126:127], v[196:197]
	v_fmac_f32_e32 v200, v124, v124
	v_fmac_f32_e32 v125, v116, v116
	v_fmac_f32_e32 v200, v126, v126
	v_fmac_f32_e32 v125, v118, v118
	v_pk_add_f32 v[120:121], v[120:121], v[210:211]
	v_fmac_f32_e32 v200, v127, v127
	v_fmac_f32_e32 v125, v119, v119
	v_lshlrev_b32_e32 v202, 16, v203
	v_and_b32_e32 v203, 0xffff0000, v203
	v_fmac_f32_e32 v200, v120, v120
	v_fmac_f32_e32 v125, v198, v198
	v_pk_add_f32 v[196:197], v[114:115], v[202:203]
	v_fmac_f32_e32 v200, v121, v121
	v_fmac_f32_e32 v125, v199, v199
	v_fmac_f32_e32 v200, v122, v122
	v_fmac_f32_e32 v125, v196, v196
	v_fmac_f32_e32 v200, v123, v123
	v_fmac_f32_e32 v125, v197, v197
	v_cvt_pk_bf16_f32 v115, v122, v123
	v_add_f32_e32 v122, v200, v125
	ds_bpermute_b32 v123, v195, v122
	v_cvt_pk_bf16_f32 v114, v120, v121
	v_lshl_add_u64 v[120:121], s[76:77], 0, v[206:207]
	v_cvt_pk_bf16_f32 v113, v126, v127
	v_lshl_add_u64 v[120:121], v[120:121], 0, v[204:205]
	global_store_dwordx4 v[120:121], v[112:115], off
	s_waitcnt lgkmcnt(0)
	s_nop 0
	v_add_f32_e32 v112, v122, v123
	ds_bpermute_b32 v113, v194, v112
	v_cvt_pk_bf16_f32 v114, v116, v117
	v_cvt_pk_bf16_f32 v115, v118, v119
	v_cvt_pk_bf16_f32 v116, v198, v199
	v_cvt_pk_bf16_f32 v117, v196, v197
	global_store_dwordx4 v[120:121], v[114:117], off offset:256
	s_and_saveexec_b64 s[22:23], s[0:1]
	s_cbranch_execz .LBB0_1281
	s_waitcnt lgkmcnt(0)
	v_add_f32_e32 v114, v112, v113
	s_lshl_b32 s24, s6, 2
	v_lshlrev_b64 v[112:113], 6, v[172:173]
	s_ashr_i32 s25, s24, 31
	v_lshl_add_u64 v[112:113], s[10:11], 0, v[112:113]
	v_lshl_add_u64 v[112:113], s[24:25], 2, v[112:113]
	s_lshl_b32 s8, s37, 2
	v_lshl_add_u64 v[112:113], v[112:113], 0, s[8:9]
	global_store_dword v[112:113], v114, off
